# combo25: combo24 + GEMM K-loops: first iteration peeled with SrcC = 0 for every first accumulator read, removing the 128-register accumulator zero-fill between tiles
# baseline (speedup 1.0000x reference)
; #define PG8_STAGE(bufoff, gbase, voff) do { _Pragma("unroll") for (int _i = 0; _i < 2; ++_i) \
;         __builtin_amdgcn_global_load_lds((const unsigned*)((const char*)(gbase) + (voff)[_i]), (PG8_LAS unsigned*)(lds + (bufoff) + ldsw + _i * 8192), 16, 0, 0); } while (0)
; #define PG8_LDA(dst, b, h) do { _Pragma("unroll") for (int m = 0; m < 4; ++m) _Pragma("unroll") for (int k = 0; k < 2; ++k) dst[m][k] = *(const PG8_LAS bf16x8*)(lds + PG8_SA(b, h) + aoff + m * 2048 + k * 1024); } while (0)
; #define PG8_LDB(dst, b, h) do { _Pragma("unroll") for (int n = 0; n < 2; ++n) _Pragma("unroll") for (int k = 0; k < 2; ++k) dst[n][k] = *(const PG8_LAS bf16x8*)(lds + PG8_SB(b, h) + boff + n * 2048 + k * 1024); } while (0)
; #define PG8_WAIT_V(n) asm volatile("s_waitcnt vmcnt(" #n ")" ::: "memory")
; #define PG8_BAR __builtin_amdgcn_s_barrier()
; template <class Epi, class Sched, bool ALIGN_EPI = false, bool SP2 = false>
; __device__ __forceinline__ void gemm_phase(PG8_LAS unsigned char* lds, const Gemm g, const Sched& S, const Epi& E, const int tid_arg) {
;     ...
;             PG8_LDB(B0, 0, 0); PG8_LDB(B1, 0, 1); PG8_SCHED; PG8_LDA(At, 0, 0); PG8_STAGE(PG8_SA(1, 1), a1 + hstep, voffA);
;             PG8_WAIT_V(8); PG8_WAIT_L(0); PG8_BAR; PG8_MMA(0, 0, At, B0); PG8_MMA(0, 1, At, B1); PG8_BAR; PG8_SCHED;
;             PG8_LDA(At, 0, 1); PG8_STAGE(PG8_SB(0, 0), b2, voffB); PG8_STAGE(PG8_SB(0, 1), b2 + hstep, voffB); PG8_STAGE(PG8_SA(0, 0), a2, voffA);
;             PG8_WAIT_V(8); PG8_WAIT_L(0); PG8_BAR; PG8_MMA(1, 0, At, B0); PG8_MMA(1, 1, At, B1); PG8_BAR; PG8_SCHED;
;             PG8_LDB(B0, 1, 0); PG8_LDB(B1, 1, 1); PG8_SCHED; PG8_LDA(At, 1, 0); PG8_STAGE(PG8_SA(0, 1), a2 + hstep, voffA);
;             PG8_WAIT_V(8); PG8_WAIT_L(0); PG8_BAR; PG8_MMA(0, 0, At, B0); PG8_MMA(0, 1, At, B1); PG8_BAR; PG8_SCHED;
;             PG8_LDA(At, 1, 1); PG8_STAGE(PG8_SB(1, 0), b3, voffB); PG8_STAGE(PG8_SB(1, 1), b3 + hstep, voffB); PG8_STAGE(PG8_SA(1, 0), a3, voffA);
;             PG8_WAIT_V(8); PG8_WAIT_L(0); PG8_BAR; PG8_MMA(1, 0, At, B0); PG8_MMA(1, 1, At, B1); PG8_BAR; PG8_SCHED;
;     ...
; #pragma unroll
;         for (int a = 0; a < 2; ++a)
; #pragma unroll
;             for (int b = 0; b < 2; ++b)
; #pragma unroll
;                 for (int m = 0; m < 4; ++m)
; #pragma unroll
;                     for (int n = 0; n < 2; ++n) acc[a][b][m][n] = (f32x4){0.f, 0.f, 0.f, 0.f};
.LBB0_252:
	s_ashr_i32 s23, s22, 31
	s_lshl_b64 s[0:1], s[22:23], 19
	s_add_u32 s24, s2, s0
	s_addc_u32 s25, s3, s1
	s_and_b64 s[0:1], s[4:5], exec
	s_cselect_b32 s23, s25, s35
	s_cselect_b32 s36, s24, s34
	s_ashr_i32 s21, s20, 31
	s_lshl_b64 s[0:1], s[20:21], 19
	s_add_u32 s26, s33, s0
	s_addc_u32 s27, s38, s1
	s_and_b64 s[0:1], s[4:5], exec
	s_cselect_b32 s21, s27, s9
	s_cselect_b32 s37, s26, s8
	s_add_u32 s68, s8, 0x100
	s_addc_u32 s69, s9, 0
	s_add_u32 s8, s34, 0x40080
	v_mov_b32_e32 v0, 0
	s_addc_u32 s9, s35, 0
	s_mov_b32 s70, -2
	ds_read_b128 v[144:147], v166
	ds_read_b128 v[148:151], v167
	ds_read_b128 v[152:155], v168
	ds_read_b128 v[156:159], v169
	ds_read_b128 v[184:187], v170
	ds_read_b128 v[188:191], v171
	ds_read_b128 v[192:195], v172
	ds_read_b128 v[196:199], v173
	s_add_u32 s0, s8, 0xfffc0080
	s_addc_u32 s1, s9, -1
	s_cmp_eq_u32 s70, 12
	s_cselect_b32 s35, s23, s1
	s_cselect_b32 s34, s36, s0
	s_cselect_b32 s1, s21, s69
	s_cselect_b32 s0, s37, s68
	s_mov_b32 m0, s57
	v_lshl_add_u64 v[160:161], s[8:9], 0, v[138:139]
	ds_read_b128 v[200:203], v165
	ds_read_b128 v[204:207], v165 offset:1024
	ds_read_b128 v[208:211], v165 offset:2048
	ds_read_b128 v[212:215], v165 offset:3072
	ds_read_b128 v[216:219], v165 offset:4096
	ds_read_b128 v[220:223], v165 offset:5120
	ds_read_b128 v[224:227], v165 offset:6144
	ds_read_b128 v[228:231], v165 offset:7168
	global_load_lds_dwordx4 v[160:161], off
	v_lshl_add_u64 v[160:161], s[8:9], 0, v[136:137]
	s_mov_b32 m0, s58
	s_nop 0
	global_load_lds_dwordx4 v[160:161], off
	s_waitcnt vmcnt(8)
	s_waitcnt lgkmcnt(0)
	s_setprio 1
	s_barrier
	v_mfma_f32_16x16x32_bf16 v[124:127], v[144:147], v[200:203], 0
	v_mfma_f32_16x16x32_bf16 v[120:123], v[152:155], v[200:203], 0
	v_mfma_f32_16x16x32_bf16 v[108:111], v[144:147], v[208:211], 0
	v_mfma_f32_16x16x32_bf16 v[104:107], v[152:155], v[208:211], 0
	v_mfma_f32_16x16x32_bf16 v[92:95], v[144:147], v[216:219], 0
	v_mfma_f32_16x16x32_bf16 v[88:91], v[152:155], v[216:219], 0
	v_mfma_f32_16x16x32_bf16 v[76:79], v[144:147], v[224:227], 0
	v_mfma_f32_16x16x32_bf16 v[72:75], v[152:155], v[224:227], 0
	v_mfma_f32_16x16x32_bf16 v[124:127], v[148:151], v[204:207], v[124:127]
	v_mfma_f32_16x16x32_bf16 v[120:123], v[156:159], v[204:207], v[120:123]
	v_mfma_f32_16x16x32_bf16 v[108:111], v[148:151], v[212:215], v[108:111]
	v_mfma_f32_16x16x32_bf16 v[104:107], v[156:159], v[212:215], v[104:107]
	v_mfma_f32_16x16x32_bf16 v[92:95], v[148:151], v[220:223], v[92:95]
	v_mfma_f32_16x16x32_bf16 v[88:91], v[156:159], v[220:223], v[88:91]
	v_mfma_f32_16x16x32_bf16 v[76:79], v[148:151], v[228:231], v[76:79]
	v_mfma_f32_16x16x32_bf16 v[72:75], v[156:159], v[228:231], v[72:75]
	s_setprio 0
	s_setprio 1
	v_mfma_f32_16x16x32_bf16 v[116:119], v[184:187], v[200:203], 0
	v_mfma_f32_16x16x32_bf16 v[112:115], v[192:195], v[200:203], 0
	v_mfma_f32_16x16x32_bf16 v[100:103], v[184:187], v[208:211], 0
	v_mfma_f32_16x16x32_bf16 v[96:99], v[192:195], v[208:211], 0
	v_mfma_f32_16x16x32_bf16 v[84:87], v[184:187], v[216:219], 0
	v_mfma_f32_16x16x32_bf16 v[80:83], v[192:195], v[216:219], 0
	v_mfma_f32_16x16x32_bf16 v[68:71], v[184:187], v[224:227], 0
	v_mfma_f32_16x16x32_bf16 v[64:67], v[192:195], v[224:227], 0
	v_mfma_f32_16x16x32_bf16 v[116:119], v[188:191], v[204:207], v[116:119]
	v_mfma_f32_16x16x32_bf16 v[112:115], v[196:199], v[204:207], v[112:115]
	v_mfma_f32_16x16x32_bf16 v[100:103], v[188:191], v[212:215], v[100:103]
	v_mfma_f32_16x16x32_bf16 v[96:99], v[196:199], v[212:215], v[96:99]
	v_mfma_f32_16x16x32_bf16 v[84:87], v[188:191], v[220:223], v[84:87]
	v_mfma_f32_16x16x32_bf16 v[80:83], v[196:199], v[220:223], v[80:83]
	v_mfma_f32_16x16x32_bf16 v[68:71], v[188:191], v[228:231], v[68:71]
	v_mfma_f32_16x16x32_bf16 v[64:67], v[196:199], v[228:231], v[64:67]
	s_barrier
	s_setprio 0
	s_mov_b32 m0, s29
	v_lshl_add_u64 v[160:161], s[0:1], 0, v[130:131]
	s_add_u32 s72, s0, 0x40000
	ds_read_b128 v[200:203], v165 offset:16384
	ds_read_b128 v[204:207], v165 offset:17408
	ds_read_b128 v[208:211], v165 offset:18432
	ds_read_b128 v[212:215], v165 offset:19456
	ds_read_b128 v[216:219], v165 offset:20480
	ds_read_b128 v[220:223], v165 offset:21504
	ds_read_b128 v[224:227], v165 offset:22528
	ds_read_b128 v[228:231], v165 offset:23552
	global_load_lds_dwordx4 v[160:161], off
	v_lshl_add_u64 v[232:233], s[0:1], 0, v[134:135]
	s_mov_b32 m0, s31
	s_addc_u32 s73, s1, 0
	global_load_lds_dwordx4 v[232:233], off
	v_lshl_add_u64 v[234:235], s[72:73], 0, v[130:131]
	s_mov_b32 m0, s40
	v_lshl_add_u64 v[236:237], s[34:35], 0, v[132:133]
	global_load_lds_dwordx4 v[234:235], off
	v_lshl_add_u64 v[234:235], s[72:73], 0, v[134:135]
	s_mov_b32 m0, s41
	s_nop 0
	global_load_lds_dwordx4 v[234:235], off
	v_lshl_add_u64 v[234:235], s[34:35], 0, v[128:129]
	s_mov_b32 m0, s39
	s_nop 0
	global_load_lds_dwordx4 v[234:235], off
	s_mov_b32 m0, s42
	s_nop 0
	global_load_lds_dwordx4 v[236:237], off
	s_waitcnt vmcnt(8)
	s_waitcnt lgkmcnt(0)
	s_setprio 1
	s_barrier
; #define PG8_STAGE(bufoff, gbase, voff) do { _Pragma("unroll") for (int _i = 0; _i < 2; ++_i) \
;         __builtin_amdgcn_global_load_lds((const unsigned*)((const char*)(gbase) + (voff)[_i]), (PG8_LAS unsigned*)(lds + (bufoff) + ldsw + _i * 8192), 16, 0, 0); } while (0)
; #define PG8_LDA(dst, b, h) do { _Pragma("unroll") for (int m = 0; m < 4; ++m) _Pragma("unroll") for (int k = 0; k < 2; ++k) dst[m][k] = *(const PG8_LAS bf16x8*)(lds + PG8_SA(b, h) + aoff + m * 2048 + k * 1024); } while (0)
; #define PG8_LDB(dst, b, h) do { _Pragma("unroll") for (int n = 0; n < 2; ++n) _Pragma("unroll") for (int k = 0; k < 2; ++k) dst[n][k] = *(const PG8_LAS bf16x8*)(lds + PG8_SB(b, h) + boff + n * 2048 + k * 1024); } while (0)
; #define PG8_MMA(ai, bj, At, Bt) do { __builtin_amdgcn_s_setprio(1); _Pragma("unroll") for (int m = 0; m < 4; ++m) _Pragma("unroll") for (int n = 0; n < 2; ++n) _Pragma("unroll") for (int k = 0; k < 2; ++k) \
;         acc[ai][bj][m][n] = __builtin_amdgcn_mfma_f32_16x16x32_bf16(Bt[n][k], At[m][k], acc[ai][bj][m][n], 0, 0, 0); __builtin_amdgcn_s_setprio(0); } while (0)
; #define PG8_BAR __builtin_amdgcn_s_barrier()
; template <class Epi, class Sched, bool ALIGN_EPI = false, bool SP2 = false>
; __device__ __forceinline__ void gemm_phase(PG8_LAS unsigned char* lds, const Gemm g, const Sched& S, const Epi& E, const int tid_arg) {
;     ...
;             PG8_LDB(B0, 0, 0); PG8_LDB(B1, 0, 1); PG8_SCHED; PG8_LDA(At, 0, 0); PG8_STAGE(PG8_SA(1, 1), a1 + hstep, voffA);
;             PG8_WAIT_V(8); PG8_WAIT_L(0); PG8_BAR; PG8_MMA(0, 0, At, B0); PG8_MMA(0, 1, At, B1); PG8_BAR; PG8_SCHED;
;             PG8_LDA(At, 0, 1); PG8_STAGE(PG8_SB(0, 0), b2, voffB); PG8_STAGE(PG8_SB(0, 1), b2 + hstep, voffB); PG8_STAGE(PG8_SA(0, 0), a2, voffA);
;             PG8_WAIT_V(8); PG8_WAIT_L(0); PG8_BAR; PG8_MMA(1, 0, At, B0); PG8_MMA(1, 1, At, B1); PG8_BAR; PG8_SCHED;
;             PG8_LDB(B0, 1, 0); PG8_LDB(B1, 1, 1); PG8_SCHED; PG8_LDA(At, 1, 0); PG8_STAGE(PG8_SA(0, 1), a2 + hstep, voffA);
;             PG8_WAIT_V(8); PG8_WAIT_L(0); PG8_BAR; PG8_MMA(0, 0, At, B0); PG8_MMA(0, 1, At, B1); PG8_BAR; PG8_SCHED;
;             PG8_LDA(At, 1, 1); PG8_STAGE(PG8_SB(1, 0), b3, voffB); PG8_STAGE(PG8_SB(1, 1), b3 + hstep, voffB); PG8_STAGE(PG8_SA(1, 0), a3, voffA);
;             PG8_WAIT_V(8); PG8_WAIT_L(0); PG8_BAR; PG8_MMA(1, 0, At, B0); PG8_MMA(1, 1, At, B1); PG8_BAR; PG8_SCHED;
	v_mfma_f32_16x16x32_bf16 v[60:63], v[144:147], v[200:203], 0
	v_mfma_f32_16x16x32_bf16 v[56:59], v[152:155], v[200:203], 0
	v_mfma_f32_16x16x32_bf16 v[44:47], v[144:147], v[208:211], 0
	v_mfma_f32_16x16x32_bf16 v[40:43], v[152:155], v[208:211], 0
	v_mfma_f32_16x16x32_bf16 v[28:31], v[144:147], v[216:219], 0
	v_mfma_f32_16x16x32_bf16 v[24:27], v[152:155], v[216:219], 0
	v_mfma_f32_16x16x32_bf16 v[12:15], v[144:147], v[224:227], 0
	v_mfma_f32_16x16x32_bf16 v[8:11], v[152:155], v[224:227], 0
	v_mfma_f32_16x16x32_bf16 v[60:63], v[148:151], v[204:207], v[60:63]
	v_mfma_f32_16x16x32_bf16 v[56:59], v[156:159], v[204:207], v[56:59]
	v_mfma_f32_16x16x32_bf16 v[44:47], v[148:151], v[212:215], v[44:47]
	v_mfma_f32_16x16x32_bf16 v[40:43], v[156:159], v[212:215], v[40:43]
	v_mfma_f32_16x16x32_bf16 v[28:31], v[148:151], v[220:223], v[28:31]
	v_mfma_f32_16x16x32_bf16 v[24:27], v[156:159], v[220:223], v[24:27]
	v_mfma_f32_16x16x32_bf16 v[12:15], v[148:151], v[228:231], v[12:15]
	v_mfma_f32_16x16x32_bf16 v[8:11], v[156:159], v[228:231], v[8:11]
	s_setprio 0
	s_setprio 1
	v_mfma_f32_16x16x32_bf16 v[52:55], v[184:187], v[200:203], 0
	v_mfma_f32_16x16x32_bf16 v[48:51], v[192:195], v[200:203], 0
	v_mfma_f32_16x16x32_bf16 v[36:39], v[184:187], v[208:211], 0
	v_mfma_f32_16x16x32_bf16 v[32:35], v[192:195], v[208:211], 0
	v_mfma_f32_16x16x32_bf16 v[20:23], v[184:187], v[216:219], 0
	v_mfma_f32_16x16x32_bf16 v[16:19], v[192:195], v[216:219], 0
	v_mfma_f32_16x16x32_bf16 v[4:7], v[184:187], v[224:227], 0
	v_mfma_f32_16x16x32_bf16 v[0:3], v[192:195], v[224:227], 0
	v_mfma_f32_16x16x32_bf16 v[52:55], v[188:191], v[204:207], v[52:55]
	v_mfma_f32_16x16x32_bf16 v[48:51], v[196:199], v[204:207], v[48:51]
	v_mfma_f32_16x16x32_bf16 v[36:39], v[188:191], v[212:215], v[36:39]
	v_mfma_f32_16x16x32_bf16 v[32:35], v[196:199], v[212:215], v[32:35]
	v_mfma_f32_16x16x32_bf16 v[20:23], v[188:191], v[220:223], v[20:23]
	v_mfma_f32_16x16x32_bf16 v[16:19], v[196:199], v[220:223], v[16:19]
	v_mfma_f32_16x16x32_bf16 v[4:7], v[188:191], v[228:231], v[4:7]
	v_mfma_f32_16x16x32_bf16 v[0:3], v[196:199], v[228:231], v[0:3]
	s_barrier
	s_setprio 0
	ds_read_b128 v[144:147], v174
	ds_read_b128 v[148:151], v175
	ds_read_b128 v[152:155], v176
	ds_read_b128 v[156:159], v177
	ds_read_b128 v[184:187], v178
	ds_read_b128 v[188:191], v179
	ds_read_b128 v[192:195], v180
	ds_read_b128 v[196:199], v181
	s_add_u32 s34, s34, 0x40000
	s_addc_u32 s35, s35, 0
	s_mov_b32 m0, s43
	v_lshl_add_u64 v[238:239], s[34:35], 0, v[128:129]
	ds_read_b128 v[200:203], v165 offset:32768
	ds_read_b128 v[204:207], v165 offset:33792
	ds_read_b128 v[208:211], v165 offset:34816
	ds_read_b128 v[212:215], v165 offset:35840
	ds_read_b128 v[216:219], v165 offset:36864
	ds_read_b128 v[220:223], v165 offset:37888
	ds_read_b128 v[224:227], v165 offset:38912
	ds_read_b128 v[228:231], v165 offset:39936
	global_load_lds_dwordx4 v[238:239], off
	v_lshl_add_u64 v[238:239], s[34:35], 0, v[132:133]
	s_mov_b32 m0, s44
	s_nop 0
	global_load_lds_dwordx4 v[238:239], off
	s_waitcnt vmcnt(8)
	s_waitcnt lgkmcnt(0)
	s_setprio 1
	s_barrier
	v_mfma_f32_16x16x32_bf16 v[124:127], v[144:147], v[200:203], v[124:127]
	v_mfma_f32_16x16x32_bf16 v[120:123], v[152:155], v[200:203], v[120:123]
	v_mfma_f32_16x16x32_bf16 v[108:111], v[144:147], v[208:211], v[108:111]
	v_mfma_f32_16x16x32_bf16 v[104:107], v[152:155], v[208:211], v[104:107]
	v_mfma_f32_16x16x32_bf16 v[92:95], v[144:147], v[216:219], v[92:95]
	v_mfma_f32_16x16x32_bf16 v[88:91], v[152:155], v[216:219], v[88:91]
	v_mfma_f32_16x16x32_bf16 v[76:79], v[144:147], v[224:227], v[76:79]
	v_mfma_f32_16x16x32_bf16 v[72:75], v[152:155], v[224:227], v[72:75]
	v_mfma_f32_16x16x32_bf16 v[124:127], v[148:151], v[204:207], v[124:127]
	v_mfma_f32_16x16x32_bf16 v[120:123], v[156:159], v[204:207], v[120:123]
	v_mfma_f32_16x16x32_bf16 v[108:111], v[148:151], v[212:215], v[108:111]
	v_mfma_f32_16x16x32_bf16 v[104:107], v[156:159], v[212:215], v[104:107]
	v_mfma_f32_16x16x32_bf16 v[92:95], v[148:151], v[220:223], v[92:95]
	v_mfma_f32_16x16x32_bf16 v[88:91], v[156:159], v[220:223], v[88:91]
	v_mfma_f32_16x16x32_bf16 v[76:79], v[148:151], v[228:231], v[76:79]
	v_mfma_f32_16x16x32_bf16 v[72:75], v[156:159], v[228:231], v[72:75]
	s_setprio 0
	s_setprio 1
	v_mfma_f32_16x16x32_bf16 v[116:119], v[184:187], v[200:203], v[116:119]
	v_mfma_f32_16x16x32_bf16 v[112:115], v[192:195], v[200:203], v[112:115]
	v_mfma_f32_16x16x32_bf16 v[100:103], v[184:187], v[208:211], v[100:103]
	v_mfma_f32_16x16x32_bf16 v[96:99], v[192:195], v[208:211], v[96:99]
	v_mfma_f32_16x16x32_bf16 v[84:87], v[184:187], v[216:219], v[84:87]
	v_mfma_f32_16x16x32_bf16 v[80:83], v[192:195], v[216:219], v[80:83]
	v_mfma_f32_16x16x32_bf16 v[68:71], v[184:187], v[224:227], v[68:71]
	v_mfma_f32_16x16x32_bf16 v[64:67], v[192:195], v[224:227], v[64:67]
	v_mfma_f32_16x16x32_bf16 v[116:119], v[188:191], v[204:207], v[116:119]
	v_mfma_f32_16x16x32_bf16 v[112:115], v[196:199], v[204:207], v[112:115]
	v_mfma_f32_16x16x32_bf16 v[100:103], v[188:191], v[212:215], v[100:103]
	v_mfma_f32_16x16x32_bf16 v[96:99], v[196:199], v[212:215], v[96:99]
	v_mfma_f32_16x16x32_bf16 v[84:87], v[188:191], v[220:223], v[84:87]
	v_mfma_f32_16x16x32_bf16 v[80:83], v[196:199], v[220:223], v[80:83]
	v_mfma_f32_16x16x32_bf16 v[68:71], v[188:191], v[228:231], v[68:71]
	v_mfma_f32_16x16x32_bf16 v[64:67], v[196:199], v[228:231], v[64:67]
	s_barrier
; #define PG8_STAGE(bufoff, gbase, voff) do { _Pragma("unroll") for (int _i = 0; _i < 2; ++_i) \
;         __builtin_amdgcn_global_load_lds((const unsigned*)((const char*)(gbase) + (voff)[_i]), (PG8_LAS unsigned*)(lds + (bufoff) + ldsw + _i * 8192), 16, 0, 0); } while (0)
; #define PG8_LDA(dst, b, h) do { _Pragma("unroll") for (int m = 0; m < 4; ++m) _Pragma("unroll") for (int k = 0; k < 2; ++k) dst[m][k] = *(const PG8_LAS bf16x8*)(lds + PG8_SA(b, h) + aoff + m * 2048 + k * 1024); } while (0)
; #define PG8_LDB(dst, b, h) do { _Pragma("unroll") for (int n = 0; n < 2; ++n) _Pragma("unroll") for (int k = 0; k < 2; ++k) dst[n][k] = *(const PG8_LAS bf16x8*)(lds + PG8_SB(b, h) + boff + n * 2048 + k * 1024); } while (0)
; #define PG8_MMA(ai, bj, At, Bt) do { __builtin_amdgcn_s_setprio(1); _Pragma("unroll") for (int m = 0; m < 4; ++m) _Pragma("unroll") for (int n = 0; n < 2; ++n) _Pragma("unroll") for (int k = 0; k < 2; ++k) \
;         acc[ai][bj][m][n] = __builtin_amdgcn_mfma_f32_16x16x32_bf16(Bt[n][k], At[m][k], acc[ai][bj][m][n], 0, 0, 0); __builtin_amdgcn_s_setprio(0); } while (0)
; #define PG8_BAR __builtin_amdgcn_s_barrier()
; template <class Epi, class Sched, bool ALIGN_EPI = false, bool SP2 = false>
; __device__ __forceinline__ void gemm_phase(PG8_LAS unsigned char* lds, const Gemm g, const Sched& S, const Epi& E, const int tid_arg) {
;     ...
;             PG8_LDB(B0, 0, 0); PG8_LDB(B1, 0, 1); PG8_SCHED; PG8_LDA(At, 0, 0); PG8_STAGE(PG8_SA(1, 1), a1 + hstep, voffA);
;             PG8_WAIT_V(8); PG8_WAIT_L(0); PG8_BAR; PG8_MMA(0, 0, At, B0); PG8_MMA(0, 1, At, B1); PG8_BAR; PG8_SCHED;
;             PG8_LDA(At, 0, 1); PG8_STAGE(PG8_SB(0, 0), b2, voffB); PG8_STAGE(PG8_SB(0, 1), b2 + hstep, voffB); PG8_STAGE(PG8_SA(0, 0), a2, voffA);
;             PG8_WAIT_V(8); PG8_WAIT_L(0); PG8_BAR; PG8_MMA(1, 0, At, B0); PG8_MMA(1, 1, At, B1); PG8_BAR; PG8_SCHED;
;             PG8_LDB(B0, 1, 0); PG8_LDB(B1, 1, 1); PG8_SCHED; PG8_LDA(At, 1, 0); PG8_STAGE(PG8_SA(0, 1), a2 + hstep, voffA);
;             PG8_WAIT_V(8); PG8_WAIT_L(0); PG8_BAR; PG8_MMA(0, 0, At, B0); PG8_MMA(0, 1, At, B1); PG8_BAR; PG8_SCHED;
;             PG8_LDA(At, 1, 1); PG8_STAGE(PG8_SB(1, 0), b3, voffB); PG8_STAGE(PG8_SB(1, 1), b3 + hstep, voffB); PG8_STAGE(PG8_SA(1, 0), a3, voffA);
;             PG8_WAIT_V(8); PG8_WAIT_L(0); PG8_BAR; PG8_MMA(1, 0, At, B0); PG8_MMA(1, 1, At, B1); PG8_BAR; PG8_SCHED;
	s_setprio 0
	s_mov_b32 m0, s47
	v_lshl_add_u64 v[160:161], v[160:161], 0, s[14:15]
	s_add_u32 s0, s0, 0x40080
	ds_read_b128 v[200:203], v165 offset:49152
	ds_read_b128 v[204:207], v165 offset:50176
	ds_read_b128 v[208:211], v165 offset:51200
	ds_read_b128 v[212:215], v165 offset:52224
	ds_read_b128 v[216:219], v165 offset:53248
	ds_read_b128 v[220:223], v165 offset:54272
	ds_read_b128 v[224:227], v165 offset:55296
	ds_read_b128 v[228:231], v165 offset:56320
	global_load_lds_dwordx4 v[160:161], off
	v_lshl_add_u64 v[160:161], v[232:233], 0, s[14:15]
	s_mov_b32 m0, s48
	s_addc_u32 s1, s1, 0
	global_load_lds_dwordx4 v[160:161], off
	v_lshl_add_u64 v[160:161], s[0:1], 0, v[130:131]
	s_mov_b32 m0, s51
	s_nop 0
	global_load_lds_dwordx4 v[160:161], off
	v_lshl_add_u64 v[160:161], s[0:1], 0, v[134:135]
	s_mov_b32 m0, s52
	s_nop 0
	global_load_lds_dwordx4 v[160:161], off
	v_lshl_add_u64 v[160:161], v[234:235], 0, s[14:15]
	s_mov_b32 m0, s49
	s_nop 0
	global_load_lds_dwordx4 v[160:161], off
	v_lshl_add_u64 v[160:161], v[236:237], 0, s[14:15]
	s_mov_b32 m0, s50
	s_nop 0
	global_load_lds_dwordx4 v[160:161], off
	s_waitcnt vmcnt(8)
	s_waitcnt lgkmcnt(0)
	s_setprio 1
	s_barrier
	v_mfma_f32_16x16x32_bf16 v[60:63], v[144:147], v[200:203], v[60:63]
	v_mfma_f32_16x16x32_bf16 v[56:59], v[152:155], v[200:203], v[56:59]
	v_mfma_f32_16x16x32_bf16 v[44:47], v[144:147], v[208:211], v[44:47]
	v_mfma_f32_16x16x32_bf16 v[40:43], v[152:155], v[208:211], v[40:43]
	v_mfma_f32_16x16x32_bf16 v[28:31], v[144:147], v[216:219], v[28:31]
	v_mfma_f32_16x16x32_bf16 v[24:27], v[152:155], v[216:219], v[24:27]
	v_mfma_f32_16x16x32_bf16 v[12:15], v[144:147], v[224:227], v[12:15]
	v_mfma_f32_16x16x32_bf16 v[8:11], v[152:155], v[224:227], v[8:11]
	v_mfma_f32_16x16x32_bf16 v[60:63], v[148:151], v[204:207], v[60:63]
	v_mfma_f32_16x16x32_bf16 v[56:59], v[156:159], v[204:207], v[56:59]
	v_mfma_f32_16x16x32_bf16 v[44:47], v[148:151], v[212:215], v[44:47]
	v_mfma_f32_16x16x32_bf16 v[40:43], v[156:159], v[212:215], v[40:43]
	v_mfma_f32_16x16x32_bf16 v[28:31], v[148:151], v[220:223], v[28:31]
	v_mfma_f32_16x16x32_bf16 v[24:27], v[156:159], v[220:223], v[24:27]
	v_mfma_f32_16x16x32_bf16 v[12:15], v[148:151], v[228:231], v[12:15]
	v_mfma_f32_16x16x32_bf16 v[8:11], v[156:159], v[228:231], v[8:11]
	s_setprio 0
	s_setprio 1
	v_mfma_f32_16x16x32_bf16 v[52:55], v[184:187], v[200:203], v[52:55]
	v_mfma_f32_16x16x32_bf16 v[48:51], v[192:195], v[200:203], v[48:51]
	v_mfma_f32_16x16x32_bf16 v[36:39], v[184:187], v[208:211], v[36:39]
	v_mfma_f32_16x16x32_bf16 v[32:35], v[192:195], v[208:211], v[32:35]
	v_mfma_f32_16x16x32_bf16 v[20:23], v[184:187], v[216:219], v[20:23]
	v_mfma_f32_16x16x32_bf16 v[16:19], v[192:195], v[216:219], v[16:19]
	v_mfma_f32_16x16x32_bf16 v[4:7], v[184:187], v[224:227], v[4:7]
	v_mfma_f32_16x16x32_bf16 v[0:3], v[192:195], v[224:227], v[0:3]
	v_mfma_f32_16x16x32_bf16 v[52:55], v[188:191], v[204:207], v[52:55]
	v_mfma_f32_16x16x32_bf16 v[48:51], v[196:199], v[204:207], v[48:51]
	v_mfma_f32_16x16x32_bf16 v[36:39], v[188:191], v[212:215], v[36:39]
	v_mfma_f32_16x16x32_bf16 v[32:35], v[196:199], v[212:215], v[32:35]
	v_mfma_f32_16x16x32_bf16 v[20:23], v[188:191], v[220:223], v[20:23]
	v_mfma_f32_16x16x32_bf16 v[16:19], v[196:199], v[220:223], v[16:19]
	v_mfma_f32_16x16x32_bf16 v[4:7], v[188:191], v[228:231], v[4:7]
	v_mfma_f32_16x16x32_bf16 v[0:3], v[196:199], v[228:231], v[0:3]
	s_barrier
	s_setprio 0
	s_add_i32 s70, s70, 2
	s_add_u32 s68, s68, 0x100
	s_addc_u32 s69, s69, 0
	s_add_u32 s8, s8, 0x100
	s_addc_u32 s9, s9, 0
	s_cmp_gt_u32 s70, 13
	s_cbranch_scc0 .LBB0_253
	s_branch .Lkpeel_exit_1

; #define PG8_BAR __builtin_amdgcn_s_barrier()
; template <class Epi, class Sched, bool ALIGN_EPI = false, bool SP2 = false>
; __device__ __forceinline__ void gemm_phase(PG8_LAS unsigned char* lds, const Gemm g, const Sched& S, const Epi& E, const int tid_arg) {
;     ...
;         if constexpr (ALIGN_EPI) { if (wr == 0) PG8_BAR; }
.Lkpeel_exit_1:
	s_and_b64 vcc, exec, s[16:17]
	s_cbranch_vccz .LBB0_256
	s_barrier

; #define PG8_STAGE(bufoff, gbase, voff) do { _Pragma("unroll") for (int _i = 0; _i < 2; ++_i) \
;         __builtin_amdgcn_global_load_lds((const unsigned*)((const char*)(gbase) + (voff)[_i]), (PG8_LAS unsigned*)(lds + (bufoff) + ldsw + _i * 8192), 16, 0, 0); } while (0)
; #define PG8_LDA(dst, b, h) do { _Pragma("unroll") for (int m = 0; m < 4; ++m) _Pragma("unroll") for (int k = 0; k < 2; ++k) dst[m][k] = *(const PG8_LAS bf16x8*)(lds + PG8_SA(b, h) + aoff + m * 2048 + k * 1024); } while (0)
; #define PG8_LDB(dst, b, h) do { _Pragma("unroll") for (int n = 0; n < 2; ++n) _Pragma("unroll") for (int k = 0; k < 2; ++k) dst[n][k] = *(const PG8_LAS bf16x8*)(lds + PG8_SB(b, h) + boff + n * 2048 + k * 1024); } while (0)
; #define PG8_WAIT_V(n) asm volatile("s_waitcnt vmcnt(" #n ")" ::: "memory")
; #define PG8_BAR __builtin_amdgcn_s_barrier()
; template <class Epi, class Sched, bool ALIGN_EPI = false, bool SP2 = false>
; __device__ __forceinline__ void gemm_phase(PG8_LAS unsigned char* lds, const Gemm g, const Sched& S, const Epi& E, const int tid_arg) {
;     ...
;             PG8_LDB(B0, 0, 0); PG8_LDB(B1, 0, 1); PG8_SCHED; PG8_LDA(At, 0, 0); PG8_STAGE(PG8_SA(1, 1), a1 + hstep, voffA);
;             PG8_WAIT_V(8); PG8_WAIT_L(0); PG8_BAR; PG8_MMA(0, 0, At, B0); PG8_MMA(0, 1, At, B1); PG8_BAR; PG8_SCHED;
;             PG8_LDA(At, 0, 1); PG8_STAGE(PG8_SB(0, 0), b2, voffB); PG8_STAGE(PG8_SB(0, 1), b2 + hstep, voffB); PG8_STAGE(PG8_SA(0, 0), a2, voffA);
;             PG8_WAIT_V(8); PG8_WAIT_L(0); PG8_BAR; PG8_MMA(1, 0, At, B0); PG8_MMA(1, 1, At, B1); PG8_BAR; PG8_SCHED;
;             PG8_LDB(B0, 1, 0); PG8_LDB(B1, 1, 1); PG8_SCHED; PG8_LDA(At, 1, 0); PG8_STAGE(PG8_SA(0, 1), a2 + hstep, voffA);
;             PG8_WAIT_V(8); PG8_WAIT_L(0); PG8_BAR; PG8_MMA(0, 0, At, B0); PG8_MMA(0, 1, At, B1); PG8_BAR; PG8_SCHED;
;             PG8_LDA(At, 1, 1); PG8_STAGE(PG8_SB(1, 0), b3, voffB); PG8_STAGE(PG8_SB(1, 1), b3 + hstep, voffB); PG8_STAGE(PG8_SA(1, 0), a3, voffA);
;             PG8_WAIT_V(8); PG8_WAIT_L(0); PG8_BAR; PG8_MMA(1, 0, At, B0); PG8_MMA(1, 1, At, B1); PG8_BAR; PG8_SCHED;
;     ...
; #pragma unroll
;         for (int a = 0; a < 2; ++a)
; #pragma unroll
;             for (int b = 0; b < 2; ++b)
; #pragma unroll
;                 for (int m = 0; m < 4; ++m)
; #pragma unroll
;                     for (int n = 0; n < 2; ++n) acc[a][b][m][n] = (f32x4){0.f, 0.f, 0.f, 0.f};
.LBB0_532:
	s_ashr_i32 s29, s28, 31
	s_lshl_b64 s[0:1], s[28:29], 19
	s_add_u32 s30, s2, s0
	s_addc_u32 s31, s3, s1
	s_and_b64 s[0:1], s[8:9], exec
	s_cselect_b32 s11, s31, s37
	s_cselect_b32 s29, s30, s36
	s_ashr_i32 s27, s26, 31
	s_lshl_b64 s[0:1], s[26:27], 19
	s_add_u32 s34, s33, s0
	s_addc_u32 s35, s38, s1
	s_and_b64 s[0:1], s[8:9], exec
	s_cselect_b32 s27, s35, s13
	s_cselect_b32 s62, s34, s12
	s_add_u32 s63, s12, 0x100
	s_addc_u32 s64, s13, 0
	s_add_u32 s12, s36, 0x40080
	v_mov_b32_e32 v0, 0
	s_addc_u32 s13, s37, 0
	s_mov_b32 s65, -2
	s_waitcnt vmcnt(0)
	ds_read_b128 v[128:131], v165
	ds_read_b128 v[132:135], v166
	ds_read_b128 v[152:155], v167
	ds_read_b128 v[156:159], v168
	ds_read_b128 v[182:185], v169
	ds_read_b128 v[186:189], v170
	ds_read_b128 v[190:193], v171
	ds_read_b128 v[194:197], v172
	s_add_u32 s0, s12, 0xfffc0080
	s_addc_u32 s1, s13, -1
	s_cmp_eq_u32 s65, 12
	s_cselect_b32 s37, s11, s1
	s_cselect_b32 s36, s29, s0
	s_cselect_b32 s1, s27, s64
	s_cselect_b32 s0, s62, s63
	s_mov_b32 m0, s59
	v_lshl_add_u64 v[160:161], s[12:13], 0, v[146:147]
	ds_read_b128 v[198:201], v164
	ds_read_b128 v[202:205], v164 offset:1024
	ds_read_b128 v[206:209], v164 offset:2048
	ds_read_b128 v[210:213], v164 offset:3072
	ds_read_b128 v[214:217], v164 offset:4096
	ds_read_b128 v[218:221], v164 offset:5120
	ds_read_b128 v[222:225], v164 offset:6144
	ds_read_b128 v[226:229], v164 offset:7168
	global_load_lds_dwordx4 v[160:161], off
	v_lshl_add_u64 v[160:161], s[12:13], 0, v[144:145]
	s_mov_b32 m0, s60
	s_nop 0
	global_load_lds_dwordx4 v[160:161], off
	s_waitcnt vmcnt(8)
	s_waitcnt lgkmcnt(0)
	s_setprio 1
	s_barrier
	v_mfma_f32_16x16x32_bf16 v[124:127], v[128:131], v[198:201], 0
	v_mfma_f32_16x16x32_bf16 v[120:123], v[152:155], v[198:201], 0
	v_mfma_f32_16x16x32_bf16 v[108:111], v[128:131], v[206:209], 0
	v_mfma_f32_16x16x32_bf16 v[104:107], v[152:155], v[206:209], 0
	v_mfma_f32_16x16x32_bf16 v[92:95], v[128:131], v[214:217], 0
	v_mfma_f32_16x16x32_bf16 v[88:91], v[152:155], v[214:217], 0
	v_mfma_f32_16x16x32_bf16 v[76:79], v[128:131], v[222:225], 0
	v_mfma_f32_16x16x32_bf16 v[72:75], v[152:155], v[222:225], 0
	v_mfma_f32_16x16x32_bf16 v[124:127], v[132:135], v[202:205], v[124:127]
	v_mfma_f32_16x16x32_bf16 v[120:123], v[156:159], v[202:205], v[120:123]
	v_mfma_f32_16x16x32_bf16 v[108:111], v[132:135], v[210:213], v[108:111]
	v_mfma_f32_16x16x32_bf16 v[104:107], v[156:159], v[210:213], v[104:107]
	v_mfma_f32_16x16x32_bf16 v[92:95], v[132:135], v[218:221], v[92:95]
	v_mfma_f32_16x16x32_bf16 v[88:91], v[156:159], v[218:221], v[88:91]
	v_mfma_f32_16x16x32_bf16 v[76:79], v[132:135], v[226:229], v[76:79]
	v_mfma_f32_16x16x32_bf16 v[72:75], v[156:159], v[226:229], v[72:75]
	s_setprio 0
	s_setprio 1
	v_mfma_f32_16x16x32_bf16 v[116:119], v[182:185], v[198:201], 0
	v_mfma_f32_16x16x32_bf16 v[112:115], v[190:193], v[198:201], 0
	v_mfma_f32_16x16x32_bf16 v[100:103], v[182:185], v[206:209], 0
	v_mfma_f32_16x16x32_bf16 v[96:99], v[190:193], v[206:209], 0
	v_mfma_f32_16x16x32_bf16 v[84:87], v[182:185], v[214:217], 0
	v_mfma_f32_16x16x32_bf16 v[80:83], v[190:193], v[214:217], 0
	v_mfma_f32_16x16x32_bf16 v[68:71], v[182:185], v[222:225], 0
	v_mfma_f32_16x16x32_bf16 v[64:67], v[190:193], v[222:225], 0
	v_mfma_f32_16x16x32_bf16 v[116:119], v[186:189], v[202:205], v[116:119]
	v_mfma_f32_16x16x32_bf16 v[112:115], v[194:197], v[202:205], v[112:115]
	v_mfma_f32_16x16x32_bf16 v[100:103], v[186:189], v[210:213], v[100:103]
	v_mfma_f32_16x16x32_bf16 v[96:99], v[194:197], v[210:213], v[96:99]
	v_mfma_f32_16x16x32_bf16 v[84:87], v[186:189], v[218:221], v[84:87]
	v_mfma_f32_16x16x32_bf16 v[80:83], v[194:197], v[218:221], v[80:83]
	v_mfma_f32_16x16x32_bf16 v[68:71], v[186:189], v[226:229], v[68:71]
	v_mfma_f32_16x16x32_bf16 v[64:67], v[194:197], v[226:229], v[64:67]
	s_barrier
	s_setprio 0
	s_mov_b32 m0, s5
	v_lshl_add_u64 v[160:161], s[0:1], 0, v[138:139]
	s_add_u32 s66, s0, 0x40000
	ds_read_b128 v[198:201], v164 offset:16384
	ds_read_b128 v[202:205], v164 offset:17408
	ds_read_b128 v[206:209], v164 offset:18432
	ds_read_b128 v[210:213], v164 offset:19456
	ds_read_b128 v[214:217], v164 offset:20480
	ds_read_b128 v[218:221], v164 offset:21504
	ds_read_b128 v[222:225], v164 offset:22528
	ds_read_b128 v[226:229], v164 offset:23552
	global_load_lds_dwordx4 v[160:161], off
	v_lshl_add_u64 v[230:231], s[0:1], 0, v[142:143]
	s_mov_b32 m0, s40
	s_addc_u32 s67, s1, 0
	global_load_lds_dwordx4 v[230:231], off
	v_lshl_add_u64 v[232:233], s[66:67], 0, v[138:139]
	s_mov_b32 m0, s41
	v_lshl_add_u64 v[234:235], s[36:37], 0, v[140:141]
	global_load_lds_dwordx4 v[232:233], off
	v_lshl_add_u64 v[232:233], s[66:67], 0, v[142:143]
	s_mov_b32 m0, s42
	s_nop 0
	global_load_lds_dwordx4 v[232:233], off
	v_lshl_add_u64 v[232:233], s[36:37], 0, v[136:137]
	s_mov_b32 m0, s39
	s_nop 0
	global_load_lds_dwordx4 v[232:233], off
	s_mov_b32 m0, s43
	s_nop 0
	global_load_lds_dwordx4 v[234:235], off
	s_waitcnt vmcnt(8)
	s_waitcnt lgkmcnt(0)
	s_setprio 1
	s_barrier
; #define PG8_STAGE(bufoff, gbase, voff) do { _Pragma("unroll") for (int _i = 0; _i < 2; ++_i) \
;         __builtin_amdgcn_global_load_lds((const unsigned*)((const char*)(gbase) + (voff)[_i]), (PG8_LAS unsigned*)(lds + (bufoff) + ldsw + _i * 8192), 16, 0, 0); } while (0)
; #define PG8_LDA(dst, b, h) do { _Pragma("unroll") for (int m = 0; m < 4; ++m) _Pragma("unroll") for (int k = 0; k < 2; ++k) dst[m][k] = *(const PG8_LAS bf16x8*)(lds + PG8_SA(b, h) + aoff + m * 2048 + k * 1024); } while (0)
; #define PG8_LDB(dst, b, h) do { _Pragma("unroll") for (int n = 0; n < 2; ++n) _Pragma("unroll") for (int k = 0; k < 2; ++k) dst[n][k] = *(const PG8_LAS bf16x8*)(lds + PG8_SB(b, h) + boff + n * 2048 + k * 1024); } while (0)
; #define PG8_MMA(ai, bj, At, Bt) do { __builtin_amdgcn_s_setprio(1); _Pragma("unroll") for (int m = 0; m < 4; ++m) _Pragma("unroll") for (int n = 0; n < 2; ++n) _Pragma("unroll") for (int k = 0; k < 2; ++k) \
;         acc[ai][bj][m][n] = __builtin_amdgcn_mfma_f32_16x16x32_bf16(Bt[n][k], At[m][k], acc[ai][bj][m][n], 0, 0, 0); __builtin_amdgcn_s_setprio(0); } while (0)
; #define PG8_BAR __builtin_amdgcn_s_barrier()
; template <class Epi, class Sched, bool ALIGN_EPI = false, bool SP2 = false>
; __device__ __forceinline__ void gemm_phase(PG8_LAS unsigned char* lds, const Gemm g, const Sched& S, const Epi& E, const int tid_arg) {
;     ...
;             PG8_LDB(B0, 0, 0); PG8_LDB(B1, 0, 1); PG8_SCHED; PG8_LDA(At, 0, 0); PG8_STAGE(PG8_SA(1, 1), a1 + hstep, voffA);
;             PG8_WAIT_V(8); PG8_WAIT_L(0); PG8_BAR; PG8_MMA(0, 0, At, B0); PG8_MMA(0, 1, At, B1); PG8_BAR; PG8_SCHED;
;             PG8_LDA(At, 0, 1); PG8_STAGE(PG8_SB(0, 0), b2, voffB); PG8_STAGE(PG8_SB(0, 1), b2 + hstep, voffB); PG8_STAGE(PG8_SA(0, 0), a2, voffA);
;             PG8_WAIT_V(8); PG8_WAIT_L(0); PG8_BAR; PG8_MMA(1, 0, At, B0); PG8_MMA(1, 1, At, B1); PG8_BAR; PG8_SCHED;
;             PG8_LDB(B0, 1, 0); PG8_LDB(B1, 1, 1); PG8_SCHED; PG8_LDA(At, 1, 0); PG8_STAGE(PG8_SA(0, 1), a2 + hstep, voffA);
;             PG8_WAIT_V(8); PG8_WAIT_L(0); PG8_BAR; PG8_MMA(0, 0, At, B0); PG8_MMA(0, 1, At, B1); PG8_BAR; PG8_SCHED;
;             PG8_LDA(At, 1, 1); PG8_STAGE(PG8_SB(1, 0), b3, voffB); PG8_STAGE(PG8_SB(1, 1), b3 + hstep, voffB); PG8_STAGE(PG8_SA(1, 0), a3, voffA);
;             PG8_WAIT_V(8); PG8_WAIT_L(0); PG8_BAR; PG8_MMA(1, 0, At, B0); PG8_MMA(1, 1, At, B1); PG8_BAR; PG8_SCHED;
	v_mfma_f32_16x16x32_bf16 v[60:63], v[128:131], v[198:201], 0
	v_mfma_f32_16x16x32_bf16 v[56:59], v[152:155], v[198:201], 0
	v_mfma_f32_16x16x32_bf16 v[44:47], v[128:131], v[206:209], 0
	v_mfma_f32_16x16x32_bf16 v[40:43], v[152:155], v[206:209], 0
	v_mfma_f32_16x16x32_bf16 v[28:31], v[128:131], v[214:217], 0
	v_mfma_f32_16x16x32_bf16 v[24:27], v[152:155], v[214:217], 0
	v_mfma_f32_16x16x32_bf16 v[12:15], v[128:131], v[222:225], 0
	v_mfma_f32_16x16x32_bf16 v[8:11], v[152:155], v[222:225], 0
	v_mfma_f32_16x16x32_bf16 v[60:63], v[132:135], v[202:205], v[60:63]
	v_mfma_f32_16x16x32_bf16 v[56:59], v[156:159], v[202:205], v[56:59]
	v_mfma_f32_16x16x32_bf16 v[44:47], v[132:135], v[210:213], v[44:47]
	v_mfma_f32_16x16x32_bf16 v[40:43], v[156:159], v[210:213], v[40:43]
	v_mfma_f32_16x16x32_bf16 v[28:31], v[132:135], v[218:221], v[28:31]
	v_mfma_f32_16x16x32_bf16 v[24:27], v[156:159], v[218:221], v[24:27]
	v_mfma_f32_16x16x32_bf16 v[12:15], v[132:135], v[226:229], v[12:15]
	v_mfma_f32_16x16x32_bf16 v[8:11], v[156:159], v[226:229], v[8:11]
	s_setprio 0
	s_setprio 1
	v_mfma_f32_16x16x32_bf16 v[52:55], v[182:185], v[198:201], 0
	v_mfma_f32_16x16x32_bf16 v[48:51], v[190:193], v[198:201], 0
	v_mfma_f32_16x16x32_bf16 v[36:39], v[182:185], v[206:209], 0
	v_mfma_f32_16x16x32_bf16 v[32:35], v[190:193], v[206:209], 0
	v_mfma_f32_16x16x32_bf16 v[20:23], v[182:185], v[214:217], 0
	v_mfma_f32_16x16x32_bf16 v[16:19], v[190:193], v[214:217], 0
	v_mfma_f32_16x16x32_bf16 v[4:7], v[182:185], v[222:225], 0
	v_mfma_f32_16x16x32_bf16 v[0:3], v[190:193], v[222:225], 0
	v_mfma_f32_16x16x32_bf16 v[52:55], v[186:189], v[202:205], v[52:55]
	v_mfma_f32_16x16x32_bf16 v[48:51], v[194:197], v[202:205], v[48:51]
	v_mfma_f32_16x16x32_bf16 v[36:39], v[186:189], v[210:213], v[36:39]
	v_mfma_f32_16x16x32_bf16 v[32:35], v[194:197], v[210:213], v[32:35]
	v_mfma_f32_16x16x32_bf16 v[20:23], v[186:189], v[218:221], v[20:23]
	v_mfma_f32_16x16x32_bf16 v[16:19], v[194:197], v[218:221], v[16:19]
	v_mfma_f32_16x16x32_bf16 v[4:7], v[186:189], v[226:229], v[4:7]
	v_mfma_f32_16x16x32_bf16 v[0:3], v[194:197], v[226:229], v[0:3]
	s_barrier
	s_setprio 0
	ds_read_b128 v[128:131], v173
	ds_read_b128 v[132:135], v174
	ds_read_b128 v[152:155], v175
	ds_read_b128 v[156:159], v176
	ds_read_b128 v[182:185], v177
	ds_read_b128 v[186:189], v178
	ds_read_b128 v[190:193], v179
	ds_read_b128 v[194:197], v180
	s_add_u32 s36, s36, 0x40000
	s_addc_u32 s37, s37, 0
	s_mov_b32 m0, s44
	v_lshl_add_u64 v[236:237], s[36:37], 0, v[136:137]
	ds_read_b128 v[198:201], v164 offset:32768
	ds_read_b128 v[202:205], v164 offset:33792
	ds_read_b128 v[206:209], v164 offset:34816
	ds_read_b128 v[210:213], v164 offset:35840
	ds_read_b128 v[214:217], v164 offset:36864
	ds_read_b128 v[218:221], v164 offset:37888
	ds_read_b128 v[222:225], v164 offset:38912
	ds_read_b128 v[226:229], v164 offset:39936
	global_load_lds_dwordx4 v[236:237], off
	v_lshl_add_u64 v[236:237], s[36:37], 0, v[140:141]
	s_mov_b32 m0, s45
	s_nop 0
	global_load_lds_dwordx4 v[236:237], off
	s_waitcnt vmcnt(8)
	s_waitcnt lgkmcnt(0)
	s_setprio 1
	s_barrier
	v_mfma_f32_16x16x32_bf16 v[124:127], v[128:131], v[198:201], v[124:127]
	v_mfma_f32_16x16x32_bf16 v[120:123], v[152:155], v[198:201], v[120:123]
	v_mfma_f32_16x16x32_bf16 v[108:111], v[128:131], v[206:209], v[108:111]
	v_mfma_f32_16x16x32_bf16 v[104:107], v[152:155], v[206:209], v[104:107]
	v_mfma_f32_16x16x32_bf16 v[92:95], v[128:131], v[214:217], v[92:95]
	v_mfma_f32_16x16x32_bf16 v[88:91], v[152:155], v[214:217], v[88:91]
	v_mfma_f32_16x16x32_bf16 v[76:79], v[128:131], v[222:225], v[76:79]
	v_mfma_f32_16x16x32_bf16 v[72:75], v[152:155], v[222:225], v[72:75]
	v_mfma_f32_16x16x32_bf16 v[124:127], v[132:135], v[202:205], v[124:127]
	v_mfma_f32_16x16x32_bf16 v[120:123], v[156:159], v[202:205], v[120:123]
	v_mfma_f32_16x16x32_bf16 v[108:111], v[132:135], v[210:213], v[108:111]
	v_mfma_f32_16x16x32_bf16 v[104:107], v[156:159], v[210:213], v[104:107]
	v_mfma_f32_16x16x32_bf16 v[92:95], v[132:135], v[218:221], v[92:95]
	v_mfma_f32_16x16x32_bf16 v[88:91], v[156:159], v[218:221], v[88:91]
	v_mfma_f32_16x16x32_bf16 v[76:79], v[132:135], v[226:229], v[76:79]
	v_mfma_f32_16x16x32_bf16 v[72:75], v[156:159], v[226:229], v[72:75]
	s_setprio 0
	s_setprio 1
	v_mfma_f32_16x16x32_bf16 v[116:119], v[182:185], v[198:201], v[116:119]
	v_mfma_f32_16x16x32_bf16 v[112:115], v[190:193], v[198:201], v[112:115]
	v_mfma_f32_16x16x32_bf16 v[100:103], v[182:185], v[206:209], v[100:103]
	v_mfma_f32_16x16x32_bf16 v[96:99], v[190:193], v[206:209], v[96:99]
	v_mfma_f32_16x16x32_bf16 v[84:87], v[182:185], v[214:217], v[84:87]
	v_mfma_f32_16x16x32_bf16 v[80:83], v[190:193], v[214:217], v[80:83]
	v_mfma_f32_16x16x32_bf16 v[68:71], v[182:185], v[222:225], v[68:71]
	v_mfma_f32_16x16x32_bf16 v[64:67], v[190:193], v[222:225], v[64:67]
	v_mfma_f32_16x16x32_bf16 v[116:119], v[186:189], v[202:205], v[116:119]
	v_mfma_f32_16x16x32_bf16 v[112:115], v[194:197], v[202:205], v[112:115]
	v_mfma_f32_16x16x32_bf16 v[100:103], v[186:189], v[210:213], v[100:103]
	v_mfma_f32_16x16x32_bf16 v[96:99], v[194:197], v[210:213], v[96:99]
	v_mfma_f32_16x16x32_bf16 v[84:87], v[186:189], v[218:221], v[84:87]
	v_mfma_f32_16x16x32_bf16 v[80:83], v[194:197], v[218:221], v[80:83]
	v_mfma_f32_16x16x32_bf16 v[68:71], v[186:189], v[226:229], v[68:71]
	v_mfma_f32_16x16x32_bf16 v[64:67], v[194:197], v[226:229], v[64:67]
	s_barrier
; #define PG8_STAGE(bufoff, gbase, voff) do { _Pragma("unroll") for (int _i = 0; _i < 2; ++_i) \
;         __builtin_amdgcn_global_load_lds((const unsigned*)((const char*)(gbase) + (voff)[_i]), (PG8_LAS unsigned*)(lds + (bufoff) + ldsw + _i * 8192), 16, 0, 0); } while (0)
; #define PG8_LDA(dst, b, h) do { _Pragma("unroll") for (int m = 0; m < 4; ++m) _Pragma("unroll") for (int k = 0; k < 2; ++k) dst[m][k] = *(const PG8_LAS bf16x8*)(lds + PG8_SA(b, h) + aoff + m * 2048 + k * 1024); } while (0)
; #define PG8_WAIT_V(n) asm volatile("s_waitcnt vmcnt(" #n ")" ::: "memory")
; #define PG8_WAIT_L(n) asm volatile("s_waitcnt lgkmcnt(" #n ")" ::: "memory")
; #define PG8_BAR __builtin_amdgcn_s_barrier()
; template <class Epi, class Sched, bool ALIGN_EPI = false, bool SP2 = false>
; __device__ __forceinline__ void gemm_phase(PG8_LAS unsigned char* lds, const Gemm g, const Sched& S, const Epi& E, const int tid_arg) {
;     ...
;         for (int t = 0; t < nt; t += 2) {
;             const bool last = (t == nt - 2);
;             const char* a1 = cA + (size_t)(t + 1) * kstep;
;             const char* a2 = last ? nA : cA + (size_t)(t + 2) * kstep; const char* b2 = last ? nB : cB + (size_t)(t + 2) * kstep;
;             const char* a3 = a2 + kstep; const char* b3 = b2 + kstep;
;             if (last && has_next) S.a_ready(nxt);
;             if constexpr (SP2) {
;             PG8_LDB(B0, 0, 0); PG8_LDB(B1, 0, 1); PG8_SCHED; PG8_LDA(At, 0, 0); PG8_STAGE(PG8_SA(1, 1), a1 + hstep, voffA);
;             PG8_WAIT_V(8); PG8_WAIT_L(0); PG8_BAR; PG8_MMA(0, 0, At, B0); PG8_MMA(0, 1, At, B1); PG8_BAR; PG8_SCHED;
;             PG8_LDA(At, 0, 1); PG8_STAGE(PG8_SB(0, 0), b2, voffB); PG8_STAGE(PG8_SB(0, 1), b2 + hstep, voffB); PG8_STAGE(PG8_SA(0, 0), a2, voffA);
;             PG8_WAIT_V(8); PG8_WAIT_L(0); PG8_BAR; PG8_MMA(1, 0, At, B0); PG8_MMA(1, 1, At, B1); PG8_BAR; PG8_SCHED;
;             PG8_LDB(B0, 1, 0); PG8_LDB(B1, 1, 1); PG8_SCHED; PG8_LDA(At, 1, 0); PG8_STAGE(PG8_SA(0, 1), a2 + hstep, voffA);
;             PG8_WAIT_V(8); PG8_WAIT_L(0); PG8_BAR; PG8_MMA(0, 0, At, B0); PG8_MMA(0, 1, At, B1); PG8_BAR; PG8_SCHED;
;             PG8_LDA(At, 1, 1); PG8_STAGE(PG8_SB(1, 0), b3, voffB); PG8_STAGE(PG8_SB(1, 1), b3 + hstep, voffB); PG8_STAGE(PG8_SA(1, 0), a3, voffA);
;             PG8_WAIT_V(8); PG8_WAIT_L(0); PG8_BAR; PG8_MMA(1, 0, At, B0); PG8_MMA(1, 1, At, B1); PG8_BAR; PG8_SCHED;
	s_setprio 0
	s_mov_b32 m0, s49
	v_lshl_add_u64 v[160:161], v[160:161], 0, s[20:21]
	s_add_u32 s0, s0, 0x40080
	ds_read_b128 v[198:201], v164 offset:49152
	ds_read_b128 v[202:205], v164 offset:50176
	ds_read_b128 v[206:209], v164 offset:51200
	ds_read_b128 v[210:213], v164 offset:52224
	ds_read_b128 v[214:217], v164 offset:53248
	ds_read_b128 v[218:221], v164 offset:54272
	ds_read_b128 v[222:225], v164 offset:55296
	ds_read_b128 v[226:229], v164 offset:56320
	global_load_lds_dwordx4 v[160:161], off
	v_lshl_add_u64 v[160:161], v[230:231], 0, s[20:21]
	s_mov_b32 m0, s50
	s_addc_u32 s1, s1, 0
	global_load_lds_dwordx4 v[160:161], off
	v_lshl_add_u64 v[160:161], s[0:1], 0, v[138:139]
	s_mov_b32 m0, s53
	s_nop 0
	global_load_lds_dwordx4 v[160:161], off
	v_lshl_add_u64 v[160:161], s[0:1], 0, v[142:143]
	s_mov_b32 m0, s54
	s_nop 0
	global_load_lds_dwordx4 v[160:161], off
	v_lshl_add_u64 v[160:161], v[232:233], 0, s[20:21]
	s_mov_b32 m0, s51
	s_nop 0
	global_load_lds_dwordx4 v[160:161], off
	v_lshl_add_u64 v[160:161], v[234:235], 0, s[20:21]
	s_mov_b32 m0, s52
	s_nop 0
	global_load_lds_dwordx4 v[160:161], off
	s_waitcnt vmcnt(8)
	s_waitcnt lgkmcnt(0)
	s_setprio 1
	s_barrier
	v_mfma_f32_16x16x32_bf16 v[60:63], v[128:131], v[198:201], v[60:63]
	v_mfma_f32_16x16x32_bf16 v[56:59], v[152:155], v[198:201], v[56:59]
	v_mfma_f32_16x16x32_bf16 v[44:47], v[128:131], v[206:209], v[44:47]
	v_mfma_f32_16x16x32_bf16 v[40:43], v[152:155], v[206:209], v[40:43]
	v_mfma_f32_16x16x32_bf16 v[28:31], v[128:131], v[214:217], v[28:31]
	v_mfma_f32_16x16x32_bf16 v[24:27], v[152:155], v[214:217], v[24:27]
	v_mfma_f32_16x16x32_bf16 v[12:15], v[128:131], v[222:225], v[12:15]
	v_mfma_f32_16x16x32_bf16 v[8:11], v[152:155], v[222:225], v[8:11]
	v_mfma_f32_16x16x32_bf16 v[60:63], v[132:135], v[202:205], v[60:63]
	v_mfma_f32_16x16x32_bf16 v[56:59], v[156:159], v[202:205], v[56:59]
	v_mfma_f32_16x16x32_bf16 v[44:47], v[132:135], v[210:213], v[44:47]
	v_mfma_f32_16x16x32_bf16 v[40:43], v[156:159], v[210:213], v[40:43]
	v_mfma_f32_16x16x32_bf16 v[28:31], v[132:135], v[218:221], v[28:31]
	v_mfma_f32_16x16x32_bf16 v[24:27], v[156:159], v[218:221], v[24:27]
	v_mfma_f32_16x16x32_bf16 v[12:15], v[132:135], v[226:229], v[12:15]
	v_mfma_f32_16x16x32_bf16 v[8:11], v[156:159], v[226:229], v[8:11]
	s_setprio 0
	s_setprio 1
	v_mfma_f32_16x16x32_bf16 v[52:55], v[182:185], v[198:201], v[52:55]
	v_mfma_f32_16x16x32_bf16 v[48:51], v[190:193], v[198:201], v[48:51]
	v_mfma_f32_16x16x32_bf16 v[36:39], v[182:185], v[206:209], v[36:39]
	v_mfma_f32_16x16x32_bf16 v[32:35], v[190:193], v[206:209], v[32:35]
	v_mfma_f32_16x16x32_bf16 v[20:23], v[182:185], v[214:217], v[20:23]
	v_mfma_f32_16x16x32_bf16 v[16:19], v[190:193], v[214:217], v[16:19]
	v_mfma_f32_16x16x32_bf16 v[4:7], v[182:185], v[222:225], v[4:7]
	v_mfma_f32_16x16x32_bf16 v[0:3], v[190:193], v[222:225], v[0:3]
	v_mfma_f32_16x16x32_bf16 v[52:55], v[186:189], v[202:205], v[52:55]
	v_mfma_f32_16x16x32_bf16 v[48:51], v[194:197], v[202:205], v[48:51]
	v_mfma_f32_16x16x32_bf16 v[36:39], v[186:189], v[210:213], v[36:39]
	v_mfma_f32_16x16x32_bf16 v[32:35], v[194:197], v[210:213], v[32:35]
	v_mfma_f32_16x16x32_bf16 v[20:23], v[186:189], v[218:221], v[20:23]
	v_mfma_f32_16x16x32_bf16 v[16:19], v[194:197], v[218:221], v[16:19]
	v_mfma_f32_16x16x32_bf16 v[4:7], v[186:189], v[226:229], v[4:7]
	v_mfma_f32_16x16x32_bf16 v[0:3], v[194:197], v[226:229], v[0:3]
	s_barrier
	s_setprio 0
	s_add_i32 s65, s65, 2
	s_add_u32 s63, s63, 0x100
	s_addc_u32 s64, s64, 0
	s_add_u32 s12, s12, 0x100
	s_addc_u32 s13, s13, 0
	s_cmp_gt_u32 s65, 13
	s_cbranch_scc0 .LBB0_533
	s_branch .Lkpeel_exit_2

; #define PG8_BAR __builtin_amdgcn_s_barrier()
; template <class Epi, class Sched, bool ALIGN_EPI = false, bool SP2 = false>
; __device__ __forceinline__ void gemm_phase(PG8_LAS unsigned char* lds, const Gemm g, const Sched& S, const Epi& E, const int tid_arg) {
;     ...
;         if constexpr (ALIGN_EPI) { if (wr == 0) PG8_BAR; }
.Lkpeel_exit_2:
	s_and_b64 vcc, exec, s[22:23]
	s_cbranch_vccz .LBB0_536
	s_barrier

; #define PG8_STAGE(bufoff, gbase, voff) do { _Pragma("unroll") for (int _i = 0; _i < 2; ++_i) \
;         __builtin_amdgcn_global_load_lds((const unsigned*)((const char*)(gbase) + (voff)[_i]), (PG8_LAS unsigned*)(lds + (bufoff) + ldsw + _i * 8192), 16, 0, 0); } while (0)
; #define PG8_LDA(dst, b, h) do { _Pragma("unroll") for (int m = 0; m < 4; ++m) _Pragma("unroll") for (int k = 0; k < 2; ++k) dst[m][k] = *(const PG8_LAS bf16x8*)(lds + PG8_SA(b, h) + aoff + m * 2048 + k * 1024); } while (0)
; #define PG8_LDB(dst, b, h) do { _Pragma("unroll") for (int n = 0; n < 2; ++n) _Pragma("unroll") for (int k = 0; k < 2; ++k) dst[n][k] = *(const PG8_LAS bf16x8*)(lds + PG8_SB(b, h) + boff + n * 2048 + k * 1024); } while (0)
; #define PG8_MMA(ai, bj, At, Bt) do { __builtin_amdgcn_s_setprio(1); _Pragma("unroll") for (int m = 0; m < 4; ++m) _Pragma("unroll") for (int n = 0; n < 2; ++n) _Pragma("unroll") for (int k = 0; k < 2; ++k) \
;         acc[ai][bj][m][n] = __builtin_amdgcn_mfma_f32_16x16x32_bf16(Bt[n][k], At[m][k], acc[ai][bj][m][n], 0, 0, 0); __builtin_amdgcn_s_setprio(0); } while (0)
; template <class Epi, class Sched, bool ALIGN_EPI = false, bool SP2 = false>
; __device__ __forceinline__ void gemm_phase(PG8_LAS unsigned char* lds, const Gemm g, const Sched& S, const Epi& E, const int tid_arg) {
;     ...
;         const bool has_next = S.next(ui + 1, nxt);
;         const char* nA = has_next ? (const char*)g.A + (size_t)nxt.pm * tstep : cA; const char* nB = has_next ? (const char*)g.Bt + (size_t)nxt.pn * tstep : cB;
;         for (int t = 0; t < nt; t += 2) {
;             const bool last = (t == nt - 2);
;             const char* a1 = cA + (size_t)(t + 1) * kstep;
;             const char* a2 = last ? nA : cA + (size_t)(t + 2) * kstep; const char* b2 = last ? nB : cB + (size_t)(t + 2) * kstep;
;             const char* a3 = a2 + kstep; const char* b3 = b2 + kstep;
;             if (last && has_next) S.a_ready(nxt);
;             if constexpr (SP2) {
;             PG8_LDB(B0, 0, 0); PG8_LDB(B1, 0, 1); PG8_SCHED; PG8_LDA(At, 0, 0); PG8_STAGE(PG8_SA(1, 1), a1 + hstep, voffA);
;             PG8_WAIT_V(8); PG8_WAIT_L(0); PG8_BAR; PG8_MMA(0, 0, At, B0); PG8_MMA(0, 1, At, B1); PG8_BAR; PG8_SCHED;
;             PG8_LDA(At, 0, 1); PG8_STAGE(PG8_SB(0, 0), b2, voffB); PG8_STAGE(PG8_SB(0, 1), b2 + hstep, voffB); PG8_STAGE(PG8_SA(0, 0), a2, voffA);
.LBB0_684:
	s_ashr_i32 s37, s36, 31
	s_lshl_b64 s[0:1], s[36:37], 19
	s_add_u32 s38, s2, s0
	s_addc_u32 s39, s3, s1
	s_and_b64 s[0:1], s[12:13], exec
	s_cselect_b32 s17, s39, s5
	s_cselect_b32 s37, s38, s4
	s_ashr_i32 s35, s34, 31
	s_lshl_b64 s[0:1], s[34:35], 19
	s_add_u32 s40, s33, s0
	s_addc_u32 s41, s48, s1
	s_and_b64 s[0:1], s[12:13], exec
	s_cselect_b32 s35, s41, s11
	s_cselect_b32 s46, s40, s10
	s_add_u32 s47, s10, 0x100
	v_mov_b32_e32 v0, 0
	s_addc_u32 s78, s11, 0
	s_mov_b32 s79, -2
	s_waitcnt vmcnt(0)
	ds_read_b128 v[72:75], v207
	ds_read_b128 v[100:103], v208
	ds_read_b128 v[136:139], v209
	ds_read_b128 v[140:143], v210
	ds_read_b128 v[144:147], v211
	ds_read_b128 v[148:151], v212
	ds_read_b128 v[152:155], v213
	ds_read_b128 v[156:159], v214
	s_add_u32 s10, s4, 0x100
	s_addc_u32 s11, s5, 0
	s_cmp_eq_u32 s79, 12
	s_cselect_b32 s15, s17, s11
	s_cselect_b32 s14, s37, s10
	s_cselect_b32 s1, s35, s78
	s_cselect_b32 s0, s46, s47
	s_mov_b32 m0, s72
	v_lshl_add_u64 v[184:185], s[4:5], 0, v[196:197]
	ds_read_b128 v[160:163], v206
	ds_read_b128 v[164:167], v206 offset:1024
	ds_read_b128 v[168:171], v206 offset:2048
	ds_read_b128 v[172:175], v206 offset:3072
	ds_read_b128 v[176:179], v206 offset:4096
	ds_read_b128 v[180:183], v206 offset:5120
	ds_read_b128 v[226:229], v206 offset:6144
	ds_read_b128 v[230:233], v206 offset:7168
	global_load_lds_dwordx4 v[184:185], off
	v_lshl_add_u64 v[184:185], s[4:5], 0, v[194:195]
	s_mov_b32 m0, s73
	s_nop 0
	global_load_lds_dwordx4 v[184:185], off
	s_waitcnt vmcnt(8)
	s_waitcnt lgkmcnt(0)
	s_setprio 1
	s_barrier
	v_mfma_f32_16x16x32_bf16 v[132:135], v[72:75], v[160:163], 0
	v_mfma_f32_16x16x32_bf16 v[60:63], v[136:139], v[160:163], 0
	v_mfma_f32_16x16x32_bf16 v[124:127], v[72:75], v[168:171], 0
	v_mfma_f32_16x16x32_bf16 v[52:55], v[136:139], v[168:171], 0
	v_mfma_f32_16x16x32_bf16 v[116:119], v[72:75], v[176:179], 0
	v_mfma_f32_16x16x32_bf16 v[44:47], v[136:139], v[176:179], 0
	v_mfma_f32_16x16x32_bf16 v[108:111], v[72:75], v[226:229], 0
	v_mfma_f32_16x16x32_bf16 v[36:39], v[136:139], v[226:229], 0
	v_mfma_f32_16x16x32_bf16 v[132:135], v[100:103], v[164:167], v[132:135]
	v_mfma_f32_16x16x32_bf16 v[60:63], v[140:143], v[164:167], v[60:63]
	v_mfma_f32_16x16x32_bf16 v[124:127], v[100:103], v[172:175], v[124:127]
	v_mfma_f32_16x16x32_bf16 v[52:55], v[140:143], v[172:175], v[52:55]
	v_mfma_f32_16x16x32_bf16 v[116:119], v[100:103], v[180:183], v[116:119]
	v_mfma_f32_16x16x32_bf16 v[44:47], v[140:143], v[180:183], v[44:47]
	v_mfma_f32_16x16x32_bf16 v[108:111], v[100:103], v[230:233], v[108:111]
	v_mfma_f32_16x16x32_bf16 v[36:39], v[140:143], v[230:233], v[36:39]
	s_setprio 0
	s_setprio 1
	v_mfma_f32_16x16x32_bf16 v[128:131], v[144:147], v[160:163], 0
	v_mfma_f32_16x16x32_bf16 v[56:59], v[152:155], v[160:163], 0
	v_mfma_f32_16x16x32_bf16 v[120:123], v[144:147], v[168:171], 0
	v_mfma_f32_16x16x32_bf16 v[48:51], v[152:155], v[168:171], 0
	v_mfma_f32_16x16x32_bf16 v[112:115], v[144:147], v[176:179], 0
	v_mfma_f32_16x16x32_bf16 v[40:43], v[152:155], v[176:179], 0
	v_mfma_f32_16x16x32_bf16 v[104:107], v[144:147], v[226:229], 0
	v_mfma_f32_16x16x32_bf16 v[32:35], v[152:155], v[226:229], 0
	v_mfma_f32_16x16x32_bf16 v[128:131], v[148:151], v[164:167], v[128:131]
	v_mfma_f32_16x16x32_bf16 v[56:59], v[156:159], v[164:167], v[56:59]
	v_mfma_f32_16x16x32_bf16 v[120:123], v[148:151], v[172:175], v[120:123]
	v_mfma_f32_16x16x32_bf16 v[48:51], v[156:159], v[172:175], v[48:51]
	v_mfma_f32_16x16x32_bf16 v[112:115], v[148:151], v[180:183], v[112:115]
	v_mfma_f32_16x16x32_bf16 v[40:43], v[156:159], v[180:183], v[40:43]
	v_mfma_f32_16x16x32_bf16 v[104:107], v[148:151], v[230:233], v[104:107]
	v_mfma_f32_16x16x32_bf16 v[32:35], v[156:159], v[230:233], v[32:35]
	s_barrier
	s_setprio 0
	s_mov_b32 m0, s43
	v_lshl_add_u64 v[184:185], s[0:1], 0, v[188:189]
	s_add_u32 s4, s0, 0x40000
	ds_read_b128 v[160:163], v206 offset:16384
	ds_read_b128 v[164:167], v206 offset:17408
	ds_read_b128 v[168:171], v206 offset:18432
	ds_read_b128 v[172:175], v206 offset:19456
	ds_read_b128 v[176:179], v206 offset:20480
	ds_read_b128 v[180:183], v206 offset:21504
	ds_read_b128 v[226:229], v206 offset:22528
	ds_read_b128 v[230:233], v206 offset:23552
	global_load_lds_dwordx4 v[184:185], off
	v_lshl_add_u64 v[202:203], s[0:1], 0, v[192:193]
	s_mov_b32 m0, s45
	s_addc_u32 s5, s1, 0
	global_load_lds_dwordx4 v[202:203], off
	v_lshl_add_u64 v[234:235], s[4:5], 0, v[188:189]
	s_mov_b32 m0, s50
	v_lshl_add_u64 v[236:237], s[14:15], 0, v[190:191]
	global_load_lds_dwordx4 v[234:235], off
	v_lshl_add_u64 v[234:235], s[4:5], 0, v[192:193]
	s_mov_b32 m0, s51
	s_nop 0
	global_load_lds_dwordx4 v[234:235], off
	v_lshl_add_u64 v[234:235], s[14:15], 0, v[186:187]
	s_mov_b32 m0, s49
	s_nop 0
	global_load_lds_dwordx4 v[234:235], off
	s_mov_b32 m0, s52
	s_nop 0
	global_load_lds_dwordx4 v[236:237], off
	s_waitcnt vmcnt(8)
	s_waitcnt lgkmcnt(0)
	s_setprio 1
	s_barrier
; #define PG8_STAGE(bufoff, gbase, voff) do { _Pragma("unroll") for (int _i = 0; _i < 2; ++_i) \
;         __builtin_amdgcn_global_load_lds((const unsigned*)((const char*)(gbase) + (voff)[_i]), (PG8_LAS unsigned*)(lds + (bufoff) + ldsw + _i * 8192), 16, 0, 0); } while (0)
; #define PG8_LDA(dst, b, h) do { _Pragma("unroll") for (int m = 0; m < 4; ++m) _Pragma("unroll") for (int k = 0; k < 2; ++k) dst[m][k] = *(const PG8_LAS bf16x8*)(lds + PG8_SA(b, h) + aoff + m * 2048 + k * 1024); } while (0)
; #define PG8_LDB(dst, b, h) do { _Pragma("unroll") for (int n = 0; n < 2; ++n) _Pragma("unroll") for (int k = 0; k < 2; ++k) dst[n][k] = *(const PG8_LAS bf16x8*)(lds + PG8_SB(b, h) + boff + n * 2048 + k * 1024); } while (0)
; #define PG8_MMA(ai, bj, At, Bt) do { __builtin_amdgcn_s_setprio(1); _Pragma("unroll") for (int m = 0; m < 4; ++m) _Pragma("unroll") for (int n = 0; n < 2; ++n) _Pragma("unroll") for (int k = 0; k < 2; ++k) \
;         acc[ai][bj][m][n] = __builtin_amdgcn_mfma_f32_16x16x32_bf16(Bt[n][k], At[m][k], acc[ai][bj][m][n], 0, 0, 0); __builtin_amdgcn_s_setprio(0); } while (0)
; #define PG8_WAIT_V(n) asm volatile("s_waitcnt vmcnt(" #n ")" ::: "memory")
; #define PG8_WAIT_L(n) asm volatile("s_waitcnt lgkmcnt(" #n ")" ::: "memory")
; #define PG8_BAR __builtin_amdgcn_s_barrier()
; #define PG8_SCHED __builtin_amdgcn_sched_barrier(0)
; template <class Epi, class Sched, bool ALIGN_EPI = false, bool SP2 = false>
; __device__ __forceinline__ void gemm_phase(PG8_LAS unsigned char* lds, const Gemm g, const Sched& S, const Epi& E, const int tid_arg) {
;     ...
;             PG8_WAIT_V(8); PG8_WAIT_L(0); PG8_BAR; PG8_MMA(1, 0, At, B0); PG8_MMA(1, 1, At, B1); PG8_BAR; PG8_SCHED;
;             PG8_LDB(B0, 1, 0); PG8_LDB(B1, 1, 1); PG8_SCHED; PG8_LDA(At, 1, 0); PG8_STAGE(PG8_SA(0, 1), a2 + hstep, voffA);
;             PG8_WAIT_V(8); PG8_WAIT_L(0); PG8_BAR; PG8_MMA(0, 0, At, B0); PG8_MMA(0, 1, At, B1); PG8_BAR; PG8_SCHED;
	v_mfma_f32_16x16x32_bf16 v[96:99], v[72:75], v[160:163], 0
	v_mfma_f32_16x16x32_bf16 v[28:31], v[136:139], v[160:163], 0
	v_mfma_f32_16x16x32_bf16 v[88:91], v[72:75], v[168:171], 0
	v_mfma_f32_16x16x32_bf16 v[20:23], v[136:139], v[168:171], 0
	v_mfma_f32_16x16x32_bf16 v[80:83], v[72:75], v[176:179], 0
	v_mfma_f32_16x16x32_bf16 v[12:15], v[136:139], v[176:179], 0
	v_mfma_f32_16x16x32_bf16 v[68:71], v[72:75], v[226:229], 0
	v_mfma_f32_16x16x32_bf16 v[4:7], v[136:139], v[226:229], 0
	v_mfma_f32_16x16x32_bf16 v[96:99], v[100:103], v[164:167], v[96:99]
	v_mfma_f32_16x16x32_bf16 v[28:31], v[140:143], v[164:167], v[28:31]
	v_mfma_f32_16x16x32_bf16 v[88:91], v[100:103], v[172:175], v[88:91]
	v_mfma_f32_16x16x32_bf16 v[20:23], v[140:143], v[172:175], v[20:23]
	v_mfma_f32_16x16x32_bf16 v[80:83], v[100:103], v[180:183], v[80:83]
	v_mfma_f32_16x16x32_bf16 v[12:15], v[140:143], v[180:183], v[12:15]
	v_mfma_f32_16x16x32_bf16 v[68:71], v[100:103], v[230:233], v[68:71]
	v_mfma_f32_16x16x32_bf16 v[4:7], v[140:143], v[230:233], v[4:7]
	s_setprio 0
	s_setprio 1
	v_mfma_f32_16x16x32_bf16 v[24:27], v[152:155], v[160:163], 0
	v_mfma_f32_16x16x32_bf16 v[84:87], v[144:147], v[168:171], 0
	v_mfma_f32_16x16x32_bf16 v[16:19], v[152:155], v[168:171], 0
	v_mfma_f32_16x16x32_bf16 v[76:79], v[144:147], v[176:179], 0
	v_mfma_f32_16x16x32_bf16 v[8:11], v[152:155], v[176:179], 0
	v_mfma_f32_16x16x32_bf16 v[64:67], v[144:147], v[226:229], 0
	v_mfma_f32_16x16x32_bf16 v[0:3], v[152:155], v[226:229], 0
	v_mfma_f32_16x16x32_bf16 v[72:75], v[144:147], v[160:163], 0
	v_mfma_f32_16x16x32_bf16 v[24:27], v[156:159], v[164:167], v[24:27]
	v_mfma_f32_16x16x32_bf16 v[84:87], v[148:151], v[172:175], v[84:87]
	v_mfma_f32_16x16x32_bf16 v[16:19], v[156:159], v[172:175], v[16:19]
	v_mfma_f32_16x16x32_bf16 v[76:79], v[148:151], v[180:183], v[76:79]
	v_mfma_f32_16x16x32_bf16 v[8:11], v[156:159], v[180:183], v[8:11]
	v_mfma_f32_16x16x32_bf16 v[64:67], v[148:151], v[230:233], v[64:67]
	v_mfma_f32_16x16x32_bf16 v[0:3], v[156:159], v[230:233], v[0:3]
	v_mfma_f32_16x16x32_bf16 v[72:75], v[148:151], v[164:167], v[72:75]
	s_barrier
	s_setprio 0
	ds_read_b128 v[92:95], v215
	ds_read_b128 v[100:103], v216
	ds_read_b128 v[136:139], v217
	ds_read_b128 v[140:143], v218
	ds_read_b128 v[144:147], v219
	ds_read_b128 v[148:151], v220
	ds_read_b128 v[152:155], v221
	ds_read_b128 v[156:159], v222
	s_add_u32 s4, s14, 0x40000
	s_addc_u32 s5, s15, 0
	s_mov_b32 m0, s53
	v_lshl_add_u64 v[238:239], s[4:5], 0, v[186:187]
	ds_read_b128 v[160:163], v206 offset:32768
	ds_read_b128 v[164:167], v206 offset:33792
	ds_read_b128 v[168:171], v206 offset:34816
	ds_read_b128 v[172:175], v206 offset:35840
	ds_read_b128 v[176:179], v206 offset:36864
	ds_read_b128 v[180:183], v206 offset:37888
	ds_read_b128 v[226:229], v206 offset:38912
	ds_read_b128 v[230:233], v206 offset:39936
	global_load_lds_dwordx4 v[238:239], off
	v_lshl_add_u64 v[238:239], s[4:5], 0, v[190:191]
	s_mov_b32 m0, s54
	s_nop 0
	global_load_lds_dwordx4 v[238:239], off
	s_waitcnt vmcnt(8)
	s_waitcnt lgkmcnt(0)
	s_setprio 1
	s_barrier
	v_mfma_f32_16x16x32_bf16 v[132:135], v[92:95], v[160:163], v[132:135]
	v_mfma_f32_16x16x32_bf16 v[60:63], v[136:139], v[160:163], v[60:63]
	v_mfma_f32_16x16x32_bf16 v[124:127], v[92:95], v[168:171], v[124:127]
	v_mfma_f32_16x16x32_bf16 v[52:55], v[136:139], v[168:171], v[52:55]
	v_mfma_f32_16x16x32_bf16 v[116:119], v[92:95], v[176:179], v[116:119]
	v_mfma_f32_16x16x32_bf16 v[44:47], v[136:139], v[176:179], v[44:47]
	v_mfma_f32_16x16x32_bf16 v[108:111], v[92:95], v[226:229], v[108:111]
	v_mfma_f32_16x16x32_bf16 v[36:39], v[136:139], v[226:229], v[36:39]
	v_mfma_f32_16x16x32_bf16 v[132:135], v[100:103], v[164:167], v[132:135]
	v_mfma_f32_16x16x32_bf16 v[60:63], v[140:143], v[164:167], v[60:63]
	v_mfma_f32_16x16x32_bf16 v[124:127], v[100:103], v[172:175], v[124:127]
	v_mfma_f32_16x16x32_bf16 v[52:55], v[140:143], v[172:175], v[52:55]
	v_mfma_f32_16x16x32_bf16 v[116:119], v[100:103], v[180:183], v[116:119]
	v_mfma_f32_16x16x32_bf16 v[44:47], v[140:143], v[180:183], v[44:47]
	v_mfma_f32_16x16x32_bf16 v[108:111], v[100:103], v[230:233], v[108:111]
	v_mfma_f32_16x16x32_bf16 v[36:39], v[140:143], v[230:233], v[36:39]
	s_setprio 0
	s_setprio 1
	v_mfma_f32_16x16x32_bf16 v[128:131], v[144:147], v[160:163], v[128:131]
	v_mfma_f32_16x16x32_bf16 v[56:59], v[152:155], v[160:163], v[56:59]
	v_mfma_f32_16x16x32_bf16 v[120:123], v[144:147], v[168:171], v[120:123]
	v_mfma_f32_16x16x32_bf16 v[48:51], v[152:155], v[168:171], v[48:51]
	v_mfma_f32_16x16x32_bf16 v[112:115], v[144:147], v[176:179], v[112:115]
	v_mfma_f32_16x16x32_bf16 v[40:43], v[152:155], v[176:179], v[40:43]
	v_mfma_f32_16x16x32_bf16 v[104:107], v[144:147], v[226:229], v[104:107]
	v_mfma_f32_16x16x32_bf16 v[32:35], v[152:155], v[226:229], v[32:35]
	v_mfma_f32_16x16x32_bf16 v[128:131], v[148:151], v[164:167], v[128:131]
	v_mfma_f32_16x16x32_bf16 v[56:59], v[156:159], v[164:167], v[56:59]
	v_mfma_f32_16x16x32_bf16 v[120:123], v[148:151], v[172:175], v[120:123]
	v_mfma_f32_16x16x32_bf16 v[48:51], v[156:159], v[172:175], v[48:51]
	v_mfma_f32_16x16x32_bf16 v[112:115], v[148:151], v[180:183], v[112:115]
	v_mfma_f32_16x16x32_bf16 v[40:43], v[156:159], v[180:183], v[40:43]
	v_mfma_f32_16x16x32_bf16 v[104:107], v[148:151], v[230:233], v[104:107]
	v_mfma_f32_16x16x32_bf16 v[32:35], v[156:159], v[230:233], v[32:35]
	s_barrier
; #define PG8_STAGE(bufoff, gbase, voff) do { _Pragma("unroll") for (int _i = 0; _i < 2; ++_i) \
;         __builtin_amdgcn_global_load_lds((const unsigned*)((const char*)(gbase) + (voff)[_i]), (PG8_LAS unsigned*)(lds + (bufoff) + ldsw + _i * 8192), 16, 0, 0); } while (0)
; #define PG8_LDA(dst, b, h) do { _Pragma("unroll") for (int m = 0; m < 4; ++m) _Pragma("unroll") for (int k = 0; k < 2; ++k) dst[m][k] = *(const PG8_LAS bf16x8*)(lds + PG8_SA(b, h) + aoff + m * 2048 + k * 1024); } while (0)
; #define PG8_LDB(dst, b, h) do { _Pragma("unroll") for (int n = 0; n < 2; ++n) _Pragma("unroll") for (int k = 0; k < 2; ++k) dst[n][k] = *(const PG8_LAS bf16x8*)(lds + PG8_SB(b, h) + boff + n * 2048 + k * 1024); } while (0)
; #define PG8_MMA(ai, bj, At, Bt) do { __builtin_amdgcn_s_setprio(1); _Pragma("unroll") for (int m = 0; m < 4; ++m) _Pragma("unroll") for (int n = 0; n < 2; ++n) _Pragma("unroll") for (int k = 0; k < 2; ++k) \
;         acc[ai][bj][m][n] = __builtin_amdgcn_mfma_f32_16x16x32_bf16(Bt[n][k], At[m][k], acc[ai][bj][m][n], 0, 0, 0); __builtin_amdgcn_s_setprio(0); } while (0)
; #define PG8_BAR __builtin_amdgcn_s_barrier()
; template <class Epi, class Sched, bool ALIGN_EPI = false, bool SP2 = false>
; __device__ __forceinline__ void gemm_phase(PG8_LAS unsigned char* lds, const Gemm g, const Sched& S, const Epi& E, const int tid_arg) {
;     ...
;             PG8_LDB(B0, 0, 0); PG8_LDB(B1, 0, 1); PG8_SCHED; PG8_LDA(At, 0, 0); PG8_STAGE(PG8_SA(1, 1), a1 + hstep, voffA);
;             PG8_WAIT_V(8); PG8_WAIT_L(0); PG8_BAR; PG8_MMA(0, 0, At, B0); PG8_MMA(0, 1, At, B1); PG8_BAR; PG8_SCHED;
;             PG8_LDA(At, 0, 1); PG8_STAGE(PG8_SB(0, 0), b2, voffB); PG8_STAGE(PG8_SB(0, 1), b2 + hstep, voffB); PG8_STAGE(PG8_SA(0, 0), a2, voffA);
;             PG8_WAIT_V(8); PG8_WAIT_L(0); PG8_BAR; PG8_MMA(1, 0, At, B0); PG8_MMA(1, 1, At, B1); PG8_BAR; PG8_SCHED;
;             PG8_LDB(B0, 1, 0); PG8_LDB(B1, 1, 1); PG8_SCHED; PG8_LDA(At, 1, 0); PG8_STAGE(PG8_SA(0, 1), a2 + hstep, voffA);
;             PG8_WAIT_V(8); PG8_WAIT_L(0); PG8_BAR; PG8_MMA(0, 0, At, B0); PG8_MMA(0, 1, At, B1); PG8_BAR; PG8_SCHED;
;             PG8_LDA(At, 1, 1); PG8_STAGE(PG8_SB(1, 0), b3, voffB); PG8_STAGE(PG8_SB(1, 1), b3 + hstep, voffB); PG8_STAGE(PG8_SA(1, 0), a3, voffA);
;             PG8_WAIT_V(8); PG8_WAIT_L(0); PG8_BAR; PG8_MMA(1, 0, At, B0); PG8_MMA(1, 1, At, B1); PG8_BAR; PG8_SCHED;
	s_setprio 0
	s_mov_b32 m0, s59
	v_lshl_add_u64 v[184:185], v[184:185], 0, s[24:25]
	s_add_u32 s0, s0, 0x40080
	ds_read_b128 v[160:163], v206 offset:49152
	ds_read_b128 v[164:167], v206 offset:50176
	ds_read_b128 v[168:171], v206 offset:51200
	ds_read_b128 v[172:175], v206 offset:52224
	ds_read_b128 v[176:179], v206 offset:53248
	ds_read_b128 v[180:183], v206 offset:54272
	ds_read_b128 v[226:229], v206 offset:55296
	ds_read_b128 v[230:233], v206 offset:56320
	global_load_lds_dwordx4 v[184:185], off
	v_lshl_add_u64 v[184:185], v[202:203], 0, s[24:25]
	s_mov_b32 m0, s60
	s_addc_u32 s1, s1, 0
	global_load_lds_dwordx4 v[184:185], off
	v_lshl_add_u64 v[184:185], s[0:1], 0, v[188:189]
	s_mov_b32 m0, s63
	s_nop 0
	global_load_lds_dwordx4 v[184:185], off
	v_lshl_add_u64 v[184:185], s[0:1], 0, v[192:193]
	s_mov_b32 m0, s64
	s_nop 0
	global_load_lds_dwordx4 v[184:185], off
	v_lshl_add_u64 v[184:185], v[234:235], 0, s[24:25]
	s_mov_b32 m0, s61
	s_nop 0
	global_load_lds_dwordx4 v[184:185], off
	v_lshl_add_u64 v[184:185], v[236:237], 0, s[24:25]
	s_mov_b32 m0, s62
	s_nop 0
	global_load_lds_dwordx4 v[184:185], off
	s_waitcnt vmcnt(8)
	s_waitcnt lgkmcnt(0)
	s_setprio 1
	s_barrier
	v_mfma_f32_16x16x32_bf16 v[96:99], v[92:95], v[160:163], v[96:99]
	v_mfma_f32_16x16x32_bf16 v[28:31], v[136:139], v[160:163], v[28:31]
	v_mfma_f32_16x16x32_bf16 v[88:91], v[92:95], v[168:171], v[88:91]
	v_mfma_f32_16x16x32_bf16 v[20:23], v[136:139], v[168:171], v[20:23]
	v_mfma_f32_16x16x32_bf16 v[80:83], v[92:95], v[176:179], v[80:83]
	v_mfma_f32_16x16x32_bf16 v[12:15], v[136:139], v[176:179], v[12:15]
	v_mfma_f32_16x16x32_bf16 v[68:71], v[92:95], v[226:229], v[68:71]
	v_mfma_f32_16x16x32_bf16 v[4:7], v[136:139], v[226:229], v[4:7]
	v_mfma_f32_16x16x32_bf16 v[96:99], v[100:103], v[164:167], v[96:99]
	v_mfma_f32_16x16x32_bf16 v[28:31], v[140:143], v[164:167], v[28:31]
	v_mfma_f32_16x16x32_bf16 v[88:91], v[100:103], v[172:175], v[88:91]
	v_mfma_f32_16x16x32_bf16 v[20:23], v[140:143], v[172:175], v[20:23]
	v_mfma_f32_16x16x32_bf16 v[80:83], v[100:103], v[180:183], v[80:83]
	v_mfma_f32_16x16x32_bf16 v[12:15], v[140:143], v[180:183], v[12:15]
	v_mfma_f32_16x16x32_bf16 v[68:71], v[100:103], v[230:233], v[68:71]
	v_mfma_f32_16x16x32_bf16 v[4:7], v[140:143], v[230:233], v[4:7]
	s_setprio 0
	s_setprio 1
	v_mfma_f32_16x16x32_bf16 v[72:75], v[144:147], v[160:163], v[72:75]
	v_mfma_f32_16x16x32_bf16 v[92:95], v[148:151], v[164:167], v[72:75]
	v_mfma_f32_16x16x32_bf16 v[72:75], v[144:147], v[168:171], v[84:87]
	v_mfma_f32_16x16x32_bf16 v[24:27], v[152:155], v[160:163], v[24:27]
	v_mfma_f32_16x16x32_bf16 v[84:87], v[148:151], v[172:175], v[72:75]
	v_mfma_f32_16x16x32_bf16 v[16:19], v[152:155], v[168:171], v[16:19]
	v_mfma_f32_16x16x32_bf16 v[72:75], v[144:147], v[176:179], v[76:79]
	v_mfma_f32_16x16x32_bf16 v[8:11], v[152:155], v[176:179], v[8:11]
	v_mfma_f32_16x16x32_bf16 v[64:67], v[144:147], v[226:229], v[64:67]
	v_mfma_f32_16x16x32_bf16 v[0:3], v[152:155], v[226:229], v[0:3]
	v_mfma_f32_16x16x32_bf16 v[24:27], v[156:159], v[164:167], v[24:27]
	v_mfma_f32_16x16x32_bf16 v[16:19], v[156:159], v[172:175], v[16:19]
	v_mfma_f32_16x16x32_bf16 v[76:79], v[148:151], v[180:183], v[72:75]
	v_mfma_f32_16x16x32_bf16 v[8:11], v[156:159], v[180:183], v[8:11]
	v_mfma_f32_16x16x32_bf16 v[64:67], v[148:151], v[230:233], v[64:67]
	v_mfma_f32_16x16x32_bf16 v[0:3], v[156:159], v[230:233], v[0:3]
	s_barrier
	s_setprio 0
	s_add_i32 s79, s79, 2
	s_add_u32 s47, s47, 0x100
	s_addc_u32 s78, s78, 0
	s_cmp_gt_u32 s79, 13
	s_mov_b64 s[4:5], s[10:11]
	s_cbranch_scc0 .LBB0_685
	s_branch .Lkpeel_exit_3
.LBB0_685:
	ds_read_b128 v[72:75], v207
	ds_read_b128 v[100:103], v208
	ds_read_b128 v[136:139], v209
	ds_read_b128 v[140:143], v210
	ds_read_b128 v[144:147], v211
	ds_read_b128 v[148:151], v212
	ds_read_b128 v[152:155], v213
	ds_read_b128 v[156:159], v214
	s_add_u32 s10, s4, 0x100
	s_addc_u32 s11, s5, 0
	s_cmp_eq_u32 s79, 12
	s_cselect_b32 s15, s17, s11
	s_cselect_b32 s14, s37, s10
	s_cselect_b32 s1, s35, s78
	s_cselect_b32 s0, s46, s47
	s_mov_b32 m0, s72
	v_lshl_add_u64 v[184:185], s[4:5], 0, v[196:197]
	ds_read_b128 v[160:163], v206
	ds_read_b128 v[164:167], v206 offset:1024
	ds_read_b128 v[168:171], v206 offset:2048
	ds_read_b128 v[172:175], v206 offset:3072
	ds_read_b128 v[176:179], v206 offset:4096
	ds_read_b128 v[180:183], v206 offset:5120
	ds_read_b128 v[226:229], v206 offset:6144
	ds_read_b128 v[230:233], v206 offset:7168
	global_load_lds_dwordx4 v[184:185], off
	v_lshl_add_u64 v[184:185], s[4:5], 0, v[194:195]
	s_mov_b32 m0, s73
	s_nop 0
	global_load_lds_dwordx4 v[184:185], off
	s_waitcnt vmcnt(8)
	s_waitcnt lgkmcnt(0)
	s_setprio 1
	s_barrier
; #define PG8_STAGE(bufoff, gbase, voff) do { _Pragma("unroll") for (int _i = 0; _i < 2; ++_i) \
;         __builtin_amdgcn_global_load_lds((const unsigned*)((const char*)(gbase) + (voff)[_i]), (PG8_LAS unsigned*)(lds + (bufoff) + ldsw + _i * 8192), 16, 0, 0); } while (0)
; #define PG8_LDA(dst, b, h) do { _Pragma("unroll") for (int m = 0; m < 4; ++m) _Pragma("unroll") for (int k = 0; k < 2; ++k) dst[m][k] = *(const PG8_LAS bf16x8*)(lds + PG8_SA(b, h) + aoff + m * 2048 + k * 1024); } while (0)
; #define PG8_LDB(dst, b, h) do { _Pragma("unroll") for (int n = 0; n < 2; ++n) _Pragma("unroll") for (int k = 0; k < 2; ++k) dst[n][k] = *(const PG8_LAS bf16x8*)(lds + PG8_SB(b, h) + boff + n * 2048 + k * 1024); } while (0)
; #define PG8_MMA(ai, bj, At, Bt) do { __builtin_amdgcn_s_setprio(1); _Pragma("unroll") for (int m = 0; m < 4; ++m) _Pragma("unroll") for (int n = 0; n < 2; ++n) _Pragma("unroll") for (int k = 0; k < 2; ++k) \
;         acc[ai][bj][m][n] = __builtin_amdgcn_mfma_f32_16x16x32_bf16(Bt[n][k], At[m][k], acc[ai][bj][m][n], 0, 0, 0); __builtin_amdgcn_s_setprio(0); } while (0)
; #define PG8_WAIT_V(n) asm volatile("s_waitcnt vmcnt(" #n ")" ::: "memory")
; #define PG8_WAIT_L(n) asm volatile("s_waitcnt lgkmcnt(" #n ")" ::: "memory")
; #define PG8_BAR __builtin_amdgcn_s_barrier()
; #define PG8_SCHED __builtin_amdgcn_sched_barrier(0)
; template <class Epi, class Sched, bool ALIGN_EPI = false, bool SP2 = false>
; __device__ __forceinline__ void gemm_phase(PG8_LAS unsigned char* lds, const Gemm g, const Sched& S, const Epi& E, const int tid_arg) {
;     ...
;             PG8_LDB(B0, 0, 0); PG8_LDB(B1, 0, 1); PG8_SCHED; PG8_LDA(At, 0, 0); PG8_STAGE(PG8_SA(1, 1), a1 + hstep, voffA);
;             PG8_WAIT_V(8); PG8_WAIT_L(0); PG8_BAR; PG8_MMA(0, 0, At, B0); PG8_MMA(0, 1, At, B1); PG8_BAR; PG8_SCHED;
;             PG8_LDA(At, 0, 1); PG8_STAGE(PG8_SB(0, 0), b2, voffB); PG8_STAGE(PG8_SB(0, 1), b2 + hstep, voffB); PG8_STAGE(PG8_SA(0, 0), a2, voffA);
;             PG8_WAIT_V(8); PG8_WAIT_L(0); PG8_BAR; PG8_MMA(1, 0, At, B0); PG8_MMA(1, 1, At, B1); PG8_BAR; PG8_SCHED;
	v_mfma_f32_16x16x32_bf16 v[132:135], v[72:75], v[160:163], v[132:135]
	v_mfma_f32_16x16x32_bf16 v[60:63], v[136:139], v[160:163], v[60:63]
	v_mfma_f32_16x16x32_bf16 v[124:127], v[72:75], v[168:171], v[124:127]
	v_mfma_f32_16x16x32_bf16 v[52:55], v[136:139], v[168:171], v[52:55]
	v_mfma_f32_16x16x32_bf16 v[116:119], v[72:75], v[176:179], v[116:119]
	v_mfma_f32_16x16x32_bf16 v[44:47], v[136:139], v[176:179], v[44:47]
	v_mfma_f32_16x16x32_bf16 v[108:111], v[72:75], v[226:229], v[108:111]
	v_mfma_f32_16x16x32_bf16 v[36:39], v[136:139], v[226:229], v[36:39]
	v_mfma_f32_16x16x32_bf16 v[132:135], v[100:103], v[164:167], v[132:135]
	v_mfma_f32_16x16x32_bf16 v[60:63], v[140:143], v[164:167], v[60:63]
	v_mfma_f32_16x16x32_bf16 v[124:127], v[100:103], v[172:175], v[124:127]
	v_mfma_f32_16x16x32_bf16 v[52:55], v[140:143], v[172:175], v[52:55]
	v_mfma_f32_16x16x32_bf16 v[116:119], v[100:103], v[180:183], v[116:119]
	v_mfma_f32_16x16x32_bf16 v[44:47], v[140:143], v[180:183], v[44:47]
	v_mfma_f32_16x16x32_bf16 v[108:111], v[100:103], v[230:233], v[108:111]
	v_mfma_f32_16x16x32_bf16 v[36:39], v[140:143], v[230:233], v[36:39]
	s_setprio 0
	s_setprio 1
	v_mfma_f32_16x16x32_bf16 v[128:131], v[144:147], v[160:163], v[128:131]
	v_mfma_f32_16x16x32_bf16 v[56:59], v[152:155], v[160:163], v[56:59]
	v_mfma_f32_16x16x32_bf16 v[120:123], v[144:147], v[168:171], v[120:123]
	v_mfma_f32_16x16x32_bf16 v[48:51], v[152:155], v[168:171], v[48:51]
	v_mfma_f32_16x16x32_bf16 v[112:115], v[144:147], v[176:179], v[112:115]
	v_mfma_f32_16x16x32_bf16 v[40:43], v[152:155], v[176:179], v[40:43]
	v_mfma_f32_16x16x32_bf16 v[104:107], v[144:147], v[226:229], v[104:107]
	v_mfma_f32_16x16x32_bf16 v[32:35], v[152:155], v[226:229], v[32:35]
	v_mfma_f32_16x16x32_bf16 v[128:131], v[148:151], v[164:167], v[128:131]
	v_mfma_f32_16x16x32_bf16 v[56:59], v[156:159], v[164:167], v[56:59]
	v_mfma_f32_16x16x32_bf16 v[120:123], v[148:151], v[172:175], v[120:123]
	v_mfma_f32_16x16x32_bf16 v[48:51], v[156:159], v[172:175], v[48:51]
	v_mfma_f32_16x16x32_bf16 v[112:115], v[148:151], v[180:183], v[112:115]
	v_mfma_f32_16x16x32_bf16 v[40:43], v[156:159], v[180:183], v[40:43]
	v_mfma_f32_16x16x32_bf16 v[104:107], v[148:151], v[230:233], v[104:107]
	v_mfma_f32_16x16x32_bf16 v[32:35], v[156:159], v[230:233], v[32:35]
	s_barrier
	s_setprio 0
	s_mov_b32 m0, s43
	v_lshl_add_u64 v[184:185], s[0:1], 0, v[188:189]
	s_add_u32 s4, s0, 0x40000
	ds_read_b128 v[160:163], v206 offset:16384
	ds_read_b128 v[164:167], v206 offset:17408
	ds_read_b128 v[168:171], v206 offset:18432
	ds_read_b128 v[172:175], v206 offset:19456
	ds_read_b128 v[176:179], v206 offset:20480
	ds_read_b128 v[180:183], v206 offset:21504
	ds_read_b128 v[226:229], v206 offset:22528
	ds_read_b128 v[230:233], v206 offset:23552
	global_load_lds_dwordx4 v[184:185], off
	v_lshl_add_u64 v[202:203], s[0:1], 0, v[192:193]
	s_mov_b32 m0, s45
	s_addc_u32 s5, s1, 0
	global_load_lds_dwordx4 v[202:203], off
	v_lshl_add_u64 v[234:235], s[4:5], 0, v[188:189]
	s_mov_b32 m0, s50
	v_lshl_add_u64 v[236:237], s[14:15], 0, v[190:191]
	global_load_lds_dwordx4 v[234:235], off
	v_lshl_add_u64 v[234:235], s[4:5], 0, v[192:193]
	s_mov_b32 m0, s51
	s_nop 0
	global_load_lds_dwordx4 v[234:235], off
	v_lshl_add_u64 v[234:235], s[14:15], 0, v[186:187]
	s_mov_b32 m0, s49
	s_nop 0
	global_load_lds_dwordx4 v[234:235], off
	s_mov_b32 m0, s52
	s_nop 0
	global_load_lds_dwordx4 v[236:237], off
	s_waitcnt vmcnt(8)
	s_waitcnt lgkmcnt(0)
	s_setprio 1
	s_barrier
	v_mfma_f32_16x16x32_bf16 v[96:99], v[72:75], v[160:163], v[96:99]
	v_mfma_f32_16x16x32_bf16 v[28:31], v[136:139], v[160:163], v[28:31]
	v_mfma_f32_16x16x32_bf16 v[88:91], v[72:75], v[168:171], v[88:91]
	v_mfma_f32_16x16x32_bf16 v[20:23], v[136:139], v[168:171], v[20:23]
	v_mfma_f32_16x16x32_bf16 v[80:83], v[72:75], v[176:179], v[80:83]
	v_mfma_f32_16x16x32_bf16 v[12:15], v[136:139], v[176:179], v[12:15]
	v_mfma_f32_16x16x32_bf16 v[68:71], v[72:75], v[226:229], v[68:71]
	v_mfma_f32_16x16x32_bf16 v[4:7], v[136:139], v[226:229], v[4:7]
	v_mfma_f32_16x16x32_bf16 v[96:99], v[100:103], v[164:167], v[96:99]
	v_mfma_f32_16x16x32_bf16 v[28:31], v[140:143], v[164:167], v[28:31]
	v_mfma_f32_16x16x32_bf16 v[88:91], v[100:103], v[172:175], v[88:91]
	v_mfma_f32_16x16x32_bf16 v[20:23], v[140:143], v[172:175], v[20:23]
	v_mfma_f32_16x16x32_bf16 v[80:83], v[100:103], v[180:183], v[80:83]
	v_mfma_f32_16x16x32_bf16 v[12:15], v[140:143], v[180:183], v[12:15]
	v_mfma_f32_16x16x32_bf16 v[68:71], v[100:103], v[230:233], v[68:71]
	v_mfma_f32_16x16x32_bf16 v[4:7], v[140:143], v[230:233], v[4:7]
	s_setprio 0
	s_setprio 1
	v_mfma_f32_16x16x32_bf16 v[24:27], v[152:155], v[160:163], v[24:27]
	v_mfma_f32_16x16x32_bf16 v[84:87], v[144:147], v[168:171], v[84:87]
	v_mfma_f32_16x16x32_bf16 v[16:19], v[152:155], v[168:171], v[16:19]
	v_mfma_f32_16x16x32_bf16 v[76:79], v[144:147], v[176:179], v[76:79]
	v_mfma_f32_16x16x32_bf16 v[8:11], v[152:155], v[176:179], v[8:11]
	v_mfma_f32_16x16x32_bf16 v[64:67], v[144:147], v[226:229], v[64:67]
	v_mfma_f32_16x16x32_bf16 v[0:3], v[152:155], v[226:229], v[0:3]
	v_mfma_f32_16x16x32_bf16 v[72:75], v[144:147], v[160:163], v[92:95]
	v_mfma_f32_16x16x32_bf16 v[24:27], v[156:159], v[164:167], v[24:27]
	v_mfma_f32_16x16x32_bf16 v[84:87], v[148:151], v[172:175], v[84:87]
	v_mfma_f32_16x16x32_bf16 v[16:19], v[156:159], v[172:175], v[16:19]
	v_mfma_f32_16x16x32_bf16 v[76:79], v[148:151], v[180:183], v[76:79]
	v_mfma_f32_16x16x32_bf16 v[8:11], v[156:159], v[180:183], v[8:11]
	v_mfma_f32_16x16x32_bf16 v[64:67], v[148:151], v[230:233], v[64:67]
	v_mfma_f32_16x16x32_bf16 v[0:3], v[156:159], v[230:233], v[0:3]
	v_mfma_f32_16x16x32_bf16 v[72:75], v[148:151], v[164:167], v[72:75]
	s_barrier
; #define PG8_STAGE(bufoff, gbase, voff) do { _Pragma("unroll") for (int _i = 0; _i < 2; ++_i) \
;         __builtin_amdgcn_global_load_lds((const unsigned*)((const char*)(gbase) + (voff)[_i]), (PG8_LAS unsigned*)(lds + (bufoff) + ldsw + _i * 8192), 16, 0, 0); } while (0)
; #define PG8_LDA(dst, b, h) do { _Pragma("unroll") for (int m = 0; m < 4; ++m) _Pragma("unroll") for (int k = 0; k < 2; ++k) dst[m][k] = *(const PG8_LAS bf16x8*)(lds + PG8_SA(b, h) + aoff + m * 2048 + k * 1024); } while (0)
; #define PG8_LDB(dst, b, h) do { _Pragma("unroll") for (int n = 0; n < 2; ++n) _Pragma("unroll") for (int k = 0; k < 2; ++k) dst[n][k] = *(const PG8_LAS bf16x8*)(lds + PG8_SB(b, h) + boff + n * 2048 + k * 1024); } while (0)
; #define PG8_MMA(ai, bj, At, Bt) do { __builtin_amdgcn_s_setprio(1); _Pragma("unroll") for (int m = 0; m < 4; ++m) _Pragma("unroll") for (int n = 0; n < 2; ++n) _Pragma("unroll") for (int k = 0; k < 2; ++k) \
;         acc[ai][bj][m][n] = __builtin_amdgcn_mfma_f32_16x16x32_bf16(Bt[n][k], At[m][k], acc[ai][bj][m][n], 0, 0, 0); __builtin_amdgcn_s_setprio(0); } while (0)
; #define PG8_WAIT_V(n) asm volatile("s_waitcnt vmcnt(" #n ")" ::: "memory")
; #define PG8_WAIT_L(n) asm volatile("s_waitcnt lgkmcnt(" #n ")" ::: "memory")
; #define PG8_BAR __builtin_amdgcn_s_barrier()
; #define PG8_SCHED __builtin_amdgcn_sched_barrier(0)
; template <class Epi, class Sched, bool ALIGN_EPI = false, bool SP2 = false>
; __device__ __forceinline__ void gemm_phase(PG8_LAS unsigned char* lds, const Gemm g, const Sched& S, const Epi& E, const int tid_arg) {
;     ...
;             PG8_LDB(B0, 1, 0); PG8_LDB(B1, 1, 1); PG8_SCHED; PG8_LDA(At, 1, 0); PG8_STAGE(PG8_SA(0, 1), a2 + hstep, voffA);
;             PG8_WAIT_V(8); PG8_WAIT_L(0); PG8_BAR; PG8_MMA(0, 0, At, B0); PG8_MMA(0, 1, At, B1); PG8_BAR; PG8_SCHED;
;             PG8_LDA(At, 1, 1); PG8_STAGE(PG8_SB(1, 0), b3, voffB); PG8_STAGE(PG8_SB(1, 1), b3 + hstep, voffB); PG8_STAGE(PG8_SA(1, 0), a3, voffA);
;             PG8_WAIT_V(8); PG8_WAIT_L(0); PG8_BAR; PG8_MMA(1, 0, At, B0); PG8_MMA(1, 1, At, B1); PG8_BAR; PG8_SCHED;
	s_setprio 0
	ds_read_b128 v[92:95], v215
	ds_read_b128 v[100:103], v216
	ds_read_b128 v[136:139], v217
	ds_read_b128 v[140:143], v218
	ds_read_b128 v[144:147], v219
	ds_read_b128 v[148:151], v220
	ds_read_b128 v[152:155], v221
	ds_read_b128 v[156:159], v222
	s_add_u32 s4, s14, 0x40000
	s_addc_u32 s5, s15, 0
	s_mov_b32 m0, s53
	v_lshl_add_u64 v[238:239], s[4:5], 0, v[186:187]
	ds_read_b128 v[160:163], v206 offset:32768
	ds_read_b128 v[164:167], v206 offset:33792
	ds_read_b128 v[168:171], v206 offset:34816
	ds_read_b128 v[172:175], v206 offset:35840
	ds_read_b128 v[176:179], v206 offset:36864
	ds_read_b128 v[180:183], v206 offset:37888
	ds_read_b128 v[226:229], v206 offset:38912
	ds_read_b128 v[230:233], v206 offset:39936
	global_load_lds_dwordx4 v[238:239], off
	v_lshl_add_u64 v[238:239], s[4:5], 0, v[190:191]
	s_mov_b32 m0, s54
	s_nop 0
	global_load_lds_dwordx4 v[238:239], off
	s_waitcnt vmcnt(8)
	s_waitcnt lgkmcnt(0)
	s_setprio 1
	s_barrier
	v_mfma_f32_16x16x32_bf16 v[132:135], v[92:95], v[160:163], v[132:135]
	v_mfma_f32_16x16x32_bf16 v[60:63], v[136:139], v[160:163], v[60:63]
	v_mfma_f32_16x16x32_bf16 v[124:127], v[92:95], v[168:171], v[124:127]
	v_mfma_f32_16x16x32_bf16 v[52:55], v[136:139], v[168:171], v[52:55]
	v_mfma_f32_16x16x32_bf16 v[116:119], v[92:95], v[176:179], v[116:119]
	v_mfma_f32_16x16x32_bf16 v[44:47], v[136:139], v[176:179], v[44:47]
	v_mfma_f32_16x16x32_bf16 v[108:111], v[92:95], v[226:229], v[108:111]
	v_mfma_f32_16x16x32_bf16 v[36:39], v[136:139], v[226:229], v[36:39]
	v_mfma_f32_16x16x32_bf16 v[132:135], v[100:103], v[164:167], v[132:135]
	v_mfma_f32_16x16x32_bf16 v[60:63], v[140:143], v[164:167], v[60:63]
	v_mfma_f32_16x16x32_bf16 v[124:127], v[100:103], v[172:175], v[124:127]
	v_mfma_f32_16x16x32_bf16 v[52:55], v[140:143], v[172:175], v[52:55]
	v_mfma_f32_16x16x32_bf16 v[116:119], v[100:103], v[180:183], v[116:119]
	v_mfma_f32_16x16x32_bf16 v[44:47], v[140:143], v[180:183], v[44:47]
	v_mfma_f32_16x16x32_bf16 v[108:111], v[100:103], v[230:233], v[108:111]
	v_mfma_f32_16x16x32_bf16 v[36:39], v[140:143], v[230:233], v[36:39]
	s_setprio 0
	s_setprio 1
	v_mfma_f32_16x16x32_bf16 v[128:131], v[144:147], v[160:163], v[128:131]
	v_mfma_f32_16x16x32_bf16 v[56:59], v[152:155], v[160:163], v[56:59]
	v_mfma_f32_16x16x32_bf16 v[120:123], v[144:147], v[168:171], v[120:123]
	v_mfma_f32_16x16x32_bf16 v[48:51], v[152:155], v[168:171], v[48:51]
	v_mfma_f32_16x16x32_bf16 v[112:115], v[144:147], v[176:179], v[112:115]
	v_mfma_f32_16x16x32_bf16 v[40:43], v[152:155], v[176:179], v[40:43]
	v_mfma_f32_16x16x32_bf16 v[104:107], v[144:147], v[226:229], v[104:107]
	v_mfma_f32_16x16x32_bf16 v[32:35], v[152:155], v[226:229], v[32:35]
	v_mfma_f32_16x16x32_bf16 v[128:131], v[148:151], v[164:167], v[128:131]
	v_mfma_f32_16x16x32_bf16 v[56:59], v[156:159], v[164:167], v[56:59]
	v_mfma_f32_16x16x32_bf16 v[120:123], v[148:151], v[172:175], v[120:123]
	v_mfma_f32_16x16x32_bf16 v[48:51], v[156:159], v[172:175], v[48:51]
	v_mfma_f32_16x16x32_bf16 v[112:115], v[148:151], v[180:183], v[112:115]
	v_mfma_f32_16x16x32_bf16 v[40:43], v[156:159], v[180:183], v[40:43]
	v_mfma_f32_16x16x32_bf16 v[104:107], v[148:151], v[230:233], v[104:107]
	v_mfma_f32_16x16x32_bf16 v[32:35], v[156:159], v[230:233], v[32:35]
	s_barrier
	s_setprio 0
	s_mov_b32 m0, s59
	v_lshl_add_u64 v[184:185], v[184:185], 0, s[24:25]
	s_add_u32 s0, s0, 0x40080
	ds_read_b128 v[160:163], v206 offset:49152
	ds_read_b128 v[164:167], v206 offset:50176
	ds_read_b128 v[168:171], v206 offset:51200
	ds_read_b128 v[172:175], v206 offset:52224
	ds_read_b128 v[176:179], v206 offset:53248
	ds_read_b128 v[180:183], v206 offset:54272
	ds_read_b128 v[226:229], v206 offset:55296
	ds_read_b128 v[230:233], v206 offset:56320
	global_load_lds_dwordx4 v[184:185], off
	v_lshl_add_u64 v[184:185], v[202:203], 0, s[24:25]
	s_mov_b32 m0, s60
	s_addc_u32 s1, s1, 0
	global_load_lds_dwordx4 v[184:185], off
	v_lshl_add_u64 v[184:185], s[0:1], 0, v[188:189]
	s_mov_b32 m0, s63
	s_nop 0
	global_load_lds_dwordx4 v[184:185], off
	v_lshl_add_u64 v[184:185], s[0:1], 0, v[192:193]
	s_mov_b32 m0, s64
	s_nop 0
	global_load_lds_dwordx4 v[184:185], off
	v_lshl_add_u64 v[184:185], v[234:235], 0, s[24:25]
	s_mov_b32 m0, s61
	s_nop 0
	global_load_lds_dwordx4 v[184:185], off
	v_lshl_add_u64 v[184:185], v[236:237], 0, s[24:25]
	s_mov_b32 m0, s62
	s_nop 0
	global_load_lds_dwordx4 v[184:185], off
	s_waitcnt vmcnt(8)
	s_waitcnt lgkmcnt(0)
	s_setprio 1
	s_barrier
	v_mfma_f32_16x16x32_bf16 v[96:99], v[92:95], v[160:163], v[96:99]
	v_mfma_f32_16x16x32_bf16 v[28:31], v[136:139], v[160:163], v[28:31]
	v_mfma_f32_16x16x32_bf16 v[88:91], v[92:95], v[168:171], v[88:91]
	v_mfma_f32_16x16x32_bf16 v[20:23], v[136:139], v[168:171], v[20:23]
	v_mfma_f32_16x16x32_bf16 v[80:83], v[92:95], v[176:179], v[80:83]
	v_mfma_f32_16x16x32_bf16 v[12:15], v[136:139], v[176:179], v[12:15]
	v_mfma_f32_16x16x32_bf16 v[68:71], v[92:95], v[226:229], v[68:71]
	v_mfma_f32_16x16x32_bf16 v[4:7], v[136:139], v[226:229], v[4:7]
	v_mfma_f32_16x16x32_bf16 v[96:99], v[100:103], v[164:167], v[96:99]
	v_mfma_f32_16x16x32_bf16 v[28:31], v[140:143], v[164:167], v[28:31]
	v_mfma_f32_16x16x32_bf16 v[88:91], v[100:103], v[172:175], v[88:91]
	v_mfma_f32_16x16x32_bf16 v[20:23], v[140:143], v[172:175], v[20:23]
	v_mfma_f32_16x16x32_bf16 v[80:83], v[100:103], v[180:183], v[80:83]
	v_mfma_f32_16x16x32_bf16 v[12:15], v[140:143], v[180:183], v[12:15]
	v_mfma_f32_16x16x32_bf16 v[68:71], v[100:103], v[230:233], v[68:71]
	v_mfma_f32_16x16x32_bf16 v[4:7], v[140:143], v[230:233], v[4:7]
	s_setprio 0
	s_setprio 1
	v_mfma_f32_16x16x32_bf16 v[72:75], v[144:147], v[160:163], v[72:75]
	v_mfma_f32_16x16x32_bf16 v[92:95], v[148:151], v[164:167], v[72:75]
	v_mfma_f32_16x16x32_bf16 v[72:75], v[144:147], v[168:171], v[84:87]
	v_mfma_f32_16x16x32_bf16 v[24:27], v[152:155], v[160:163], v[24:27]
	v_mfma_f32_16x16x32_bf16 v[84:87], v[148:151], v[172:175], v[72:75]
	v_mfma_f32_16x16x32_bf16 v[16:19], v[152:155], v[168:171], v[16:19]
	v_mfma_f32_16x16x32_bf16 v[72:75], v[144:147], v[176:179], v[76:79]
	v_mfma_f32_16x16x32_bf16 v[8:11], v[152:155], v[176:179], v[8:11]
	v_mfma_f32_16x16x32_bf16 v[64:67], v[144:147], v[226:229], v[64:67]
	v_mfma_f32_16x16x32_bf16 v[0:3], v[152:155], v[226:229], v[0:3]
	v_mfma_f32_16x16x32_bf16 v[24:27], v[156:159], v[164:167], v[24:27]
	v_mfma_f32_16x16x32_bf16 v[16:19], v[156:159], v[172:175], v[16:19]
	v_mfma_f32_16x16x32_bf16 v[76:79], v[148:151], v[180:183], v[72:75]
	v_mfma_f32_16x16x32_bf16 v[8:11], v[156:159], v[180:183], v[8:11]
	v_mfma_f32_16x16x32_bf16 v[64:67], v[148:151], v[230:233], v[64:67]
	v_mfma_f32_16x16x32_bf16 v[0:3], v[156:159], v[230:233], v[0:3]
	s_barrier
	s_setprio 0
	s_add_i32 s79, s79, 2
	s_add_u32 s47, s47, 0x100
	s_addc_u32 s78, s78, 0
	s_cmp_gt_u32 s79, 13
	s_mov_b64 s[4:5], s[10:11]
	s_cbranch_scc0 .LBB0_685
; __device__ __forceinline__ float row_rstd(const u64_t* rsq, int row) { return fast_rsq(rsq_sum(rsq, row) * (1.0f / DM) + EPS); }
; #define PG8_BAR __builtin_amdgcn_s_barrier()
;     __device__ __forceinline__ void run(const f32x4 (&acc)[2][2][4][2], const Unit& u, const Unit& nxt, bool has_next, int ui, int wr, int wc, int fr_in, int fq_in) const {
;     ...
;         const int tid = (wr * 4 + wc) * 64 + fq * 16 + fr;
;         const int slot = ui & 1;
;         if (ui == 0) {
;             prm[slot * 1024 + tid] = ldp(tid, u.pn); prm[slot * 1024 + tid + 512] = ldp(tid + 512, u.pn);
;             if (tid < 256) rsd[slot * 256 + tid] = row_rstd(rsq, u.pm * BM + tid);
; template <class Epi, class Sched, bool ALIGN_EPI = false, bool SP2 = false>
; __device__ __forceinline__ void gemm_phase(PG8_LAS unsigned char* lds, const Gemm g, const Sched& S, const Epi& E, const int tid_arg) {
;     ...
;         if constexpr (ALIGN_EPI) { if (wr == 0) PG8_BAR; }
.Lkpeel_exit_3:
	s_and_b64 vcc, exec, s[26:27]
	s_cbranch_vccz .LBB0_688
	s_barrier
.LBB0_688:
	v_mov_b32_e32 v169, v204
	v_mov_b32_e32 v136, v205
	s_cmp_lg_u32 s16, 0
	v_lshlrev_b32_e32 v72, 4, v136
	v_add3_u32 v226, s66, v169, v72
	v_cmp_gt_i32_e32 vcc, s65, v226
	s_cbranch_scc0 .LBB0_693
	v_cndmask_b32_e64 v72, 0, 1, s[12:13]
	v_cmp_ne_u32_e64 s[10:11], 1, v72
	s_andn2_b64 vcc, exec, s[12:13]
	s_cbranch_vccnz .LBB0_696

; #define PG8_STAGE(bufoff, gbase, voff) do { _Pragma("unroll") for (int _i = 0; _i < 2; ++_i) \
;         __builtin_amdgcn_global_load_lds((const unsigned*)((const char*)(gbase) + (voff)[_i]), (PG8_LAS unsigned*)(lds + (bufoff) + ldsw + _i * 8192), 16, 0, 0); } while (0)
; #define PG8_LDA(dst, b, h) do { _Pragma("unroll") for (int m = 0; m < 4; ++m) _Pragma("unroll") for (int k = 0; k < 2; ++k) dst[m][k] = *(const PG8_LAS bf16x8*)(lds + PG8_SA(b, h) + aoff + m * 2048 + k * 1024); } while (0)
; #define PG8_LDB(dst, b, h) do { _Pragma("unroll") for (int n = 0; n < 2; ++n) _Pragma("unroll") for (int k = 0; k < 2; ++k) dst[n][k] = *(const PG8_LAS bf16x8*)(lds + PG8_SB(b, h) + boff + n * 2048 + k * 1024); } while (0)
; #define PG8_MMA(ai, bj, At, Bt) do { __builtin_amdgcn_s_setprio(1); _Pragma("unroll") for (int m = 0; m < 4; ++m) _Pragma("unroll") for (int n = 0; n < 2; ++n) _Pragma("unroll") for (int k = 0; k < 2; ++k) \
;         acc[ai][bj][m][n] = __builtin_amdgcn_mfma_f32_16x16x32_bf16(Bt[n][k], At[m][k], acc[ai][bj][m][n], 0, 0, 0); __builtin_amdgcn_s_setprio(0); } while (0)
; template <class Epi, class Sched, bool ALIGN_EPI = false, bool SP2 = false>
; __device__ __forceinline__ void gemm_phase(PG8_LAS unsigned char* lds, const Gemm g, const Sched& S, const Epi& E, const int tid_arg) {
;     ...
;         const bool has_next = S.next(ui + 1, nxt);
;         const char* nA = has_next ? (const char*)g.A + (size_t)nxt.pm * tstep : cA; const char* nB = has_next ? (const char*)g.Bt + (size_t)nxt.pn * tstep : cB;
;         for (int t = 0; t < nt; t += 2) {
;             const bool last = (t == nt - 2);
;             const char* a1 = cA + (size_t)(t + 1) * kstep;
;             const char* a2 = last ? nA : cA + (size_t)(t + 2) * kstep; const char* b2 = last ? nB : cB + (size_t)(t + 2) * kstep;
;             const char* a3 = a2 + kstep; const char* b3 = b2 + kstep;
;             if (last && has_next) S.a_ready(nxt);
;             if constexpr (SP2) {
;             PG8_LDB(B0, 0, 0); PG8_LDB(B1, 0, 1); PG8_SCHED; PG8_LDA(At, 0, 0); PG8_STAGE(PG8_SA(1, 1), a1 + hstep, voffA);
;             PG8_WAIT_V(8); PG8_WAIT_L(0); PG8_BAR; PG8_MMA(0, 0, At, B0); PG8_MMA(0, 1, At, B1); PG8_BAR; PG8_SCHED;
;             PG8_LDA(At, 0, 1); PG8_STAGE(PG8_SB(0, 0), b2, voffB); PG8_STAGE(PG8_SB(0, 1), b2 + hstep, voffB); PG8_STAGE(PG8_SA(0, 0), a2, voffA);
.LBB0_870:
	s_add_u32 s55, s22, 0x100
	v_mov_b32_e32 v0, 0
	s_addc_u32 s56, s23, 0
	s_mov_b32 s57, -2
	ds_read_b128 v[144:147], v151
	ds_read_b128 v[168:171], v152
	ds_read_b128 v[172:175], v153
	ds_read_b128 v[176:179], v154
	ds_read_b128 v[180:183], v155
	ds_read_b128 v[184:187], v156
	ds_read_b128 v[188:191], v157
	ds_read_b128 v[192:195], v158
	s_add_u32 s22, s4, 0x100
	s_addc_u32 s23, s5, 0
	s_cmp_eq_u32 s57, 40
	s_cselect_b32 s25, s13, s23
	s_cselect_b32 s24, s12, s22
	s_cselect_b32 s1, s21, s56
	s_cselect_b32 s0, s20, s55
	s_mov_b32 m0, s48
	v_lshl_add_u64 v[228:229], s[4:5], 0, v[138:139]
	ds_read_b128 v[196:199], v150
	ds_read_b128 v[200:203], v150 offset:1024
	ds_read_b128 v[204:207], v150 offset:2048
	ds_read_b128 v[208:211], v150 offset:3072
	ds_read_b128 v[212:215], v150 offset:4096
	ds_read_b128 v[216:219], v150 offset:5120
	ds_read_b128 v[220:223], v150 offset:6144
	ds_read_b128 v[224:227], v150 offset:7168
	global_load_lds_dwordx4 v[228:229], off
	v_lshl_add_u64 v[228:229], s[4:5], 0, v[136:137]
	s_mov_b32 m0, s49
	s_nop 0
	global_load_lds_dwordx4 v[228:229], off
	s_waitcnt vmcnt(8)
	s_waitcnt lgkmcnt(0)
	s_setprio 1
	s_barrier
	v_mfma_f32_16x16x32_bf16 v[124:127], v[144:147], v[196:199], 0
	v_mfma_f32_16x16x32_bf16 v[120:123], v[172:175], v[196:199], 0
	v_mfma_f32_16x16x32_bf16 v[108:111], v[144:147], v[204:207], 0
	v_mfma_f32_16x16x32_bf16 v[104:107], v[172:175], v[204:207], 0
	v_mfma_f32_16x16x32_bf16 v[92:95], v[144:147], v[212:215], 0
	v_mfma_f32_16x16x32_bf16 v[88:91], v[172:175], v[212:215], 0
	v_mfma_f32_16x16x32_bf16 v[76:79], v[144:147], v[220:223], 0
	v_mfma_f32_16x16x32_bf16 v[72:75], v[172:175], v[220:223], 0
	v_mfma_f32_16x16x32_bf16 v[124:127], v[168:171], v[200:203], v[124:127]
	v_mfma_f32_16x16x32_bf16 v[120:123], v[176:179], v[200:203], v[120:123]
	v_mfma_f32_16x16x32_bf16 v[108:111], v[168:171], v[208:211], v[108:111]
	v_mfma_f32_16x16x32_bf16 v[104:107], v[176:179], v[208:211], v[104:107]
	v_mfma_f32_16x16x32_bf16 v[92:95], v[168:171], v[216:219], v[92:95]
	v_mfma_f32_16x16x32_bf16 v[88:91], v[176:179], v[216:219], v[88:91]
	v_mfma_f32_16x16x32_bf16 v[76:79], v[168:171], v[224:227], v[76:79]
	v_mfma_f32_16x16x32_bf16 v[72:75], v[176:179], v[224:227], v[72:75]
	s_setprio 0
	s_setprio 1
	v_mfma_f32_16x16x32_bf16 v[116:119], v[180:183], v[196:199], 0
	v_mfma_f32_16x16x32_bf16 v[112:115], v[188:191], v[196:199], 0
	v_mfma_f32_16x16x32_bf16 v[100:103], v[180:183], v[204:207], 0
	v_mfma_f32_16x16x32_bf16 v[96:99], v[188:191], v[204:207], 0
	v_mfma_f32_16x16x32_bf16 v[84:87], v[180:183], v[212:215], 0
	v_mfma_f32_16x16x32_bf16 v[80:83], v[188:191], v[212:215], 0
	v_mfma_f32_16x16x32_bf16 v[68:71], v[180:183], v[220:223], 0
	v_mfma_f32_16x16x32_bf16 v[64:67], v[188:191], v[220:223], 0
	v_mfma_f32_16x16x32_bf16 v[116:119], v[184:187], v[200:203], v[116:119]
	v_mfma_f32_16x16x32_bf16 v[112:115], v[192:195], v[200:203], v[112:115]
	v_mfma_f32_16x16x32_bf16 v[100:103], v[184:187], v[208:211], v[100:103]
	v_mfma_f32_16x16x32_bf16 v[96:99], v[192:195], v[208:211], v[96:99]
	v_mfma_f32_16x16x32_bf16 v[84:87], v[184:187], v[216:219], v[84:87]
	v_mfma_f32_16x16x32_bf16 v[80:83], v[192:195], v[216:219], v[80:83]
	v_mfma_f32_16x16x32_bf16 v[68:71], v[184:187], v[224:227], v[68:71]
	v_mfma_f32_16x16x32_bf16 v[64:67], v[192:195], v[224:227], v[64:67]
	s_barrier
	s_setprio 0
	s_mov_b32 m0, s29
	v_lshl_add_u64 v[228:229], s[0:1], 0, v[130:131]
	s_add_u32 s4, s0, 0xb0000
	ds_read_b128 v[196:199], v150 offset:16384
	ds_read_b128 v[200:203], v150 offset:17408
	ds_read_b128 v[204:207], v150 offset:18432
	ds_read_b128 v[208:211], v150 offset:19456
	ds_read_b128 v[212:215], v150 offset:20480
	ds_read_b128 v[216:219], v150 offset:21504
	ds_read_b128 v[220:223], v150 offset:22528
	ds_read_b128 v[224:227], v150 offset:23552
	global_load_lds_dwordx4 v[228:229], off
	v_lshl_add_u64 v[230:231], s[0:1], 0, v[134:135]
	s_mov_b32 m0, s30
	s_addc_u32 s5, s1, 0
	global_load_lds_dwordx4 v[230:231], off
	v_lshl_add_u64 v[232:233], s[4:5], 0, v[130:131]
	s_mov_b32 m0, s31
	v_lshl_add_u64 v[234:235], s[24:25], 0, v[132:133]
	global_load_lds_dwordx4 v[232:233], off
	v_lshl_add_u64 v[232:233], s[4:5], 0, v[134:135]
	s_mov_b32 m0, s33
	s_nop 0
	global_load_lds_dwordx4 v[232:233], off
	v_lshl_add_u64 v[232:233], s[24:25], 0, v[128:129]
	s_mov_b32 m0, s28
	s_nop 0
	global_load_lds_dwordx4 v[232:233], off
	s_mov_b32 m0, s34
	s_nop 0
	global_load_lds_dwordx4 v[234:235], off
	s_waitcnt vmcnt(8)
	s_waitcnt lgkmcnt(0)
	s_setprio 1
	s_barrier
	v_mfma_f32_16x16x32_bf16 v[60:63], v[144:147], v[196:199], 0
	v_mfma_f32_16x16x32_bf16 v[56:59], v[172:175], v[196:199], 0
	v_mfma_f32_16x16x32_bf16 v[44:47], v[144:147], v[204:207], 0
	v_mfma_f32_16x16x32_bf16 v[40:43], v[172:175], v[204:207], 0
	v_mfma_f32_16x16x32_bf16 v[28:31], v[144:147], v[212:215], 0
	v_mfma_f32_16x16x32_bf16 v[24:27], v[172:175], v[212:215], 0
	v_mfma_f32_16x16x32_bf16 v[12:15], v[144:147], v[220:223], 0
	v_mfma_f32_16x16x32_bf16 v[8:11], v[172:175], v[220:223], 0
	v_mfma_f32_16x16x32_bf16 v[60:63], v[168:171], v[200:203], v[60:63]
	v_mfma_f32_16x16x32_bf16 v[56:59], v[176:179], v[200:203], v[56:59]
	v_mfma_f32_16x16x32_bf16 v[44:47], v[168:171], v[208:211], v[44:47]
	v_mfma_f32_16x16x32_bf16 v[40:43], v[176:179], v[208:211], v[40:43]
	v_mfma_f32_16x16x32_bf16 v[28:31], v[168:171], v[216:219], v[28:31]
	v_mfma_f32_16x16x32_bf16 v[24:27], v[176:179], v[216:219], v[24:27]
	v_mfma_f32_16x16x32_bf16 v[12:15], v[168:171], v[224:227], v[12:15]
	v_mfma_f32_16x16x32_bf16 v[8:11], v[176:179], v[224:227], v[8:11]
	s_setprio 0
	s_setprio 1
	v_mfma_f32_16x16x32_bf16 v[52:55], v[180:183], v[196:199], 0
	v_mfma_f32_16x16x32_bf16 v[48:51], v[188:191], v[196:199], 0
	v_mfma_f32_16x16x32_bf16 v[36:39], v[180:183], v[204:207], 0
	v_mfma_f32_16x16x32_bf16 v[32:35], v[188:191], v[204:207], 0
	v_mfma_f32_16x16x32_bf16 v[20:23], v[180:183], v[212:215], 0
	v_mfma_f32_16x16x32_bf16 v[16:19], v[188:191], v[212:215], 0
	v_mfma_f32_16x16x32_bf16 v[4:7], v[180:183], v[220:223], 0
	v_mfma_f32_16x16x32_bf16 v[0:3], v[188:191], v[220:223], 0
	v_mfma_f32_16x16x32_bf16 v[52:55], v[184:187], v[200:203], v[52:55]
	v_mfma_f32_16x16x32_bf16 v[48:51], v[192:195], v[200:203], v[48:51]
	v_mfma_f32_16x16x32_bf16 v[36:39], v[184:187], v[208:211], v[36:39]
	v_mfma_f32_16x16x32_bf16 v[32:35], v[192:195], v[208:211], v[32:35]
	v_mfma_f32_16x16x32_bf16 v[20:23], v[184:187], v[216:219], v[20:23]
	v_mfma_f32_16x16x32_bf16 v[16:19], v[192:195], v[216:219], v[16:19]
	v_mfma_f32_16x16x32_bf16 v[4:7], v[184:187], v[224:227], v[4:7]
	v_mfma_f32_16x16x32_bf16 v[0:3], v[192:195], v[224:227], v[0:3]
	s_barrier
; #define PG8_STAGE(bufoff, gbase, voff) do { _Pragma("unroll") for (int _i = 0; _i < 2; ++_i) \
;         __builtin_amdgcn_global_load_lds((const unsigned*)((const char*)(gbase) + (voff)[_i]), (PG8_LAS unsigned*)(lds + (bufoff) + ldsw + _i * 8192), 16, 0, 0); } while (0)
; #define PG8_LDA(dst, b, h) do { _Pragma("unroll") for (int m = 0; m < 4; ++m) _Pragma("unroll") for (int k = 0; k < 2; ++k) dst[m][k] = *(const PG8_LAS bf16x8*)(lds + PG8_SA(b, h) + aoff + m * 2048 + k * 1024); } while (0)
; #define PG8_LDB(dst, b, h) do { _Pragma("unroll") for (int n = 0; n < 2; ++n) _Pragma("unroll") for (int k = 0; k < 2; ++k) dst[n][k] = *(const PG8_LAS bf16x8*)(lds + PG8_SB(b, h) + boff + n * 2048 + k * 1024); } while (0)
; #define PG8_MMA(ai, bj, At, Bt) do { __builtin_amdgcn_s_setprio(1); _Pragma("unroll") for (int m = 0; m < 4; ++m) _Pragma("unroll") for (int n = 0; n < 2; ++n) _Pragma("unroll") for (int k = 0; k < 2; ++k) \
;         acc[ai][bj][m][n] = __builtin_amdgcn_mfma_f32_16x16x32_bf16(Bt[n][k], At[m][k], acc[ai][bj][m][n], 0, 0, 0); __builtin_amdgcn_s_setprio(0); } while (0)
; #define PG8_WAIT_V(n) asm volatile("s_waitcnt vmcnt(" #n ")" ::: "memory")
; #define PG8_WAIT_L(n) asm volatile("s_waitcnt lgkmcnt(" #n ")" ::: "memory")
; #define PG8_BAR __builtin_amdgcn_s_barrier()
; #define PG8_SCHED __builtin_amdgcn_sched_barrier(0)
; template <class Epi, class Sched, bool ALIGN_EPI = false, bool SP2 = false>
; __device__ __forceinline__ void gemm_phase(PG8_LAS unsigned char* lds, const Gemm g, const Sched& S, const Epi& E, const int tid_arg) {
;     ...
;         for (int t = 0; t < nt; t += 2) {
;     ...
;             PG8_LDB(B0, 1, 0); PG8_LDB(B1, 1, 1); PG8_SCHED; PG8_LDA(At, 1, 0); PG8_STAGE(PG8_SA(0, 1), a2 + hstep, voffA);
;             PG8_WAIT_V(8); PG8_WAIT_L(0); PG8_BAR; PG8_MMA(0, 0, At, B0); PG8_MMA(0, 1, At, B1); PG8_BAR; PG8_SCHED;
;             PG8_LDA(At, 1, 1); PG8_STAGE(PG8_SB(1, 0), b3, voffB); PG8_STAGE(PG8_SB(1, 1), b3 + hstep, voffB); PG8_STAGE(PG8_SA(1, 0), a3, voffA);
;             PG8_WAIT_V(8); PG8_WAIT_L(0); PG8_BAR; PG8_MMA(1, 0, At, B0); PG8_MMA(1, 1, At, B1); PG8_BAR; PG8_SCHED;
	s_setprio 0
	ds_read_b128 v[144:147], v159
	ds_read_b128 v[168:171], v160
	ds_read_b128 v[172:175], v161
	ds_read_b128 v[176:179], v162
	ds_read_b128 v[180:183], v163
	ds_read_b128 v[184:187], v164
	ds_read_b128 v[188:191], v165
	ds_read_b128 v[192:195], v166
	s_add_u32 s4, s24, 0xb0000
	s_addc_u32 s5, s25, 0
	s_mov_b32 m0, s35
	v_lshl_add_u64 v[236:237], s[4:5], 0, v[128:129]
	ds_read_b128 v[196:199], v150 offset:32768
	ds_read_b128 v[200:203], v150 offset:33792
	ds_read_b128 v[204:207], v150 offset:34816
	ds_read_b128 v[208:211], v150 offset:35840
	ds_read_b128 v[212:215], v150 offset:36864
	ds_read_b128 v[216:219], v150 offset:37888
	ds_read_b128 v[220:223], v150 offset:38912
	ds_read_b128 v[224:227], v150 offset:39936
	global_load_lds_dwordx4 v[236:237], off
	v_lshl_add_u64 v[236:237], s[4:5], 0, v[132:133]
	s_mov_b32 m0, s36
	s_nop 0
	global_load_lds_dwordx4 v[236:237], off
	s_waitcnt vmcnt(8)
	s_waitcnt lgkmcnt(0)
	s_setprio 1
	s_barrier
	v_mfma_f32_16x16x32_bf16 v[124:127], v[144:147], v[196:199], v[124:127]
	v_mfma_f32_16x16x32_bf16 v[120:123], v[172:175], v[196:199], v[120:123]
	v_mfma_f32_16x16x32_bf16 v[108:111], v[144:147], v[204:207], v[108:111]
	v_mfma_f32_16x16x32_bf16 v[104:107], v[172:175], v[204:207], v[104:107]
	v_mfma_f32_16x16x32_bf16 v[92:95], v[144:147], v[212:215], v[92:95]
	v_mfma_f32_16x16x32_bf16 v[88:91], v[172:175], v[212:215], v[88:91]
	v_mfma_f32_16x16x32_bf16 v[76:79], v[144:147], v[220:223], v[76:79]
	v_mfma_f32_16x16x32_bf16 v[72:75], v[172:175], v[220:223], v[72:75]
	v_mfma_f32_16x16x32_bf16 v[124:127], v[168:171], v[200:203], v[124:127]
	v_mfma_f32_16x16x32_bf16 v[120:123], v[176:179], v[200:203], v[120:123]
	v_mfma_f32_16x16x32_bf16 v[108:111], v[168:171], v[208:211], v[108:111]
	v_mfma_f32_16x16x32_bf16 v[104:107], v[176:179], v[208:211], v[104:107]
	v_mfma_f32_16x16x32_bf16 v[92:95], v[168:171], v[216:219], v[92:95]
	v_mfma_f32_16x16x32_bf16 v[88:91], v[176:179], v[216:219], v[88:91]
	v_mfma_f32_16x16x32_bf16 v[76:79], v[168:171], v[224:227], v[76:79]
	v_mfma_f32_16x16x32_bf16 v[72:75], v[176:179], v[224:227], v[72:75]
	s_setprio 0
	s_setprio 1
	v_mfma_f32_16x16x32_bf16 v[116:119], v[180:183], v[196:199], v[116:119]
	v_mfma_f32_16x16x32_bf16 v[112:115], v[188:191], v[196:199], v[112:115]
	v_mfma_f32_16x16x32_bf16 v[100:103], v[180:183], v[204:207], v[100:103]
	v_mfma_f32_16x16x32_bf16 v[96:99], v[188:191], v[204:207], v[96:99]
	v_mfma_f32_16x16x32_bf16 v[84:87], v[180:183], v[212:215], v[84:87]
	v_mfma_f32_16x16x32_bf16 v[80:83], v[188:191], v[212:215], v[80:83]
	v_mfma_f32_16x16x32_bf16 v[68:71], v[180:183], v[220:223], v[68:71]
	v_mfma_f32_16x16x32_bf16 v[64:67], v[188:191], v[220:223], v[64:67]
	v_mfma_f32_16x16x32_bf16 v[116:119], v[184:187], v[200:203], v[116:119]
	v_mfma_f32_16x16x32_bf16 v[112:115], v[192:195], v[200:203], v[112:115]
	v_mfma_f32_16x16x32_bf16 v[100:103], v[184:187], v[208:211], v[100:103]
	v_mfma_f32_16x16x32_bf16 v[96:99], v[192:195], v[208:211], v[96:99]
	v_mfma_f32_16x16x32_bf16 v[84:87], v[184:187], v[216:219], v[84:87]
	v_mfma_f32_16x16x32_bf16 v[80:83], v[192:195], v[216:219], v[80:83]
	v_mfma_f32_16x16x32_bf16 v[68:71], v[184:187], v[224:227], v[68:71]
	v_mfma_f32_16x16x32_bf16 v[64:67], v[192:195], v[224:227], v[64:67]
	s_barrier
	s_setprio 0
	s_mov_b32 m0, s40
	v_lshl_add_u64 v[228:229], v[228:229], 0, s[16:17]
	s_add_u32 s0, s0, 0xb0080
	ds_read_b128 v[196:199], v150 offset:49152
	ds_read_b128 v[200:203], v150 offset:50176
	ds_read_b128 v[204:207], v150 offset:51200
	ds_read_b128 v[208:211], v150 offset:52224
	ds_read_b128 v[212:215], v150 offset:53248
	ds_read_b128 v[216:219], v150 offset:54272
	ds_read_b128 v[220:223], v150 offset:55296
	ds_read_b128 v[224:227], v150 offset:56320
	global_load_lds_dwordx4 v[228:229], off
	v_lshl_add_u64 v[228:229], v[230:231], 0, s[16:17]
	s_mov_b32 m0, s41
	s_addc_u32 s1, s1, 0
	global_load_lds_dwordx4 v[228:229], off
	v_lshl_add_u64 v[228:229], s[0:1], 0, v[130:131]
	s_mov_b32 m0, s44
	s_nop 0
	global_load_lds_dwordx4 v[228:229], off
	v_lshl_add_u64 v[228:229], s[0:1], 0, v[134:135]
	s_mov_b32 m0, s45
	s_nop 0
	global_load_lds_dwordx4 v[228:229], off
	v_lshl_add_u64 v[228:229], v[232:233], 0, s[16:17]
	s_mov_b32 m0, s42
	s_nop 0
	global_load_lds_dwordx4 v[228:229], off
	v_lshl_add_u64 v[228:229], v[234:235], 0, s[16:17]
	s_mov_b32 m0, s43
	s_nop 0
	global_load_lds_dwordx4 v[228:229], off
	s_waitcnt vmcnt(8)
	s_waitcnt lgkmcnt(0)
	s_setprio 1
	s_barrier
	v_mfma_f32_16x16x32_bf16 v[60:63], v[144:147], v[196:199], v[60:63]
	v_mfma_f32_16x16x32_bf16 v[56:59], v[172:175], v[196:199], v[56:59]
	v_mfma_f32_16x16x32_bf16 v[44:47], v[144:147], v[204:207], v[44:47]
	v_mfma_f32_16x16x32_bf16 v[40:43], v[172:175], v[204:207], v[40:43]
	v_mfma_f32_16x16x32_bf16 v[28:31], v[144:147], v[212:215], v[28:31]
	v_mfma_f32_16x16x32_bf16 v[24:27], v[172:175], v[212:215], v[24:27]
	v_mfma_f32_16x16x32_bf16 v[12:15], v[144:147], v[220:223], v[12:15]
	v_mfma_f32_16x16x32_bf16 v[8:11], v[172:175], v[220:223], v[8:11]
	v_mfma_f32_16x16x32_bf16 v[60:63], v[168:171], v[200:203], v[60:63]
	v_mfma_f32_16x16x32_bf16 v[56:59], v[176:179], v[200:203], v[56:59]
	v_mfma_f32_16x16x32_bf16 v[44:47], v[168:171], v[208:211], v[44:47]
	v_mfma_f32_16x16x32_bf16 v[40:43], v[176:179], v[208:211], v[40:43]
	v_mfma_f32_16x16x32_bf16 v[28:31], v[168:171], v[216:219], v[28:31]
	v_mfma_f32_16x16x32_bf16 v[24:27], v[176:179], v[216:219], v[24:27]
	v_mfma_f32_16x16x32_bf16 v[12:15], v[168:171], v[224:227], v[12:15]
	v_mfma_f32_16x16x32_bf16 v[8:11], v[176:179], v[224:227], v[8:11]
	s_setprio 0
	s_setprio 1
	v_mfma_f32_16x16x32_bf16 v[52:55], v[180:183], v[196:199], v[52:55]
	v_mfma_f32_16x16x32_bf16 v[48:51], v[188:191], v[196:199], v[48:51]
	v_mfma_f32_16x16x32_bf16 v[36:39], v[180:183], v[204:207], v[36:39]
	v_mfma_f32_16x16x32_bf16 v[32:35], v[188:191], v[204:207], v[32:35]
	v_mfma_f32_16x16x32_bf16 v[20:23], v[180:183], v[212:215], v[20:23]
	v_mfma_f32_16x16x32_bf16 v[16:19], v[188:191], v[212:215], v[16:19]
	v_mfma_f32_16x16x32_bf16 v[4:7], v[180:183], v[220:223], v[4:7]
	v_mfma_f32_16x16x32_bf16 v[0:3], v[188:191], v[220:223], v[0:3]
	v_mfma_f32_16x16x32_bf16 v[52:55], v[184:187], v[200:203], v[52:55]
	v_mfma_f32_16x16x32_bf16 v[48:51], v[192:195], v[200:203], v[48:51]
	v_mfma_f32_16x16x32_bf16 v[36:39], v[184:187], v[208:211], v[36:39]
	v_mfma_f32_16x16x32_bf16 v[32:35], v[192:195], v[208:211], v[32:35]
	v_mfma_f32_16x16x32_bf16 v[20:23], v[184:187], v[216:219], v[20:23]
	v_mfma_f32_16x16x32_bf16 v[16:19], v[192:195], v[216:219], v[16:19]
	v_mfma_f32_16x16x32_bf16 v[4:7], v[184:187], v[224:227], v[4:7]
	v_mfma_f32_16x16x32_bf16 v[0:3], v[192:195], v[224:227], v[0:3]
	s_barrier
	s_setprio 0
	s_add_i32 s57, s57, 2
	s_add_u32 s55, s55, 0x100
	s_addc_u32 s56, s56, 0
	s_cmp_gt_u32 s57, 41
	s_mov_b64 s[4:5], s[22:23]
	s_cbranch_scc0 .LBB0_871
	s_branch .Lkpeel_exit_4

; #define PG8_BAR __builtin_amdgcn_s_barrier()
; template <class Epi, class Sched, bool ALIGN_EPI = false, bool SP2 = false>
; __device__ __forceinline__ void gemm_phase(PG8_LAS unsigned char* lds, const Gemm g, const Sched& S, const Epi& E, const int tid_arg) {
;     ...
;         if constexpr (ALIGN_EPI) { if (wr == 0) PG8_BAR; }
.Lkpeel_exit_4:
	s_and_b64 vcc, exec, s[18:19]
	s_cbranch_vccz .LBB0_874
	s_barrier

; #define PG8_STAGE(bufoff, gbase, voff) do { _Pragma("unroll") for (int _i = 0; _i < 2; ++_i) \
;         __builtin_amdgcn_global_load_lds((const unsigned*)((const char*)(gbase) + (voff)[_i]), (PG8_LAS unsigned*)(lds + (bufoff) + ldsw + _i * 8192), 16, 0, 0); } while (0)
; #define PG8_LDA(dst, b, h) do { _Pragma("unroll") for (int m = 0; m < 4; ++m) _Pragma("unroll") for (int k = 0; k < 2; ++k) dst[m][k] = *(const PG8_LAS bf16x8*)(lds + PG8_SA(b, h) + aoff + m * 2048 + k * 1024); } while (0)
; #define PG8_LDB(dst, b, h) do { _Pragma("unroll") for (int n = 0; n < 2; ++n) _Pragma("unroll") for (int k = 0; k < 2; ++k) dst[n][k] = *(const PG8_LAS bf16x8*)(lds + PG8_SB(b, h) + boff + n * 2048 + k * 1024); } while (0)
; #define PG8_MMA(ai, bj, At, Bt) do { __builtin_amdgcn_s_setprio(1); _Pragma("unroll") for (int m = 0; m < 4; ++m) _Pragma("unroll") for (int n = 0; n < 2; ++n) _Pragma("unroll") for (int k = 0; k < 2; ++k) \
;         acc[ai][bj][m][n] = __builtin_amdgcn_mfma_f32_16x16x32_bf16(Bt[n][k], At[m][k], acc[ai][bj][m][n], 0, 0, 0); __builtin_amdgcn_s_setprio(0); } while (0)
; template <class Epi, class Sched, bool ALIGN_EPI = false, bool SP2 = false>
; __device__ __forceinline__ void gemm_phase(PG8_LAS unsigned char* lds, const Gemm g, const Sched& S, const Epi& E, const int tid_arg) {
;     ...
;         const bool has_next = S.next(ui + 1, nxt);
;         const char* nA = has_next ? (const char*)g.A + (size_t)nxt.pm * tstep : cA; const char* nB = has_next ? (const char*)g.Bt + (size_t)nxt.pn * tstep : cB;
;         for (int t = 0; t < nt; t += 2) {
;             const bool last = (t == nt - 2);
;             const char* a1 = cA + (size_t)(t + 1) * kstep;
;             const char* a2 = last ? nA : cA + (size_t)(t + 2) * kstep; const char* b2 = last ? nB : cB + (size_t)(t + 2) * kstep;
;             const char* a3 = a2 + kstep; const char* b3 = b2 + kstep;
;             if (last && has_next) S.a_ready(nxt);
;             if constexpr (SP2) {
;             PG8_LDB(B0, 0, 0); PG8_LDB(B1, 0, 1); PG8_SCHED; PG8_LDA(At, 0, 0); PG8_STAGE(PG8_SA(1, 1), a1 + hstep, voffA);
;             PG8_WAIT_V(8); PG8_WAIT_L(0); PG8_BAR; PG8_MMA(0, 0, At, B0); PG8_MMA(0, 1, At, B1); PG8_BAR; PG8_SCHED;
;             PG8_LDA(At, 0, 1); PG8_STAGE(PG8_SB(0, 0), b2, voffB); PG8_STAGE(PG8_SB(0, 1), b2 + hstep, voffB); PG8_STAGE(PG8_SA(0, 0), a2, voffA);
.LBB0_964:
	s_ashr_i32 s35, s34, 31
	s_lshl_b64 s[0:1], s[34:35], 19
	s_add_u32 s36, s3, s0
	s_addc_u32 s37, s33, s1
	s_and_b64 s[0:1], s[10:11], exec
	s_cselect_b32 s35, s37, s43
	s_cselect_b32 s68, s36, s42
	s_ashr_i32 s31, s30, 31
	s_lshl_b64 s[0:1], s[30:31], 19
	s_add_u32 s38, s44, s0
	s_addc_u32 s39, s45, s1
	s_and_b64 s[0:1], s[10:11], exec
	s_cselect_b32 s31, s39, s41
	s_cselect_b32 s69, s38, s40
	s_add_u32 s70, s40, 0x100
	s_addc_u32 s71, s41, 0
	s_add_u32 s40, s42, 0x40080
	v_mov_b32_e32 v0, 0
	s_addc_u32 s41, s43, 0
	s_mov_b32 s72, -2
	ds_read_b128 v[170:173], v151
	ds_read_b128 v[174:177], v153
	ds_read_b128 v[178:181], v155
	ds_read_b128 v[182:185], v156
	ds_read_b128 v[186:189], v157
	ds_read_b128 v[190:193], v158
	ds_read_b128 v[194:197], v159
	ds_read_b128 v[198:201], v160
	s_add_u32 s0, s40, 0xfffc0080
	s_addc_u32 s1, s41, -1
	s_cmp_eq_u32 s72, 12
	s_cselect_b32 s43, s35, s1
	s_cselect_b32 s42, s68, s0
	s_cselect_b32 s1, s31, s71
	s_cselect_b32 s0, s69, s70
	s_mov_b32 m0, s60
	v_lshl_add_u64 v[234:235], s[40:41], 0, v[138:139]
	ds_read_b128 v[202:205], v149
	ds_read_b128 v[206:209], v149 offset:1024
	ds_read_b128 v[210:213], v149 offset:2048
	ds_read_b128 v[214:217], v149 offset:3072
	ds_read_b128 v[218:221], v149 offset:4096
	ds_read_b128 v[222:225], v149 offset:5120
	ds_read_b128 v[226:229], v149 offset:6144
	ds_read_b128 v[230:233], v149 offset:7168
	global_load_lds_dwordx4 v[234:235], off
	v_lshl_add_u64 v[234:235], s[40:41], 0, v[136:137]
	s_mov_b32 m0, s61
	s_nop 0
	global_load_lds_dwordx4 v[234:235], off
	s_waitcnt vmcnt(8)
	s_waitcnt lgkmcnt(0)
	s_setprio 1
	s_barrier
	v_mfma_f32_16x16x32_bf16 v[124:127], v[170:173], v[202:205], 0
	v_mfma_f32_16x16x32_bf16 v[120:123], v[178:181], v[202:205], 0
	v_mfma_f32_16x16x32_bf16 v[108:111], v[170:173], v[210:213], 0
	v_mfma_f32_16x16x32_bf16 v[104:107], v[178:181], v[210:213], 0
	v_mfma_f32_16x16x32_bf16 v[92:95], v[170:173], v[218:221], 0
	v_mfma_f32_16x16x32_bf16 v[88:91], v[178:181], v[218:221], 0
	v_mfma_f32_16x16x32_bf16 v[76:79], v[170:173], v[226:229], 0
	v_mfma_f32_16x16x32_bf16 v[72:75], v[178:181], v[226:229], 0
	v_mfma_f32_16x16x32_bf16 v[124:127], v[174:177], v[206:209], v[124:127]
	v_mfma_f32_16x16x32_bf16 v[120:123], v[182:185], v[206:209], v[120:123]
	v_mfma_f32_16x16x32_bf16 v[108:111], v[174:177], v[214:217], v[108:111]
	v_mfma_f32_16x16x32_bf16 v[104:107], v[182:185], v[214:217], v[104:107]
	v_mfma_f32_16x16x32_bf16 v[92:95], v[174:177], v[222:225], v[92:95]
	v_mfma_f32_16x16x32_bf16 v[88:91], v[182:185], v[222:225], v[88:91]
	v_mfma_f32_16x16x32_bf16 v[76:79], v[174:177], v[230:233], v[76:79]
	v_mfma_f32_16x16x32_bf16 v[72:75], v[182:185], v[230:233], v[72:75]
	s_setprio 0
	s_setprio 1
	v_mfma_f32_16x16x32_bf16 v[116:119], v[186:189], v[202:205], 0
	v_mfma_f32_16x16x32_bf16 v[112:115], v[194:197], v[202:205], 0
	v_mfma_f32_16x16x32_bf16 v[100:103], v[186:189], v[210:213], 0
	v_mfma_f32_16x16x32_bf16 v[96:99], v[194:197], v[210:213], 0
	v_mfma_f32_16x16x32_bf16 v[84:87], v[186:189], v[218:221], 0
	v_mfma_f32_16x16x32_bf16 v[80:83], v[194:197], v[218:221], 0
	v_mfma_f32_16x16x32_bf16 v[68:71], v[186:189], v[226:229], 0
	v_mfma_f32_16x16x32_bf16 v[64:67], v[194:197], v[226:229], 0
	v_mfma_f32_16x16x32_bf16 v[116:119], v[190:193], v[206:209], v[116:119]
	v_mfma_f32_16x16x32_bf16 v[112:115], v[198:201], v[206:209], v[112:115]
	v_mfma_f32_16x16x32_bf16 v[100:103], v[190:193], v[214:217], v[100:103]
	v_mfma_f32_16x16x32_bf16 v[96:99], v[198:201], v[214:217], v[96:99]
	v_mfma_f32_16x16x32_bf16 v[84:87], v[190:193], v[222:225], v[84:87]
	v_mfma_f32_16x16x32_bf16 v[80:83], v[198:201], v[222:225], v[80:83]
	v_mfma_f32_16x16x32_bf16 v[68:71], v[190:193], v[230:233], v[68:71]
	v_mfma_f32_16x16x32_bf16 v[64:67], v[198:201], v[230:233], v[64:67]
	s_barrier
	s_setprio 0
	s_mov_b32 m0, s5
	v_lshl_add_u64 v[234:235], s[0:1], 0, v[130:131]
	s_add_u32 s74, s0, 0x40000
	ds_read_b128 v[202:205], v149 offset:16384
	ds_read_b128 v[206:209], v149 offset:17408
	ds_read_b128 v[210:213], v149 offset:18432
	ds_read_b128 v[214:217], v149 offset:19456
	ds_read_b128 v[218:221], v149 offset:20480
	ds_read_b128 v[222:225], v149 offset:21504
	ds_read_b128 v[226:229], v149 offset:22528
	ds_read_b128 v[230:233], v149 offset:23552
	global_load_lds_dwordx4 v[234:235], off
	v_lshl_add_u64 v[236:237], s[0:1], 0, v[134:135]
	s_mov_b32 m0, s47
	s_addc_u32 s75, s1, 0
	global_load_lds_dwordx4 v[236:237], off
	v_lshl_add_u64 v[238:239], s[74:75], 0, v[130:131]
	s_mov_b32 m0, s48
	v_lshl_add_u64 v[240:241], s[42:43], 0, v[132:133]
	global_load_lds_dwordx4 v[238:239], off
	v_lshl_add_u64 v[238:239], s[74:75], 0, v[134:135]
	s_mov_b32 m0, s49
	s_nop 0
	global_load_lds_dwordx4 v[238:239], off
	v_lshl_add_u64 v[238:239], s[42:43], 0, v[128:129]
	s_mov_b32 m0, s46
	s_nop 0
	global_load_lds_dwordx4 v[238:239], off
	s_mov_b32 m0, s50
	s_nop 0
	global_load_lds_dwordx4 v[240:241], off
	s_waitcnt vmcnt(8)
	s_waitcnt lgkmcnt(0)
	s_setprio 1
	s_barrier
; #define PG8_STAGE(bufoff, gbase, voff) do { _Pragma("unroll") for (int _i = 0; _i < 2; ++_i) \
;         __builtin_amdgcn_global_load_lds((const unsigned*)((const char*)(gbase) + (voff)[_i]), (PG8_LAS unsigned*)(lds + (bufoff) + ldsw + _i * 8192), 16, 0, 0); } while (0)
; #define PG8_LDA(dst, b, h) do { _Pragma("unroll") for (int m = 0; m < 4; ++m) _Pragma("unroll") for (int k = 0; k < 2; ++k) dst[m][k] = *(const PG8_LAS bf16x8*)(lds + PG8_SA(b, h) + aoff + m * 2048 + k * 1024); } while (0)
; #define PG8_LDB(dst, b, h) do { _Pragma("unroll") for (int n = 0; n < 2; ++n) _Pragma("unroll") for (int k = 0; k < 2; ++k) dst[n][k] = *(const PG8_LAS bf16x8*)(lds + PG8_SB(b, h) + boff + n * 2048 + k * 1024); } while (0)
; #define PG8_MMA(ai, bj, At, Bt) do { __builtin_amdgcn_s_setprio(1); _Pragma("unroll") for (int m = 0; m < 4; ++m) _Pragma("unroll") for (int n = 0; n < 2; ++n) _Pragma("unroll") for (int k = 0; k < 2; ++k) \
;         acc[ai][bj][m][n] = __builtin_amdgcn_mfma_f32_16x16x32_bf16(Bt[n][k], At[m][k], acc[ai][bj][m][n], 0, 0, 0); __builtin_amdgcn_s_setprio(0); } while (0)
; #define PG8_WAIT_V(n) asm volatile("s_waitcnt vmcnt(" #n ")" ::: "memory")
; #define PG8_WAIT_L(n) asm volatile("s_waitcnt lgkmcnt(" #n ")" ::: "memory")
; #define PG8_BAR __builtin_amdgcn_s_barrier()
; #define PG8_SCHED __builtin_amdgcn_sched_barrier(0)
; template <class Epi, class Sched, bool ALIGN_EPI = false, bool SP2 = false>
; __device__ __forceinline__ void gemm_phase(PG8_LAS unsigned char* lds, const Gemm g, const Sched& S, const Epi& E, const int tid_arg) {
;     ...
;             PG8_WAIT_V(8); PG8_WAIT_L(0); PG8_BAR; PG8_MMA(1, 0, At, B0); PG8_MMA(1, 1, At, B1); PG8_BAR; PG8_SCHED;
;             PG8_LDB(B0, 1, 0); PG8_LDB(B1, 1, 1); PG8_SCHED; PG8_LDA(At, 1, 0); PG8_STAGE(PG8_SA(0, 1), a2 + hstep, voffA);
;             PG8_WAIT_V(8); PG8_WAIT_L(0); PG8_BAR; PG8_MMA(0, 0, At, B0); PG8_MMA(0, 1, At, B1); PG8_BAR; PG8_SCHED;
	v_mfma_f32_16x16x32_bf16 v[60:63], v[170:173], v[202:205], 0
	v_mfma_f32_16x16x32_bf16 v[56:59], v[178:181], v[202:205], 0
	v_mfma_f32_16x16x32_bf16 v[44:47], v[170:173], v[210:213], 0
	v_mfma_f32_16x16x32_bf16 v[40:43], v[178:181], v[210:213], 0
	v_mfma_f32_16x16x32_bf16 v[28:31], v[170:173], v[218:221], 0
	v_mfma_f32_16x16x32_bf16 v[24:27], v[178:181], v[218:221], 0
	v_mfma_f32_16x16x32_bf16 v[12:15], v[170:173], v[226:229], 0
	v_mfma_f32_16x16x32_bf16 v[8:11], v[178:181], v[226:229], 0
	v_mfma_f32_16x16x32_bf16 v[60:63], v[174:177], v[206:209], v[60:63]
	v_mfma_f32_16x16x32_bf16 v[56:59], v[182:185], v[206:209], v[56:59]
	v_mfma_f32_16x16x32_bf16 v[44:47], v[174:177], v[214:217], v[44:47]
	v_mfma_f32_16x16x32_bf16 v[40:43], v[182:185], v[214:217], v[40:43]
	v_mfma_f32_16x16x32_bf16 v[28:31], v[174:177], v[222:225], v[28:31]
	v_mfma_f32_16x16x32_bf16 v[24:27], v[182:185], v[222:225], v[24:27]
	v_mfma_f32_16x16x32_bf16 v[12:15], v[174:177], v[230:233], v[12:15]
	v_mfma_f32_16x16x32_bf16 v[8:11], v[182:185], v[230:233], v[8:11]
	s_setprio 0
	s_setprio 1
	v_mfma_f32_16x16x32_bf16 v[52:55], v[186:189], v[202:205], 0
	v_mfma_f32_16x16x32_bf16 v[48:51], v[194:197], v[202:205], 0
	v_mfma_f32_16x16x32_bf16 v[36:39], v[186:189], v[210:213], 0
	v_mfma_f32_16x16x32_bf16 v[32:35], v[194:197], v[210:213], 0
	v_mfma_f32_16x16x32_bf16 v[20:23], v[186:189], v[218:221], 0
	v_mfma_f32_16x16x32_bf16 v[16:19], v[194:197], v[218:221], 0
	v_mfma_f32_16x16x32_bf16 v[4:7], v[186:189], v[226:229], 0
	v_mfma_f32_16x16x32_bf16 v[0:3], v[194:197], v[226:229], 0
	v_mfma_f32_16x16x32_bf16 v[52:55], v[190:193], v[206:209], v[52:55]
	v_mfma_f32_16x16x32_bf16 v[48:51], v[198:201], v[206:209], v[48:51]
	v_mfma_f32_16x16x32_bf16 v[36:39], v[190:193], v[214:217], v[36:39]
	v_mfma_f32_16x16x32_bf16 v[32:35], v[198:201], v[214:217], v[32:35]
	v_mfma_f32_16x16x32_bf16 v[20:23], v[190:193], v[222:225], v[20:23]
	v_mfma_f32_16x16x32_bf16 v[16:19], v[198:201], v[222:225], v[16:19]
	v_mfma_f32_16x16x32_bf16 v[4:7], v[190:193], v[230:233], v[4:7]
	v_mfma_f32_16x16x32_bf16 v[0:3], v[198:201], v[230:233], v[0:3]
	s_barrier
	s_setprio 0
	ds_read_b128 v[170:173], v161
	ds_read_b128 v[174:177], v162
	ds_read_b128 v[178:181], v163
	ds_read_b128 v[182:185], v164
	ds_read_b128 v[186:189], v165
	ds_read_b128 v[190:193], v166
	ds_read_b128 v[194:197], v167
	ds_read_b128 v[198:201], v168
	s_add_u32 s42, s42, 0x40000
	s_addc_u32 s43, s43, 0
	s_mov_b32 m0, s51
	v_lshl_add_u64 v[242:243], s[42:43], 0, v[128:129]
	ds_read_b128 v[202:205], v149 offset:32768
	ds_read_b128 v[206:209], v149 offset:33792
	ds_read_b128 v[210:213], v149 offset:34816
	ds_read_b128 v[214:217], v149 offset:35840
	ds_read_b128 v[218:221], v149 offset:36864
	ds_read_b128 v[222:225], v149 offset:37888
	ds_read_b128 v[226:229], v149 offset:38912
	ds_read_b128 v[230:233], v149 offset:39936
	global_load_lds_dwordx4 v[242:243], off
	v_lshl_add_u64 v[242:243], s[42:43], 0, v[132:133]
	s_mov_b32 m0, s52
	s_nop 0
	global_load_lds_dwordx4 v[242:243], off
	s_waitcnt vmcnt(8)
	s_waitcnt lgkmcnt(0)
	s_setprio 1
	s_barrier
	v_mfma_f32_16x16x32_bf16 v[124:127], v[170:173], v[202:205], v[124:127]
	v_mfma_f32_16x16x32_bf16 v[120:123], v[178:181], v[202:205], v[120:123]
	v_mfma_f32_16x16x32_bf16 v[108:111], v[170:173], v[210:213], v[108:111]
	v_mfma_f32_16x16x32_bf16 v[104:107], v[178:181], v[210:213], v[104:107]
	v_mfma_f32_16x16x32_bf16 v[92:95], v[170:173], v[218:221], v[92:95]
	v_mfma_f32_16x16x32_bf16 v[88:91], v[178:181], v[218:221], v[88:91]
	v_mfma_f32_16x16x32_bf16 v[76:79], v[170:173], v[226:229], v[76:79]
	v_mfma_f32_16x16x32_bf16 v[72:75], v[178:181], v[226:229], v[72:75]
	v_mfma_f32_16x16x32_bf16 v[124:127], v[174:177], v[206:209], v[124:127]
	v_mfma_f32_16x16x32_bf16 v[120:123], v[182:185], v[206:209], v[120:123]
	v_mfma_f32_16x16x32_bf16 v[108:111], v[174:177], v[214:217], v[108:111]
	v_mfma_f32_16x16x32_bf16 v[104:107], v[182:185], v[214:217], v[104:107]
	v_mfma_f32_16x16x32_bf16 v[92:95], v[174:177], v[222:225], v[92:95]
	v_mfma_f32_16x16x32_bf16 v[88:91], v[182:185], v[222:225], v[88:91]
	v_mfma_f32_16x16x32_bf16 v[76:79], v[174:177], v[230:233], v[76:79]
	v_mfma_f32_16x16x32_bf16 v[72:75], v[182:185], v[230:233], v[72:75]
	s_setprio 0
	s_setprio 1
	v_mfma_f32_16x16x32_bf16 v[116:119], v[186:189], v[202:205], v[116:119]
	v_mfma_f32_16x16x32_bf16 v[112:115], v[194:197], v[202:205], v[112:115]
	v_mfma_f32_16x16x32_bf16 v[100:103], v[186:189], v[210:213], v[100:103]
	v_mfma_f32_16x16x32_bf16 v[96:99], v[194:197], v[210:213], v[96:99]
	v_mfma_f32_16x16x32_bf16 v[84:87], v[186:189], v[218:221], v[84:87]
	v_mfma_f32_16x16x32_bf16 v[80:83], v[194:197], v[218:221], v[80:83]
	v_mfma_f32_16x16x32_bf16 v[68:71], v[186:189], v[226:229], v[68:71]
	v_mfma_f32_16x16x32_bf16 v[64:67], v[194:197], v[226:229], v[64:67]
	v_mfma_f32_16x16x32_bf16 v[116:119], v[190:193], v[206:209], v[116:119]
	v_mfma_f32_16x16x32_bf16 v[112:115], v[198:201], v[206:209], v[112:115]
	v_mfma_f32_16x16x32_bf16 v[100:103], v[190:193], v[214:217], v[100:103]
	v_mfma_f32_16x16x32_bf16 v[96:99], v[198:201], v[214:217], v[96:99]
	v_mfma_f32_16x16x32_bf16 v[84:87], v[190:193], v[222:225], v[84:87]
	v_mfma_f32_16x16x32_bf16 v[80:83], v[198:201], v[222:225], v[80:83]
	v_mfma_f32_16x16x32_bf16 v[68:71], v[190:193], v[230:233], v[68:71]
	v_mfma_f32_16x16x32_bf16 v[64:67], v[198:201], v[230:233], v[64:67]
	s_barrier
; #define PG8_STAGE(bufoff, gbase, voff) do { _Pragma("unroll") for (int _i = 0; _i < 2; ++_i) \
;         __builtin_amdgcn_global_load_lds((const unsigned*)((const char*)(gbase) + (voff)[_i]), (PG8_LAS unsigned*)(lds + (bufoff) + ldsw + _i * 8192), 16, 0, 0); } while (0)
; #define PG8_LDA(dst, b, h) do { _Pragma("unroll") for (int m = 0; m < 4; ++m) _Pragma("unroll") for (int k = 0; k < 2; ++k) dst[m][k] = *(const PG8_LAS bf16x8*)(lds + PG8_SA(b, h) + aoff + m * 2048 + k * 1024); } while (0)
; #define PG8_MMA(ai, bj, At, Bt) do { __builtin_amdgcn_s_setprio(1); _Pragma("unroll") for (int m = 0; m < 4; ++m) _Pragma("unroll") for (int n = 0; n < 2; ++n) _Pragma("unroll") for (int k = 0; k < 2; ++k) \
;         acc[ai][bj][m][n] = __builtin_amdgcn_mfma_f32_16x16x32_bf16(Bt[n][k], At[m][k], acc[ai][bj][m][n], 0, 0, 0); __builtin_amdgcn_s_setprio(0); } while (0)
; #define PG8_WAIT_V(n) asm volatile("s_waitcnt vmcnt(" #n ")" ::: "memory")
; #define PG8_WAIT_L(n) asm volatile("s_waitcnt lgkmcnt(" #n ")" ::: "memory")
; #define PG8_BAR __builtin_amdgcn_s_barrier()
; #define PG8_SCHED __builtin_amdgcn_sched_barrier(0)
; template <class Epi, class Sched, bool ALIGN_EPI = false, bool SP2 = false>
; __device__ __forceinline__ void gemm_phase(PG8_LAS unsigned char* lds, const Gemm g, const Sched& S, const Epi& E, const int tid_arg) {
;     ...
;         for (int t = 0; t < nt; t += 2) {
;     ...
;             PG8_LDA(At, 1, 1); PG8_STAGE(PG8_SB(1, 0), b3, voffB); PG8_STAGE(PG8_SB(1, 1), b3 + hstep, voffB); PG8_STAGE(PG8_SA(1, 0), a3, voffA);
;             PG8_WAIT_V(8); PG8_WAIT_L(0); PG8_BAR; PG8_MMA(1, 0, At, B0); PG8_MMA(1, 1, At, B1); PG8_BAR; PG8_SCHED;
	s_setprio 0
	s_mov_b32 m0, s54
	v_lshl_add_u64 v[234:235], v[234:235], 0, s[12:13]
	s_add_u32 s0, s0, 0x40080
	ds_read_b128 v[202:205], v149 offset:49152
	ds_read_b128 v[206:209], v149 offset:50176
	ds_read_b128 v[210:213], v149 offset:51200
	ds_read_b128 v[214:217], v149 offset:52224
	ds_read_b128 v[218:221], v149 offset:53248
	ds_read_b128 v[222:225], v149 offset:54272
	ds_read_b128 v[226:229], v149 offset:55296
	ds_read_b128 v[230:233], v149 offset:56320
	global_load_lds_dwordx4 v[234:235], off
	v_lshl_add_u64 v[234:235], v[236:237], 0, s[12:13]
	s_mov_b32 m0, s55
	s_addc_u32 s1, s1, 0
	global_load_lds_dwordx4 v[234:235], off
	v_lshl_add_u64 v[234:235], s[0:1], 0, v[130:131]
	s_mov_b32 m0, s58
	s_nop 0
	global_load_lds_dwordx4 v[234:235], off
	v_lshl_add_u64 v[234:235], s[0:1], 0, v[134:135]
	s_mov_b32 m0, s59
	s_nop 0
	global_load_lds_dwordx4 v[234:235], off
	v_lshl_add_u64 v[234:235], v[238:239], 0, s[12:13]
	s_mov_b32 m0, s56
	s_nop 0
	global_load_lds_dwordx4 v[234:235], off
	v_lshl_add_u64 v[234:235], v[240:241], 0, s[12:13]
	s_mov_b32 m0, s57
	s_nop 0
	global_load_lds_dwordx4 v[234:235], off
	s_waitcnt vmcnt(8)
	s_waitcnt lgkmcnt(0)
	s_setprio 1
	s_barrier
	v_mfma_f32_16x16x32_bf16 v[60:63], v[170:173], v[202:205], v[60:63]
	v_mfma_f32_16x16x32_bf16 v[56:59], v[178:181], v[202:205], v[56:59]
	v_mfma_f32_16x16x32_bf16 v[44:47], v[170:173], v[210:213], v[44:47]
	v_mfma_f32_16x16x32_bf16 v[40:43], v[178:181], v[210:213], v[40:43]
	v_mfma_f32_16x16x32_bf16 v[28:31], v[170:173], v[218:221], v[28:31]
	v_mfma_f32_16x16x32_bf16 v[24:27], v[178:181], v[218:221], v[24:27]
	v_mfma_f32_16x16x32_bf16 v[12:15], v[170:173], v[226:229], v[12:15]
	v_mfma_f32_16x16x32_bf16 v[8:11], v[178:181], v[226:229], v[8:11]
	v_mfma_f32_16x16x32_bf16 v[60:63], v[174:177], v[206:209], v[60:63]
	v_mfma_f32_16x16x32_bf16 v[56:59], v[182:185], v[206:209], v[56:59]
	v_mfma_f32_16x16x32_bf16 v[44:47], v[174:177], v[214:217], v[44:47]
	v_mfma_f32_16x16x32_bf16 v[40:43], v[182:185], v[214:217], v[40:43]
	v_mfma_f32_16x16x32_bf16 v[28:31], v[174:177], v[222:225], v[28:31]
	v_mfma_f32_16x16x32_bf16 v[24:27], v[182:185], v[222:225], v[24:27]
	v_mfma_f32_16x16x32_bf16 v[12:15], v[174:177], v[230:233], v[12:15]
	v_mfma_f32_16x16x32_bf16 v[8:11], v[182:185], v[230:233], v[8:11]
	s_setprio 0
	s_setprio 1
	v_mfma_f32_16x16x32_bf16 v[52:55], v[186:189], v[202:205], v[52:55]
	v_mfma_f32_16x16x32_bf16 v[48:51], v[194:197], v[202:205], v[48:51]
	v_mfma_f32_16x16x32_bf16 v[36:39], v[186:189], v[210:213], v[36:39]
	v_mfma_f32_16x16x32_bf16 v[32:35], v[194:197], v[210:213], v[32:35]
	v_mfma_f32_16x16x32_bf16 v[20:23], v[186:189], v[218:221], v[20:23]
	v_mfma_f32_16x16x32_bf16 v[16:19], v[194:197], v[218:221], v[16:19]
	v_mfma_f32_16x16x32_bf16 v[4:7], v[186:189], v[226:229], v[4:7]
	v_mfma_f32_16x16x32_bf16 v[0:3], v[194:197], v[226:229], v[0:3]
	v_mfma_f32_16x16x32_bf16 v[52:55], v[190:193], v[206:209], v[52:55]
	v_mfma_f32_16x16x32_bf16 v[48:51], v[198:201], v[206:209], v[48:51]
	v_mfma_f32_16x16x32_bf16 v[36:39], v[190:193], v[214:217], v[36:39]
	v_mfma_f32_16x16x32_bf16 v[32:35], v[198:201], v[214:217], v[32:35]
	v_mfma_f32_16x16x32_bf16 v[20:23], v[190:193], v[222:225], v[20:23]
	v_mfma_f32_16x16x32_bf16 v[16:19], v[198:201], v[222:225], v[16:19]
	v_mfma_f32_16x16x32_bf16 v[4:7], v[190:193], v[230:233], v[4:7]
	v_mfma_f32_16x16x32_bf16 v[0:3], v[198:201], v[230:233], v[0:3]
	s_barrier
	s_setprio 0
	s_add_i32 s72, s72, 2
	s_add_u32 s70, s70, 0x100
	s_addc_u32 s71, s71, 0
	s_add_u32 s40, s40, 0x100
	s_addc_u32 s41, s41, 0
	s_cmp_gt_u32 s72, 13
	s_cbranch_scc0 .LBB0_965
	s_branch .Lkpeel_exit_5

; #define PG8_BAR __builtin_amdgcn_s_barrier()
; template <class Epi, class Sched, bool ALIGN_EPI = false, bool SP2 = false>
; __device__ __forceinline__ void gemm_phase(PG8_LAS unsigned char* lds, const Gemm g, const Sched& S, const Epi& E, const int tid_arg) {
;     ...
;         if constexpr (ALIGN_EPI) { if (wr == 0) PG8_BAR; }
.Lkpeel_exit_5:
	s_and_b64 vcc, exec, s[14:15]
	s_cbranch_vccz .LBB0_968
	s_barrier

; #define PG8_STAGE(bufoff, gbase, voff) do { _Pragma("unroll") for (int _i = 0; _i < 2; ++_i) \
;         __builtin_amdgcn_global_load_lds((const unsigned*)((const char*)(gbase) + (voff)[_i]), (PG8_LAS unsigned*)(lds + (bufoff) + ldsw + _i * 8192), 16, 0, 0); } while (0)
; #define PG8_LDA(dst, b, h) do { _Pragma("unroll") for (int m = 0; m < 4; ++m) _Pragma("unroll") for (int k = 0; k < 2; ++k) dst[m][k] = *(const PG8_LAS bf16x8*)(lds + PG8_SA(b, h) + aoff + m * 2048 + k * 1024); } while (0)
; #define PG8_LDB(dst, b, h) do { _Pragma("unroll") for (int n = 0; n < 2; ++n) _Pragma("unroll") for (int k = 0; k < 2; ++k) dst[n][k] = *(const PG8_LAS bf16x8*)(lds + PG8_SB(b, h) + boff + n * 2048 + k * 1024); } while (0)
; #define PG8_MMA(ai, bj, At, Bt) do { __builtin_amdgcn_s_setprio(1); _Pragma("unroll") for (int m = 0; m < 4; ++m) _Pragma("unroll") for (int n = 0; n < 2; ++n) _Pragma("unroll") for (int k = 0; k < 2; ++k) \
;         acc[ai][bj][m][n] = __builtin_amdgcn_mfma_f32_16x16x32_bf16(Bt[n][k], At[m][k], acc[ai][bj][m][n], 0, 0, 0); __builtin_amdgcn_s_setprio(0); } while (0)
; template <class Epi, class Sched, bool ALIGN_EPI = false, bool SP2 = false>
; __device__ __forceinline__ void gemm_phase(PG8_LAS unsigned char* lds, const Gemm g, const Sched& S, const Epi& E, const int tid_arg) {
;     ...
;         const bool has_next = S.next(ui + 1, nxt);
;         const char* nA = has_next ? (const char*)g.A + (size_t)nxt.pm * tstep : cA; const char* nB = has_next ? (const char*)g.Bt + (size_t)nxt.pn * tstep : cB;
;         for (int t = 0; t < nt; t += 2) {
;             const bool last = (t == nt - 2);
;             const char* a1 = cA + (size_t)(t + 1) * kstep;
;             const char* a2 = last ? nA : cA + (size_t)(t + 2) * kstep; const char* b2 = last ? nB : cB + (size_t)(t + 2) * kstep;
;             const char* a3 = a2 + kstep; const char* b3 = b2 + kstep;
;             if (last && has_next) S.a_ready(nxt);
;             if constexpr (SP2) {
;             PG8_LDB(B0, 0, 0); PG8_LDB(B1, 0, 1); PG8_SCHED; PG8_LDA(At, 0, 0); PG8_STAGE(PG8_SA(1, 1), a1 + hstep, voffA);
;             PG8_WAIT_V(8); PG8_WAIT_L(0); PG8_BAR; PG8_MMA(0, 0, At, B0); PG8_MMA(0, 1, At, B1); PG8_BAR; PG8_SCHED;
;             PG8_LDA(At, 0, 1); PG8_STAGE(PG8_SB(0, 0), b2, voffB); PG8_STAGE(PG8_SB(0, 1), b2 + hstep, voffB); PG8_STAGE(PG8_SA(0, 0), a2, voffA);
.LBB0_1044:
	v_mov_b32_e32 v127, 0
	s_and_b64 vcc, exec, s[10:11]
	s_cbranch_vccnz .LBB0_1047
	s_add_u32 s60, s4, 0x100
	s_addc_u32 s61, s5, 0
	s_add_u32 s4, s30, 0x80
	v_mov_b32_e32 v0, 0
	s_addc_u32 s5, s31, 0
	s_mov_b32 s0, 0
	ds_read_b128 v[144:147], v151
	ds_read_b128 v[168:171], v152
	ds_read_b128 v[172:175], v153
	ds_read_b128 v[176:179], v154
	ds_read_b128 v[180:183], v155
	ds_read_b128 v[184:187], v156
	ds_read_b128 v[188:191], v157
	ds_read_b128 v[192:195], v158
	s_add_i32 s30, s0, 2
	s_add_u32 s31, s4, 0x80
	s_addc_u32 s1, s5, 0
	s_cmp_eq_u32 s52, s0
	s_cselect_b32 s0, s14, s31
	s_cselect_b32 s1, s15, s1
	s_cselect_b32 s63, s29, s61
	s_cselect_b32 s62, s28, s60
	s_mov_b32 m0, s53
	v_lshl_add_u64 v[228:229], s[4:5], 0, v[138:139]
	ds_read_b128 v[196:199], v150
	ds_read_b128 v[200:203], v150 offset:1024
	ds_read_b128 v[204:207], v150 offset:2048
	ds_read_b128 v[208:211], v150 offset:3072
	ds_read_b128 v[212:215], v150 offset:4096
	ds_read_b128 v[216:219], v150 offset:5120
	ds_read_b128 v[220:223], v150 offset:6144
	ds_read_b128 v[224:227], v150 offset:7168
	global_load_lds_dwordx4 v[228:229], off
	v_lshl_add_u64 v[228:229], s[4:5], 0, v[136:137]
	s_mov_b32 m0, s54
	s_nop 0
	global_load_lds_dwordx4 v[228:229], off
	s_waitcnt vmcnt(8)
	s_waitcnt lgkmcnt(0)
	s_setprio 1
	s_barrier
	v_mfma_f32_16x16x32_bf16 v[124:127], v[144:147], v[196:199], 0
	v_mfma_f32_16x16x32_bf16 v[120:123], v[172:175], v[196:199], 0
	v_mfma_f32_16x16x32_bf16 v[108:111], v[144:147], v[204:207], 0
	v_mfma_f32_16x16x32_bf16 v[104:107], v[172:175], v[204:207], 0
	v_mfma_f32_16x16x32_bf16 v[92:95], v[144:147], v[212:215], 0
	v_mfma_f32_16x16x32_bf16 v[88:91], v[172:175], v[212:215], 0
	v_mfma_f32_16x16x32_bf16 v[76:79], v[144:147], v[220:223], 0
	v_mfma_f32_16x16x32_bf16 v[72:75], v[172:175], v[220:223], 0
	v_mfma_f32_16x16x32_bf16 v[124:127], v[168:171], v[200:203], v[124:127]
	v_mfma_f32_16x16x32_bf16 v[120:123], v[176:179], v[200:203], v[120:123]
	v_mfma_f32_16x16x32_bf16 v[108:111], v[168:171], v[208:211], v[108:111]
	v_mfma_f32_16x16x32_bf16 v[104:107], v[176:179], v[208:211], v[104:107]
	v_mfma_f32_16x16x32_bf16 v[92:95], v[168:171], v[216:219], v[92:95]
	v_mfma_f32_16x16x32_bf16 v[88:91], v[176:179], v[216:219], v[88:91]
	v_mfma_f32_16x16x32_bf16 v[76:79], v[168:171], v[224:227], v[76:79]
	v_mfma_f32_16x16x32_bf16 v[72:75], v[176:179], v[224:227], v[72:75]
	s_setprio 0
	s_setprio 1
	v_mfma_f32_16x16x32_bf16 v[116:119], v[180:183], v[196:199], 0
	v_mfma_f32_16x16x32_bf16 v[112:115], v[188:191], v[196:199], 0
	v_mfma_f32_16x16x32_bf16 v[100:103], v[180:183], v[204:207], 0
	v_mfma_f32_16x16x32_bf16 v[96:99], v[188:191], v[204:207], 0
	v_mfma_f32_16x16x32_bf16 v[84:87], v[180:183], v[212:215], 0
	v_mfma_f32_16x16x32_bf16 v[80:83], v[188:191], v[212:215], 0
	v_mfma_f32_16x16x32_bf16 v[68:71], v[180:183], v[220:223], 0
	v_mfma_f32_16x16x32_bf16 v[64:67], v[188:191], v[220:223], 0
	v_mfma_f32_16x16x32_bf16 v[116:119], v[184:187], v[200:203], v[116:119]
	v_mfma_f32_16x16x32_bf16 v[112:115], v[192:195], v[200:203], v[112:115]
	v_mfma_f32_16x16x32_bf16 v[100:103], v[184:187], v[208:211], v[100:103]
	v_mfma_f32_16x16x32_bf16 v[96:99], v[192:195], v[208:211], v[96:99]
	v_mfma_f32_16x16x32_bf16 v[84:87], v[184:187], v[216:219], v[84:87]
	v_mfma_f32_16x16x32_bf16 v[80:83], v[192:195], v[216:219], v[80:83]
	v_mfma_f32_16x16x32_bf16 v[68:71], v[184:187], v[224:227], v[68:71]
	v_mfma_f32_16x16x32_bf16 v[64:67], v[192:195], v[224:227], v[64:67]
	s_barrier
	s_setprio 0
	s_mov_b32 m0, s37
	v_lshl_add_u64 v[228:229], s[62:63], 0, v[130:131]
	v_lshl_add_u64 v[230:231], s[62:63], 0, v[134:135]
	s_add_u32 s62, s62, s6
	ds_read_b128 v[196:199], v150 offset:16384
	ds_read_b128 v[200:203], v150 offset:17408
	ds_read_b128 v[204:207], v150 offset:18432
	ds_read_b128 v[208:211], v150 offset:19456
	ds_read_b128 v[212:215], v150 offset:20480
	ds_read_b128 v[216:219], v150 offset:21504
	ds_read_b128 v[220:223], v150 offset:22528
	ds_read_b128 v[224:227], v150 offset:23552
	global_load_lds_dwordx4 v[228:229], off
	s_mov_b32 m0, s38
	s_addc_u32 s63, s63, s7
	global_load_lds_dwordx4 v[230:231], off
	v_lshl_add_u64 v[232:233], s[62:63], 0, v[130:131]
	s_mov_b32 m0, s39
	v_lshl_add_u64 v[234:235], s[62:63], 0, v[134:135]
	global_load_lds_dwordx4 v[232:233], off
	s_mov_b32 m0, s40
	v_lshl_add_u64 v[236:237], s[0:1], 0, v[128:129]
	global_load_lds_dwordx4 v[234:235], off
	s_mov_b32 m0, s36
	v_lshl_add_u64 v[238:239], s[0:1], 0, v[132:133]
	global_load_lds_dwordx4 v[236:237], off
	s_mov_b32 m0, s41
	s_nop 0
	global_load_lds_dwordx4 v[238:239], off
	s_waitcnt vmcnt(8)
	s_waitcnt lgkmcnt(0)
	s_setprio 1
	s_barrier
; #define PG8_STAGE(bufoff, gbase, voff) do { _Pragma("unroll") for (int _i = 0; _i < 2; ++_i) \
;         __builtin_amdgcn_global_load_lds((const unsigned*)((const char*)(gbase) + (voff)[_i]), (PG8_LAS unsigned*)(lds + (bufoff) + ldsw + _i * 8192), 16, 0, 0); } while (0)
; #define PG8_LDA(dst, b, h) do { _Pragma("unroll") for (int m = 0; m < 4; ++m) _Pragma("unroll") for (int k = 0; k < 2; ++k) dst[m][k] = *(const PG8_LAS bf16x8*)(lds + PG8_SA(b, h) + aoff + m * 2048 + k * 1024); } while (0)
; #define PG8_LDB(dst, b, h) do { _Pragma("unroll") for (int n = 0; n < 2; ++n) _Pragma("unroll") for (int k = 0; k < 2; ++k) dst[n][k] = *(const PG8_LAS bf16x8*)(lds + PG8_SB(b, h) + boff + n * 2048 + k * 1024); } while (0)
; #define PG8_MMA(ai, bj, At, Bt) do { __builtin_amdgcn_s_setprio(1); _Pragma("unroll") for (int m = 0; m < 4; ++m) _Pragma("unroll") for (int n = 0; n < 2; ++n) _Pragma("unroll") for (int k = 0; k < 2; ++k) \
;         acc[ai][bj][m][n] = __builtin_amdgcn_mfma_f32_16x16x32_bf16(Bt[n][k], At[m][k], acc[ai][bj][m][n], 0, 0, 0); __builtin_amdgcn_s_setprio(0); } while (0)
; #define PG8_WAIT_V(n) asm volatile("s_waitcnt vmcnt(" #n ")" ::: "memory")
; #define PG8_WAIT_L(n) asm volatile("s_waitcnt lgkmcnt(" #n ")" ::: "memory")
; #define PG8_BAR __builtin_amdgcn_s_barrier()
; #define PG8_SCHED __builtin_amdgcn_sched_barrier(0)
; template <class Epi, class Sched, bool ALIGN_EPI = false, bool SP2 = false>
; __device__ __forceinline__ void gemm_phase(PG8_LAS unsigned char* lds, const Gemm g, const Sched& S, const Epi& E, const int tid_arg) {
;     ...
;             PG8_WAIT_V(8); PG8_WAIT_L(0); PG8_BAR; PG8_MMA(1, 0, At, B0); PG8_MMA(1, 1, At, B1); PG8_BAR; PG8_SCHED;
;             PG8_LDB(B0, 1, 0); PG8_LDB(B1, 1, 1); PG8_SCHED; PG8_LDA(At, 1, 0); PG8_STAGE(PG8_SA(0, 1), a2 + hstep, voffA);
;             PG8_WAIT_V(8); PG8_WAIT_L(0); PG8_BAR; PG8_MMA(0, 0, At, B0); PG8_MMA(0, 1, At, B1); PG8_BAR; PG8_SCHED;
	v_mfma_f32_16x16x32_bf16 v[60:63], v[144:147], v[196:199], 0
	v_mfma_f32_16x16x32_bf16 v[56:59], v[172:175], v[196:199], 0
	v_mfma_f32_16x16x32_bf16 v[44:47], v[144:147], v[204:207], 0
	v_mfma_f32_16x16x32_bf16 v[40:43], v[172:175], v[204:207], 0
	v_mfma_f32_16x16x32_bf16 v[28:31], v[144:147], v[212:215], 0
	v_mfma_f32_16x16x32_bf16 v[24:27], v[172:175], v[212:215], 0
	v_mfma_f32_16x16x32_bf16 v[12:15], v[144:147], v[220:223], 0
	v_mfma_f32_16x16x32_bf16 v[8:11], v[172:175], v[220:223], 0
	v_mfma_f32_16x16x32_bf16 v[60:63], v[168:171], v[200:203], v[60:63]
	v_mfma_f32_16x16x32_bf16 v[56:59], v[176:179], v[200:203], v[56:59]
	v_mfma_f32_16x16x32_bf16 v[44:47], v[168:171], v[208:211], v[44:47]
	v_mfma_f32_16x16x32_bf16 v[40:43], v[176:179], v[208:211], v[40:43]
	v_mfma_f32_16x16x32_bf16 v[28:31], v[168:171], v[216:219], v[28:31]
	v_mfma_f32_16x16x32_bf16 v[24:27], v[176:179], v[216:219], v[24:27]
	v_mfma_f32_16x16x32_bf16 v[12:15], v[168:171], v[224:227], v[12:15]
	v_mfma_f32_16x16x32_bf16 v[8:11], v[176:179], v[224:227], v[8:11]
	s_setprio 0
	s_setprio 1
	v_mfma_f32_16x16x32_bf16 v[52:55], v[180:183], v[196:199], 0
	v_mfma_f32_16x16x32_bf16 v[48:51], v[188:191], v[196:199], 0
	v_mfma_f32_16x16x32_bf16 v[36:39], v[180:183], v[204:207], 0
	v_mfma_f32_16x16x32_bf16 v[32:35], v[188:191], v[204:207], 0
	v_mfma_f32_16x16x32_bf16 v[20:23], v[180:183], v[212:215], 0
	v_mfma_f32_16x16x32_bf16 v[16:19], v[188:191], v[212:215], 0
	v_mfma_f32_16x16x32_bf16 v[4:7], v[180:183], v[220:223], 0
	v_mfma_f32_16x16x32_bf16 v[0:3], v[188:191], v[220:223], 0
	v_mfma_f32_16x16x32_bf16 v[52:55], v[184:187], v[200:203], v[52:55]
	v_mfma_f32_16x16x32_bf16 v[48:51], v[192:195], v[200:203], v[48:51]
	v_mfma_f32_16x16x32_bf16 v[36:39], v[184:187], v[208:211], v[36:39]
	v_mfma_f32_16x16x32_bf16 v[32:35], v[192:195], v[208:211], v[32:35]
	v_mfma_f32_16x16x32_bf16 v[20:23], v[184:187], v[216:219], v[20:23]
	v_mfma_f32_16x16x32_bf16 v[16:19], v[192:195], v[216:219], v[16:19]
	v_mfma_f32_16x16x32_bf16 v[4:7], v[184:187], v[224:227], v[4:7]
	v_mfma_f32_16x16x32_bf16 v[0:3], v[192:195], v[224:227], v[0:3]
	s_barrier
	s_setprio 0
	ds_read_b128 v[144:147], v159
	ds_read_b128 v[168:171], v160
	ds_read_b128 v[172:175], v161
	ds_read_b128 v[176:179], v162
	ds_read_b128 v[180:183], v163
	ds_read_b128 v[184:187], v164
	ds_read_b128 v[188:191], v165
	ds_read_b128 v[192:195], v166
	s_add_u32 s0, s0, s6
	s_addc_u32 s1, s1, s7
	s_mov_b32 m0, s42
	v_lshl_add_u64 v[240:241], s[0:1], 0, v[128:129]
	ds_read_b128 v[196:199], v150 offset:32768
	ds_read_b128 v[200:203], v150 offset:33792
	ds_read_b128 v[204:207], v150 offset:34816
	ds_read_b128 v[208:211], v150 offset:35840
	ds_read_b128 v[212:215], v150 offset:36864
	ds_read_b128 v[216:219], v150 offset:37888
	ds_read_b128 v[220:223], v150 offset:38912
	ds_read_b128 v[224:227], v150 offset:39936
	global_load_lds_dwordx4 v[240:241], off
	v_lshl_add_u64 v[240:241], s[0:1], 0, v[132:133]
	s_mov_b32 m0, s43
	s_nop 0
	global_load_lds_dwordx4 v[240:241], off
	s_waitcnt vmcnt(8)
	s_waitcnt lgkmcnt(0)
	s_setprio 1
	s_barrier
	v_mfma_f32_16x16x32_bf16 v[124:127], v[144:147], v[196:199], v[124:127]
	v_mfma_f32_16x16x32_bf16 v[120:123], v[172:175], v[196:199], v[120:123]
	v_mfma_f32_16x16x32_bf16 v[108:111], v[144:147], v[204:207], v[108:111]
	v_mfma_f32_16x16x32_bf16 v[104:107], v[172:175], v[204:207], v[104:107]
	v_mfma_f32_16x16x32_bf16 v[92:95], v[144:147], v[212:215], v[92:95]
	v_mfma_f32_16x16x32_bf16 v[88:91], v[172:175], v[212:215], v[88:91]
	v_mfma_f32_16x16x32_bf16 v[76:79], v[144:147], v[220:223], v[76:79]
	v_mfma_f32_16x16x32_bf16 v[72:75], v[172:175], v[220:223], v[72:75]
	v_mfma_f32_16x16x32_bf16 v[124:127], v[168:171], v[200:203], v[124:127]
	v_mfma_f32_16x16x32_bf16 v[120:123], v[176:179], v[200:203], v[120:123]
	v_mfma_f32_16x16x32_bf16 v[108:111], v[168:171], v[208:211], v[108:111]
	v_mfma_f32_16x16x32_bf16 v[104:107], v[176:179], v[208:211], v[104:107]
	v_mfma_f32_16x16x32_bf16 v[92:95], v[168:171], v[216:219], v[92:95]
	v_mfma_f32_16x16x32_bf16 v[88:91], v[176:179], v[216:219], v[88:91]
	v_mfma_f32_16x16x32_bf16 v[76:79], v[168:171], v[224:227], v[76:79]
	v_mfma_f32_16x16x32_bf16 v[72:75], v[176:179], v[224:227], v[72:75]
	s_setprio 0
	s_setprio 1
	v_mfma_f32_16x16x32_bf16 v[116:119], v[180:183], v[196:199], v[116:119]
	v_mfma_f32_16x16x32_bf16 v[112:115], v[188:191], v[196:199], v[112:115]
	v_mfma_f32_16x16x32_bf16 v[100:103], v[180:183], v[204:207], v[100:103]
	v_mfma_f32_16x16x32_bf16 v[96:99], v[188:191], v[204:207], v[96:99]
	v_mfma_f32_16x16x32_bf16 v[84:87], v[180:183], v[212:215], v[84:87]
	v_mfma_f32_16x16x32_bf16 v[80:83], v[188:191], v[212:215], v[80:83]
	v_mfma_f32_16x16x32_bf16 v[68:71], v[180:183], v[220:223], v[68:71]
	v_mfma_f32_16x16x32_bf16 v[64:67], v[188:191], v[220:223], v[64:67]
	v_mfma_f32_16x16x32_bf16 v[116:119], v[184:187], v[200:203], v[116:119]
	v_mfma_f32_16x16x32_bf16 v[112:115], v[192:195], v[200:203], v[112:115]
	v_mfma_f32_16x16x32_bf16 v[100:103], v[184:187], v[208:211], v[100:103]
	v_mfma_f32_16x16x32_bf16 v[96:99], v[192:195], v[208:211], v[96:99]
	v_mfma_f32_16x16x32_bf16 v[84:87], v[184:187], v[216:219], v[84:87]
	v_mfma_f32_16x16x32_bf16 v[80:83], v[192:195], v[216:219], v[80:83]
	v_mfma_f32_16x16x32_bf16 v[68:71], v[184:187], v[224:227], v[68:71]
	v_mfma_f32_16x16x32_bf16 v[64:67], v[192:195], v[224:227], v[64:67]
	s_barrier
; #define PG8_STAGE(bufoff, gbase, voff) do { _Pragma("unroll") for (int _i = 0; _i < 2; ++_i) \
;         __builtin_amdgcn_global_load_lds((const unsigned*)((const char*)(gbase) + (voff)[_i]), (PG8_LAS unsigned*)(lds + (bufoff) + ldsw + _i * 8192), 16, 0, 0); } while (0)
; #define PG8_LDA(dst, b, h) do { _Pragma("unroll") for (int m = 0; m < 4; ++m) _Pragma("unroll") for (int k = 0; k < 2; ++k) dst[m][k] = *(const PG8_LAS bf16x8*)(lds + PG8_SA(b, h) + aoff + m * 2048 + k * 1024); } while (0)
; #define PG8_MMA(ai, bj, At, Bt) do { __builtin_amdgcn_s_setprio(1); _Pragma("unroll") for (int m = 0; m < 4; ++m) _Pragma("unroll") for (int n = 0; n < 2; ++n) _Pragma("unroll") for (int k = 0; k < 2; ++k) \
;         acc[ai][bj][m][n] = __builtin_amdgcn_mfma_f32_16x16x32_bf16(Bt[n][k], At[m][k], acc[ai][bj][m][n], 0, 0, 0); __builtin_amdgcn_s_setprio(0); } while (0)
; #define PG8_WAIT_V(n) asm volatile("s_waitcnt vmcnt(" #n ")" ::: "memory")
; #define PG8_WAIT_L(n) asm volatile("s_waitcnt lgkmcnt(" #n ")" ::: "memory")
; #define PG8_BAR __builtin_amdgcn_s_barrier()
; #define PG8_SCHED __builtin_amdgcn_sched_barrier(0)
; template <class Epi, class Sched, bool ALIGN_EPI = false, bool SP2 = false>
; __device__ __forceinline__ void gemm_phase(PG8_LAS unsigned char* lds, const Gemm g, const Sched& S, const Epi& E, const int tid_arg) {
;     ...
;         for (int t = 0; t < nt; t += 2) {
;     ...
;             PG8_LDA(At, 1, 1); PG8_STAGE(PG8_SB(1, 0), b3, voffB); PG8_STAGE(PG8_SB(1, 1), b3 + hstep, voffB); PG8_STAGE(PG8_SA(1, 0), a3, voffA);
;             PG8_WAIT_V(8); PG8_WAIT_L(0); PG8_BAR; PG8_MMA(1, 0, At, B0); PG8_MMA(1, 1, At, B1); PG8_BAR; PG8_SCHED;
	s_setprio 0
	s_mov_b32 m0, s44
	v_lshl_add_u64 v[228:229], v[228:229], 0, s[22:23]
	ds_read_b128 v[196:199], v150 offset:49152
	ds_read_b128 v[200:203], v150 offset:50176
	ds_read_b128 v[204:207], v150 offset:51200
	ds_read_b128 v[208:211], v150 offset:52224
	ds_read_b128 v[212:215], v150 offset:53248
	ds_read_b128 v[216:219], v150 offset:54272
	ds_read_b128 v[220:223], v150 offset:55296
	ds_read_b128 v[224:227], v150 offset:56320
	global_load_lds_dwordx4 v[228:229], off
	v_lshl_add_u64 v[228:229], v[230:231], 0, s[22:23]
	s_mov_b32 m0, s45
	s_nop 0
	global_load_lds_dwordx4 v[228:229], off
	v_lshl_add_u64 v[228:229], v[232:233], 0, s[22:23]
	s_mov_b32 m0, s48
	s_nop 0
	global_load_lds_dwordx4 v[228:229], off
	v_lshl_add_u64 v[228:229], v[234:235], 0, s[22:23]
	s_mov_b32 m0, s49
	s_nop 0
	global_load_lds_dwordx4 v[228:229], off
	v_lshl_add_u64 v[228:229], v[236:237], 0, s[22:23]
	s_mov_b32 m0, s46
	s_nop 0
	global_load_lds_dwordx4 v[228:229], off
	v_lshl_add_u64 v[228:229], v[238:239], 0, s[22:23]
	s_mov_b32 m0, s47
	s_nop 0
	global_load_lds_dwordx4 v[228:229], off
	s_waitcnt vmcnt(8)
	s_waitcnt lgkmcnt(0)
	s_setprio 1
	s_barrier
	v_mfma_f32_16x16x32_bf16 v[60:63], v[144:147], v[196:199], v[60:63]
	v_mfma_f32_16x16x32_bf16 v[56:59], v[172:175], v[196:199], v[56:59]
	v_mfma_f32_16x16x32_bf16 v[44:47], v[144:147], v[204:207], v[44:47]
	v_mfma_f32_16x16x32_bf16 v[40:43], v[172:175], v[204:207], v[40:43]
	v_mfma_f32_16x16x32_bf16 v[28:31], v[144:147], v[212:215], v[28:31]
	v_mfma_f32_16x16x32_bf16 v[24:27], v[172:175], v[212:215], v[24:27]
	v_mfma_f32_16x16x32_bf16 v[12:15], v[144:147], v[220:223], v[12:15]
	v_mfma_f32_16x16x32_bf16 v[8:11], v[172:175], v[220:223], v[8:11]
	v_mfma_f32_16x16x32_bf16 v[60:63], v[168:171], v[200:203], v[60:63]
	v_mfma_f32_16x16x32_bf16 v[56:59], v[176:179], v[200:203], v[56:59]
	v_mfma_f32_16x16x32_bf16 v[44:47], v[168:171], v[208:211], v[44:47]
	v_mfma_f32_16x16x32_bf16 v[40:43], v[176:179], v[208:211], v[40:43]
	v_mfma_f32_16x16x32_bf16 v[28:31], v[168:171], v[216:219], v[28:31]
	v_mfma_f32_16x16x32_bf16 v[24:27], v[176:179], v[216:219], v[24:27]
	v_mfma_f32_16x16x32_bf16 v[12:15], v[168:171], v[224:227], v[12:15]
	v_mfma_f32_16x16x32_bf16 v[8:11], v[176:179], v[224:227], v[8:11]
	s_setprio 0
	s_setprio 1
	v_mfma_f32_16x16x32_bf16 v[52:55], v[180:183], v[196:199], v[52:55]
	v_mfma_f32_16x16x32_bf16 v[48:51], v[188:191], v[196:199], v[48:51]
	v_mfma_f32_16x16x32_bf16 v[36:39], v[180:183], v[204:207], v[36:39]
	v_mfma_f32_16x16x32_bf16 v[32:35], v[188:191], v[204:207], v[32:35]
	v_mfma_f32_16x16x32_bf16 v[20:23], v[180:183], v[212:215], v[20:23]
	v_mfma_f32_16x16x32_bf16 v[16:19], v[188:191], v[212:215], v[16:19]
	v_mfma_f32_16x16x32_bf16 v[4:7], v[180:183], v[220:223], v[4:7]
	v_mfma_f32_16x16x32_bf16 v[0:3], v[188:191], v[220:223], v[0:3]
	v_mfma_f32_16x16x32_bf16 v[52:55], v[184:187], v[200:203], v[52:55]
	v_mfma_f32_16x16x32_bf16 v[48:51], v[192:195], v[200:203], v[48:51]
	v_mfma_f32_16x16x32_bf16 v[36:39], v[184:187], v[208:211], v[36:39]
	v_mfma_f32_16x16x32_bf16 v[32:35], v[192:195], v[208:211], v[32:35]
	v_mfma_f32_16x16x32_bf16 v[20:23], v[184:187], v[216:219], v[20:23]
	v_mfma_f32_16x16x32_bf16 v[16:19], v[192:195], v[216:219], v[16:19]
	v_mfma_f32_16x16x32_bf16 v[4:7], v[184:187], v[224:227], v[4:7]
	v_mfma_f32_16x16x32_bf16 v[0:3], v[192:195], v[224:227], v[0:3]
	s_barrier
	s_setprio 0
	s_add_u32 s60, s60, 0x100
	s_addc_u32 s61, s61, 0
	s_add_u32 s4, s4, 0x100
	s_addc_u32 s5, s5, 0
	s_cmp_ge_i32 s30, s50
	s_mov_b32 s0, s30
	s_cbranch_scc0 .LBB0_1046
	s_branch .Lkpeel_exit_6

; #define PG8_BAR __builtin_amdgcn_s_barrier()
; template <class Epi, class Sched, bool ALIGN_EPI = false, bool SP2 = false>
; __device__ __forceinline__ void gemm_phase(PG8_LAS unsigned char* lds, const Gemm g, const Sched& S, const Epi& E, const int tid_arg) {
;     ...
;         if constexpr (ALIGN_EPI) { if (wr == 0) PG8_BAR; }
.Lkpeel_exit_6:
.LBB0_1047:
	s_and_b64 vcc, exec, s[26:27]
	s_cbranch_vccz .LBB0_1049
	s_barrier

; #define PG8_STAGE(bufoff, gbase, voff) do { _Pragma("unroll") for (int _i = 0; _i < 2; ++_i) \
;         __builtin_amdgcn_global_load_lds((const unsigned*)((const char*)(gbase) + (voff)[_i]), (PG8_LAS unsigned*)(lds + (bufoff) + ldsw + _i * 8192), 16, 0, 0); } while (0)
; #define PG8_LDA(dst, b, h) do { _Pragma("unroll") for (int m = 0; m < 4; ++m) _Pragma("unroll") for (int k = 0; k < 2; ++k) dst[m][k] = *(const PG8_LAS bf16x8*)(lds + PG8_SA(b, h) + aoff + m * 2048 + k * 1024); } while (0)
; #define PG8_LDB(dst, b, h) do { _Pragma("unroll") for (int n = 0; n < 2; ++n) _Pragma("unroll") for (int k = 0; k < 2; ++k) dst[n][k] = *(const PG8_LAS bf16x8*)(lds + PG8_SB(b, h) + boff + n * 2048 + k * 1024); } while (0)
; #define PG8_MMA(ai, bj, At, Bt) do { __builtin_amdgcn_s_setprio(1); _Pragma("unroll") for (int m = 0; m < 4; ++m) _Pragma("unroll") for (int n = 0; n < 2; ++n) _Pragma("unroll") for (int k = 0; k < 2; ++k) \
;         acc[ai][bj][m][n] = __builtin_amdgcn_mfma_f32_16x16x32_bf16(Bt[n][k], At[m][k], acc[ai][bj][m][n], 0, 0, 0); __builtin_amdgcn_s_setprio(0); } while (0)
; template <class Epi, class Sched, bool ALIGN_EPI = false, bool SP2 = false>
; __device__ __forceinline__ void gemm_phase(PG8_LAS unsigned char* lds, const Gemm g, const Sched& S, const Epi& E, const int tid_arg) {
;     ...
;         const bool has_next = S.next(ui + 1, nxt);
;         const char* nA = has_next ? (const char*)g.A + (size_t)nxt.pm * tstep : cA; const char* nB = has_next ? (const char*)g.Bt + (size_t)nxt.pn * tstep : cB;
;         for (int t = 0; t < nt; t += 2) {
;             const bool last = (t == nt - 2);
;             const char* a1 = cA + (size_t)(t + 1) * kstep;
;             const char* a2 = last ? nA : cA + (size_t)(t + 2) * kstep; const char* b2 = last ? nB : cB + (size_t)(t + 2) * kstep;
;             const char* a3 = a2 + kstep; const char* b3 = b2 + kstep;
;             if (last && has_next) S.a_ready(nxt);
;             if constexpr (SP2) {
;             PG8_LDB(B0, 0, 0); PG8_LDB(B1, 0, 1); PG8_SCHED; PG8_LDA(At, 0, 0); PG8_STAGE(PG8_SA(1, 1), a1 + hstep, voffA);
;             PG8_WAIT_V(8); PG8_WAIT_L(0); PG8_BAR; PG8_MMA(0, 0, At, B0); PG8_MMA(0, 1, At, B1); PG8_BAR; PG8_SCHED;
;             PG8_LDA(At, 0, 1); PG8_STAGE(PG8_SB(0, 0), b2, voffB); PG8_STAGE(PG8_SB(0, 1), b2 + hstep, voffB); PG8_STAGE(PG8_SA(0, 0), a2, voffA);
.LBB0_1178:
	s_ashr_i32 s25, s24, 31
	s_lshl_b64 s[0:1], s[24:25], 19
	s_add_u32 s26, s2, s0
	s_addc_u32 s27, s3, s1
	s_and_b64 s[0:1], s[6:7], exec
	s_cselect_b32 s25, s27, s11
	s_cselect_b32 s36, s26, s10
	s_ashr_i32 s23, s22, 31
	s_lshl_b64 s[0:1], s[22:23], 19
	s_add_u32 s28, s33, s0
	s_addc_u32 s29, s38, s1
	s_and_b64 s[0:1], s[6:7], exec
	s_cselect_b32 s23, s29, s5
	s_cselect_b32 s37, s28, s4
	s_add_u32 s66, s4, 0x100
	s_addc_u32 s67, s5, 0
	s_add_u32 s4, s10, 0x40080
	v_mov_b32_e32 v0, 0
	s_addc_u32 s5, s11, 0
	s_mov_b32 s68, -2
	s_waitcnt vmcnt(0)
	ds_read_b128 v[144:147], v166
	ds_read_b128 v[148:151], v167
	ds_read_b128 v[152:155], v168
	ds_read_b128 v[156:159], v169
	ds_read_b128 v[184:187], v170
	ds_read_b128 v[188:191], v171
	ds_read_b128 v[192:195], v172
	ds_read_b128 v[196:199], v173
	s_add_u32 s0, s4, 0xfffc0080
	s_addc_u32 s1, s5, -1
	s_cmp_eq_u32 s68, 12
	s_cselect_b32 s11, s25, s1
	s_cselect_b32 s10, s36, s0
	s_cselect_b32 s1, s23, s67
	s_cselect_b32 s0, s37, s66
	s_mov_b32 m0, s55
	v_lshl_add_u64 v[160:161], s[4:5], 0, v[138:139]
	ds_read_b128 v[200:203], v165
	ds_read_b128 v[204:207], v165 offset:1024
	ds_read_b128 v[208:211], v165 offset:2048
	ds_read_b128 v[212:215], v165 offset:3072
	ds_read_b128 v[216:219], v165 offset:4096
	ds_read_b128 v[220:223], v165 offset:5120
	ds_read_b128 v[224:227], v165 offset:6144
	ds_read_b128 v[228:231], v165 offset:7168
	global_load_lds_dwordx4 v[160:161], off
	v_lshl_add_u64 v[160:161], s[4:5], 0, v[136:137]
	s_mov_b32 m0, s56
	s_nop 0
	global_load_lds_dwordx4 v[160:161], off
	s_waitcnt vmcnt(8)
	s_waitcnt lgkmcnt(0)
	s_setprio 1
	s_barrier
	v_mfma_f32_16x16x32_bf16 v[124:127], v[144:147], v[200:203], 0
	v_mfma_f32_16x16x32_bf16 v[120:123], v[152:155], v[200:203], 0
	v_mfma_f32_16x16x32_bf16 v[108:111], v[144:147], v[208:211], 0
	v_mfma_f32_16x16x32_bf16 v[104:107], v[152:155], v[208:211], 0
	v_mfma_f32_16x16x32_bf16 v[92:95], v[144:147], v[216:219], 0
	v_mfma_f32_16x16x32_bf16 v[88:91], v[152:155], v[216:219], 0
	v_mfma_f32_16x16x32_bf16 v[76:79], v[144:147], v[224:227], 0
	v_mfma_f32_16x16x32_bf16 v[72:75], v[152:155], v[224:227], 0
	v_mfma_f32_16x16x32_bf16 v[124:127], v[148:151], v[204:207], v[124:127]
	v_mfma_f32_16x16x32_bf16 v[120:123], v[156:159], v[204:207], v[120:123]
	v_mfma_f32_16x16x32_bf16 v[108:111], v[148:151], v[212:215], v[108:111]
	v_mfma_f32_16x16x32_bf16 v[104:107], v[156:159], v[212:215], v[104:107]
	v_mfma_f32_16x16x32_bf16 v[92:95], v[148:151], v[220:223], v[92:95]
	v_mfma_f32_16x16x32_bf16 v[88:91], v[156:159], v[220:223], v[88:91]
	v_mfma_f32_16x16x32_bf16 v[76:79], v[148:151], v[228:231], v[76:79]
	v_mfma_f32_16x16x32_bf16 v[72:75], v[156:159], v[228:231], v[72:75]
	s_setprio 0
	s_setprio 1
	v_mfma_f32_16x16x32_bf16 v[116:119], v[184:187], v[200:203], 0
	v_mfma_f32_16x16x32_bf16 v[112:115], v[192:195], v[200:203], 0
	v_mfma_f32_16x16x32_bf16 v[100:103], v[184:187], v[208:211], 0
	v_mfma_f32_16x16x32_bf16 v[96:99], v[192:195], v[208:211], 0
	v_mfma_f32_16x16x32_bf16 v[84:87], v[184:187], v[216:219], 0
	v_mfma_f32_16x16x32_bf16 v[80:83], v[192:195], v[216:219], 0
	v_mfma_f32_16x16x32_bf16 v[68:71], v[184:187], v[224:227], 0
	v_mfma_f32_16x16x32_bf16 v[64:67], v[192:195], v[224:227], 0
	v_mfma_f32_16x16x32_bf16 v[116:119], v[188:191], v[204:207], v[116:119]
	v_mfma_f32_16x16x32_bf16 v[112:115], v[196:199], v[204:207], v[112:115]
	v_mfma_f32_16x16x32_bf16 v[100:103], v[188:191], v[212:215], v[100:103]
	v_mfma_f32_16x16x32_bf16 v[96:99], v[196:199], v[212:215], v[96:99]
	v_mfma_f32_16x16x32_bf16 v[84:87], v[188:191], v[220:223], v[84:87]
	v_mfma_f32_16x16x32_bf16 v[80:83], v[196:199], v[220:223], v[80:83]
	v_mfma_f32_16x16x32_bf16 v[68:71], v[188:191], v[228:231], v[68:71]
	v_mfma_f32_16x16x32_bf16 v[64:67], v[196:199], v[228:231], v[64:67]
	s_barrier
	s_setprio 0
	s_mov_b32 m0, s31
	v_lshl_add_u64 v[160:161], s[0:1], 0, v[130:131]
	s_add_u32 s70, s0, 0x40000
	ds_read_b128 v[200:203], v165 offset:16384
	ds_read_b128 v[204:207], v165 offset:17408
	ds_read_b128 v[208:211], v165 offset:18432
	ds_read_b128 v[212:215], v165 offset:19456
	ds_read_b128 v[216:219], v165 offset:20480
	ds_read_b128 v[220:223], v165 offset:21504
	ds_read_b128 v[224:227], v165 offset:22528
	ds_read_b128 v[228:231], v165 offset:23552
	global_load_lds_dwordx4 v[160:161], off
	v_lshl_add_u64 v[232:233], s[0:1], 0, v[134:135]
	s_mov_b32 m0, s35
	s_addc_u32 s71, s1, 0
	global_load_lds_dwordx4 v[232:233], off
	v_lshl_add_u64 v[234:235], s[70:71], 0, v[130:131]
	s_mov_b32 m0, s40
	v_lshl_add_u64 v[236:237], s[10:11], 0, v[132:133]
	global_load_lds_dwordx4 v[234:235], off
	v_lshl_add_u64 v[234:235], s[70:71], 0, v[134:135]
	s_mov_b32 m0, s41
	s_nop 0
	global_load_lds_dwordx4 v[234:235], off
	v_lshl_add_u64 v[234:235], s[10:11], 0, v[128:129]
	s_mov_b32 m0, s39
	s_nop 0
	global_load_lds_dwordx4 v[234:235], off
	s_mov_b32 m0, s42
	s_nop 0
	global_load_lds_dwordx4 v[236:237], off
	s_waitcnt vmcnt(8)
	s_waitcnt lgkmcnt(0)
	s_setprio 1
	s_barrier
; #define PG8_STAGE(bufoff, gbase, voff) do { _Pragma("unroll") for (int _i = 0; _i < 2; ++_i) \
;         __builtin_amdgcn_global_load_lds((const unsigned*)((const char*)(gbase) + (voff)[_i]), (PG8_LAS unsigned*)(lds + (bufoff) + ldsw + _i * 8192), 16, 0, 0); } while (0)
; #define PG8_LDA(dst, b, h) do { _Pragma("unroll") for (int m = 0; m < 4; ++m) _Pragma("unroll") for (int k = 0; k < 2; ++k) dst[m][k] = *(const PG8_LAS bf16x8*)(lds + PG8_SA(b, h) + aoff + m * 2048 + k * 1024); } while (0)
; #define PG8_LDB(dst, b, h) do { _Pragma("unroll") for (int n = 0; n < 2; ++n) _Pragma("unroll") for (int k = 0; k < 2; ++k) dst[n][k] = *(const PG8_LAS bf16x8*)(lds + PG8_SB(b, h) + boff + n * 2048 + k * 1024); } while (0)
; #define PG8_MMA(ai, bj, At, Bt) do { __builtin_amdgcn_s_setprio(1); _Pragma("unroll") for (int m = 0; m < 4; ++m) _Pragma("unroll") for (int n = 0; n < 2; ++n) _Pragma("unroll") for (int k = 0; k < 2; ++k) \
;         acc[ai][bj][m][n] = __builtin_amdgcn_mfma_f32_16x16x32_bf16(Bt[n][k], At[m][k], acc[ai][bj][m][n], 0, 0, 0); __builtin_amdgcn_s_setprio(0); } while (0)
; #define PG8_WAIT_V(n) asm volatile("s_waitcnt vmcnt(" #n ")" ::: "memory")
; #define PG8_WAIT_L(n) asm volatile("s_waitcnt lgkmcnt(" #n ")" ::: "memory")
; #define PG8_BAR __builtin_amdgcn_s_barrier()
; #define PG8_SCHED __builtin_amdgcn_sched_barrier(0)
; template <class Epi, class Sched, bool ALIGN_EPI = false, bool SP2 = false>
; __device__ __forceinline__ void gemm_phase(PG8_LAS unsigned char* lds, const Gemm g, const Sched& S, const Epi& E, const int tid_arg) {
;     ...
;             PG8_WAIT_V(8); PG8_WAIT_L(0); PG8_BAR; PG8_MMA(1, 0, At, B0); PG8_MMA(1, 1, At, B1); PG8_BAR; PG8_SCHED;
;             PG8_LDB(B0, 1, 0); PG8_LDB(B1, 1, 1); PG8_SCHED; PG8_LDA(At, 1, 0); PG8_STAGE(PG8_SA(0, 1), a2 + hstep, voffA);
;             PG8_WAIT_V(8); PG8_WAIT_L(0); PG8_BAR; PG8_MMA(0, 0, At, B0); PG8_MMA(0, 1, At, B1); PG8_BAR; PG8_SCHED;
	v_mfma_f32_16x16x32_bf16 v[60:63], v[144:147], v[200:203], 0
	v_mfma_f32_16x16x32_bf16 v[56:59], v[152:155], v[200:203], 0
	v_mfma_f32_16x16x32_bf16 v[44:47], v[144:147], v[208:211], 0
	v_mfma_f32_16x16x32_bf16 v[40:43], v[152:155], v[208:211], 0
	v_mfma_f32_16x16x32_bf16 v[28:31], v[144:147], v[216:219], 0
	v_mfma_f32_16x16x32_bf16 v[24:27], v[152:155], v[216:219], 0
	v_mfma_f32_16x16x32_bf16 v[12:15], v[144:147], v[224:227], 0
	v_mfma_f32_16x16x32_bf16 v[8:11], v[152:155], v[224:227], 0
	v_mfma_f32_16x16x32_bf16 v[60:63], v[148:151], v[204:207], v[60:63]
	v_mfma_f32_16x16x32_bf16 v[56:59], v[156:159], v[204:207], v[56:59]
	v_mfma_f32_16x16x32_bf16 v[44:47], v[148:151], v[212:215], v[44:47]
	v_mfma_f32_16x16x32_bf16 v[40:43], v[156:159], v[212:215], v[40:43]
	v_mfma_f32_16x16x32_bf16 v[28:31], v[148:151], v[220:223], v[28:31]
	v_mfma_f32_16x16x32_bf16 v[24:27], v[156:159], v[220:223], v[24:27]
	v_mfma_f32_16x16x32_bf16 v[12:15], v[148:151], v[228:231], v[12:15]
	v_mfma_f32_16x16x32_bf16 v[8:11], v[156:159], v[228:231], v[8:11]
	s_setprio 0
	s_setprio 1
	v_mfma_f32_16x16x32_bf16 v[52:55], v[184:187], v[200:203], 0
	v_mfma_f32_16x16x32_bf16 v[48:51], v[192:195], v[200:203], 0
	v_mfma_f32_16x16x32_bf16 v[36:39], v[184:187], v[208:211], 0
	v_mfma_f32_16x16x32_bf16 v[32:35], v[192:195], v[208:211], 0
	v_mfma_f32_16x16x32_bf16 v[20:23], v[184:187], v[216:219], 0
	v_mfma_f32_16x16x32_bf16 v[16:19], v[192:195], v[216:219], 0
	v_mfma_f32_16x16x32_bf16 v[4:7], v[184:187], v[224:227], 0
	v_mfma_f32_16x16x32_bf16 v[0:3], v[192:195], v[224:227], 0
	v_mfma_f32_16x16x32_bf16 v[52:55], v[188:191], v[204:207], v[52:55]
	v_mfma_f32_16x16x32_bf16 v[48:51], v[196:199], v[204:207], v[48:51]
	v_mfma_f32_16x16x32_bf16 v[36:39], v[188:191], v[212:215], v[36:39]
	v_mfma_f32_16x16x32_bf16 v[32:35], v[196:199], v[212:215], v[32:35]
	v_mfma_f32_16x16x32_bf16 v[20:23], v[188:191], v[220:223], v[20:23]
	v_mfma_f32_16x16x32_bf16 v[16:19], v[196:199], v[220:223], v[16:19]
	v_mfma_f32_16x16x32_bf16 v[4:7], v[188:191], v[228:231], v[4:7]
	v_mfma_f32_16x16x32_bf16 v[0:3], v[196:199], v[228:231], v[0:3]
	s_barrier
	s_setprio 0
	ds_read_b128 v[144:147], v174
	ds_read_b128 v[148:151], v175
	ds_read_b128 v[152:155], v176
	ds_read_b128 v[156:159], v177
	ds_read_b128 v[184:187], v178
	ds_read_b128 v[188:191], v179
	ds_read_b128 v[192:195], v180
	ds_read_b128 v[196:199], v181
	s_add_u32 s10, s10, 0x40000
	s_addc_u32 s11, s11, 0
	s_mov_b32 m0, s43
	v_lshl_add_u64 v[238:239], s[10:11], 0, v[128:129]
	ds_read_b128 v[200:203], v165 offset:32768
	ds_read_b128 v[204:207], v165 offset:33792
	ds_read_b128 v[208:211], v165 offset:34816
	ds_read_b128 v[212:215], v165 offset:35840
	ds_read_b128 v[216:219], v165 offset:36864
	ds_read_b128 v[220:223], v165 offset:37888
	ds_read_b128 v[224:227], v165 offset:38912
	ds_read_b128 v[228:231], v165 offset:39936
	global_load_lds_dwordx4 v[238:239], off
	v_lshl_add_u64 v[238:239], s[10:11], 0, v[132:133]
	s_mov_b32 m0, s44
	s_nop 0
	global_load_lds_dwordx4 v[238:239], off
	s_waitcnt vmcnt(8)
	s_waitcnt lgkmcnt(0)
	s_setprio 1
	s_barrier
	v_mfma_f32_16x16x32_bf16 v[124:127], v[144:147], v[200:203], v[124:127]
	v_mfma_f32_16x16x32_bf16 v[120:123], v[152:155], v[200:203], v[120:123]
	v_mfma_f32_16x16x32_bf16 v[108:111], v[144:147], v[208:211], v[108:111]
	v_mfma_f32_16x16x32_bf16 v[104:107], v[152:155], v[208:211], v[104:107]
	v_mfma_f32_16x16x32_bf16 v[92:95], v[144:147], v[216:219], v[92:95]
	v_mfma_f32_16x16x32_bf16 v[88:91], v[152:155], v[216:219], v[88:91]
	v_mfma_f32_16x16x32_bf16 v[76:79], v[144:147], v[224:227], v[76:79]
	v_mfma_f32_16x16x32_bf16 v[72:75], v[152:155], v[224:227], v[72:75]
	v_mfma_f32_16x16x32_bf16 v[124:127], v[148:151], v[204:207], v[124:127]
	v_mfma_f32_16x16x32_bf16 v[120:123], v[156:159], v[204:207], v[120:123]
	v_mfma_f32_16x16x32_bf16 v[108:111], v[148:151], v[212:215], v[108:111]
	v_mfma_f32_16x16x32_bf16 v[104:107], v[156:159], v[212:215], v[104:107]
	v_mfma_f32_16x16x32_bf16 v[92:95], v[148:151], v[220:223], v[92:95]
	v_mfma_f32_16x16x32_bf16 v[88:91], v[156:159], v[220:223], v[88:91]
	v_mfma_f32_16x16x32_bf16 v[76:79], v[148:151], v[228:231], v[76:79]
	v_mfma_f32_16x16x32_bf16 v[72:75], v[156:159], v[228:231], v[72:75]
	s_setprio 0
	s_setprio 1
	v_mfma_f32_16x16x32_bf16 v[116:119], v[184:187], v[200:203], v[116:119]
	v_mfma_f32_16x16x32_bf16 v[112:115], v[192:195], v[200:203], v[112:115]
	v_mfma_f32_16x16x32_bf16 v[100:103], v[184:187], v[208:211], v[100:103]
	v_mfma_f32_16x16x32_bf16 v[96:99], v[192:195], v[208:211], v[96:99]
	v_mfma_f32_16x16x32_bf16 v[84:87], v[184:187], v[216:219], v[84:87]
	v_mfma_f32_16x16x32_bf16 v[80:83], v[192:195], v[216:219], v[80:83]
	v_mfma_f32_16x16x32_bf16 v[68:71], v[184:187], v[224:227], v[68:71]
	v_mfma_f32_16x16x32_bf16 v[64:67], v[192:195], v[224:227], v[64:67]
	v_mfma_f32_16x16x32_bf16 v[116:119], v[188:191], v[204:207], v[116:119]
	v_mfma_f32_16x16x32_bf16 v[112:115], v[196:199], v[204:207], v[112:115]
	v_mfma_f32_16x16x32_bf16 v[100:103], v[188:191], v[212:215], v[100:103]
	v_mfma_f32_16x16x32_bf16 v[96:99], v[196:199], v[212:215], v[96:99]
	v_mfma_f32_16x16x32_bf16 v[84:87], v[188:191], v[220:223], v[84:87]
	v_mfma_f32_16x16x32_bf16 v[80:83], v[196:199], v[220:223], v[80:83]
	v_mfma_f32_16x16x32_bf16 v[68:71], v[188:191], v[228:231], v[68:71]
	v_mfma_f32_16x16x32_bf16 v[64:67], v[196:199], v[228:231], v[64:67]
	s_barrier
; #define PG8_STAGE(bufoff, gbase, voff) do { _Pragma("unroll") for (int _i = 0; _i < 2; ++_i) \
;         __builtin_amdgcn_global_load_lds((const unsigned*)((const char*)(gbase) + (voff)[_i]), (PG8_LAS unsigned*)(lds + (bufoff) + ldsw + _i * 8192), 16, 0, 0); } while (0)
; #define PG8_LDA(dst, b, h) do { _Pragma("unroll") for (int m = 0; m < 4; ++m) _Pragma("unroll") for (int k = 0; k < 2; ++k) dst[m][k] = *(const PG8_LAS bf16x8*)(lds + PG8_SA(b, h) + aoff + m * 2048 + k * 1024); } while (0)
; #define PG8_MMA(ai, bj, At, Bt) do { __builtin_amdgcn_s_setprio(1); _Pragma("unroll") for (int m = 0; m < 4; ++m) _Pragma("unroll") for (int n = 0; n < 2; ++n) _Pragma("unroll") for (int k = 0; k < 2; ++k) \
;         acc[ai][bj][m][n] = __builtin_amdgcn_mfma_f32_16x16x32_bf16(Bt[n][k], At[m][k], acc[ai][bj][m][n], 0, 0, 0); __builtin_amdgcn_s_setprio(0); } while (0)
; #define PG8_WAIT_V(n) asm volatile("s_waitcnt vmcnt(" #n ")" ::: "memory")
; #define PG8_WAIT_L(n) asm volatile("s_waitcnt lgkmcnt(" #n ")" ::: "memory")
; #define PG8_BAR __builtin_amdgcn_s_barrier()
; #define PG8_SCHED __builtin_amdgcn_sched_barrier(0)
; template <class Epi, class Sched, bool ALIGN_EPI = false, bool SP2 = false>
; __device__ __forceinline__ void gemm_phase(PG8_LAS unsigned char* lds, const Gemm g, const Sched& S, const Epi& E, const int tid_arg) {
;     ...
;         for (int t = 0; t < nt; t += 2) {
;     ...
;             PG8_LDA(At, 1, 1); PG8_STAGE(PG8_SB(1, 0), b3, voffB); PG8_STAGE(PG8_SB(1, 1), b3 + hstep, voffB); PG8_STAGE(PG8_SA(1, 0), a3, voffA);
;             PG8_WAIT_V(8); PG8_WAIT_L(0); PG8_BAR; PG8_MMA(1, 0, At, B0); PG8_MMA(1, 1, At, B1); PG8_BAR; PG8_SCHED;
	s_setprio 0
	s_mov_b32 m0, s47
	v_lshl_add_u64 v[160:161], v[160:161], 0, s[16:17]
	s_add_u32 s0, s0, 0x40080
	ds_read_b128 v[200:203], v165 offset:49152
	ds_read_b128 v[204:207], v165 offset:50176
	ds_read_b128 v[208:211], v165 offset:51200
	ds_read_b128 v[212:215], v165 offset:52224
	ds_read_b128 v[216:219], v165 offset:53248
	ds_read_b128 v[220:223], v165 offset:54272
	ds_read_b128 v[224:227], v165 offset:55296
	ds_read_b128 v[228:231], v165 offset:56320
	global_load_lds_dwordx4 v[160:161], off
	v_lshl_add_u64 v[160:161], v[232:233], 0, s[16:17]
	s_mov_b32 m0, s48
	s_addc_u32 s1, s1, 0
	global_load_lds_dwordx4 v[160:161], off
	v_lshl_add_u64 v[160:161], s[0:1], 0, v[130:131]
	s_mov_b32 m0, s51
	s_nop 0
	global_load_lds_dwordx4 v[160:161], off
	v_lshl_add_u64 v[160:161], s[0:1], 0, v[134:135]
	s_mov_b32 m0, s52
	s_nop 0
	global_load_lds_dwordx4 v[160:161], off
	v_lshl_add_u64 v[160:161], v[234:235], 0, s[16:17]
	s_mov_b32 m0, s49
	s_nop 0
	global_load_lds_dwordx4 v[160:161], off
	v_lshl_add_u64 v[160:161], v[236:237], 0, s[16:17]
	s_mov_b32 m0, s50
	s_nop 0
	global_load_lds_dwordx4 v[160:161], off
	s_waitcnt vmcnt(8)
	s_waitcnt lgkmcnt(0)
	s_setprio 1
	s_barrier
	v_mfma_f32_16x16x32_bf16 v[60:63], v[144:147], v[200:203], v[60:63]
	v_mfma_f32_16x16x32_bf16 v[56:59], v[152:155], v[200:203], v[56:59]
	v_mfma_f32_16x16x32_bf16 v[44:47], v[144:147], v[208:211], v[44:47]
	v_mfma_f32_16x16x32_bf16 v[40:43], v[152:155], v[208:211], v[40:43]
	v_mfma_f32_16x16x32_bf16 v[28:31], v[144:147], v[216:219], v[28:31]
	v_mfma_f32_16x16x32_bf16 v[24:27], v[152:155], v[216:219], v[24:27]
	v_mfma_f32_16x16x32_bf16 v[12:15], v[144:147], v[224:227], v[12:15]
	v_mfma_f32_16x16x32_bf16 v[8:11], v[152:155], v[224:227], v[8:11]
	v_mfma_f32_16x16x32_bf16 v[60:63], v[148:151], v[204:207], v[60:63]
	v_mfma_f32_16x16x32_bf16 v[56:59], v[156:159], v[204:207], v[56:59]
	v_mfma_f32_16x16x32_bf16 v[44:47], v[148:151], v[212:215], v[44:47]
	v_mfma_f32_16x16x32_bf16 v[40:43], v[156:159], v[212:215], v[40:43]
	v_mfma_f32_16x16x32_bf16 v[28:31], v[148:151], v[220:223], v[28:31]
	v_mfma_f32_16x16x32_bf16 v[24:27], v[156:159], v[220:223], v[24:27]
	v_mfma_f32_16x16x32_bf16 v[12:15], v[148:151], v[228:231], v[12:15]
	v_mfma_f32_16x16x32_bf16 v[8:11], v[156:159], v[228:231], v[8:11]
	s_setprio 0
	s_setprio 1
	v_mfma_f32_16x16x32_bf16 v[52:55], v[184:187], v[200:203], v[52:55]
	v_mfma_f32_16x16x32_bf16 v[48:51], v[192:195], v[200:203], v[48:51]
	v_mfma_f32_16x16x32_bf16 v[36:39], v[184:187], v[208:211], v[36:39]
	v_mfma_f32_16x16x32_bf16 v[32:35], v[192:195], v[208:211], v[32:35]
	v_mfma_f32_16x16x32_bf16 v[20:23], v[184:187], v[216:219], v[20:23]
	v_mfma_f32_16x16x32_bf16 v[16:19], v[192:195], v[216:219], v[16:19]
	v_mfma_f32_16x16x32_bf16 v[4:7], v[184:187], v[224:227], v[4:7]
	v_mfma_f32_16x16x32_bf16 v[0:3], v[192:195], v[224:227], v[0:3]
	v_mfma_f32_16x16x32_bf16 v[52:55], v[188:191], v[204:207], v[52:55]
	v_mfma_f32_16x16x32_bf16 v[48:51], v[196:199], v[204:207], v[48:51]
	v_mfma_f32_16x16x32_bf16 v[36:39], v[188:191], v[212:215], v[36:39]
	v_mfma_f32_16x16x32_bf16 v[32:35], v[196:199], v[212:215], v[32:35]
	v_mfma_f32_16x16x32_bf16 v[20:23], v[188:191], v[220:223], v[20:23]
	v_mfma_f32_16x16x32_bf16 v[16:19], v[196:199], v[220:223], v[16:19]
	v_mfma_f32_16x16x32_bf16 v[4:7], v[188:191], v[228:231], v[4:7]
	v_mfma_f32_16x16x32_bf16 v[0:3], v[196:199], v[228:231], v[0:3]
	s_barrier
	s_setprio 0
	s_add_i32 s68, s68, 2
	s_add_u32 s66, s66, 0x100
	s_addc_u32 s67, s67, 0
	s_add_u32 s4, s4, 0x100
	s_addc_u32 s5, s5, 0
	s_cmp_gt_u32 s68, 13
	s_cbranch_scc0 .LBB0_1179
	s_branch .Lkpeel_exit_7

; #define PG8_STAGE(bufoff, gbase, voff) do { _Pragma("unroll") for (int _i = 0; _i < 2; ++_i) \
;         __builtin_amdgcn_global_load_lds((const unsigned*)((const char*)(gbase) + (voff)[_i]), (PG8_LAS unsigned*)(lds + (bufoff) + ldsw + _i * 8192), 16, 0, 0); } while (0)
; #define PG8_LDA(dst, b, h) do { _Pragma("unroll") for (int m = 0; m < 4; ++m) _Pragma("unroll") for (int k = 0; k < 2; ++k) dst[m][k] = *(const PG8_LAS bf16x8*)(lds + PG8_SA(b, h) + aoff + m * 2048 + k * 1024); } while (0)
; #define PG8_LDB(dst, b, h) do { _Pragma("unroll") for (int n = 0; n < 2; ++n) _Pragma("unroll") for (int k = 0; k < 2; ++k) dst[n][k] = *(const PG8_LAS bf16x8*)(lds + PG8_SB(b, h) + boff + n * 2048 + k * 1024); } while (0)
; #define PG8_MMA(ai, bj, At, Bt) do { __builtin_amdgcn_s_setprio(1); _Pragma("unroll") for (int m = 0; m < 4; ++m) _Pragma("unroll") for (int n = 0; n < 2; ++n) _Pragma("unroll") for (int k = 0; k < 2; ++k) \
;         acc[ai][bj][m][n] = __builtin_amdgcn_mfma_f32_16x16x32_bf16(Bt[n][k], At[m][k], acc[ai][bj][m][n], 0, 0, 0); __builtin_amdgcn_s_setprio(0); } while (0)
; template <class Epi, class Sched, bool ALIGN_EPI = false, bool SP2 = false>
; __device__ __forceinline__ void gemm_phase(PG8_LAS unsigned char* lds, const Gemm g, const Sched& S, const Epi& E, const int tid_arg) {
;     ...
;         const bool has_next = S.next(ui + 1, nxt);
;         const char* nA = has_next ? (const char*)g.A + (size_t)nxt.pm * tstep : cA; const char* nB = has_next ? (const char*)g.Bt + (size_t)nxt.pn * tstep : cB;
;         for (int t = 0; t < nt; t += 2) {
;             const bool last = (t == nt - 2);
;             const char* a1 = cA + (size_t)(t + 1) * kstep;
;             const char* a2 = last ? nA : cA + (size_t)(t + 2) * kstep; const char* b2 = last ? nB : cB + (size_t)(t + 2) * kstep;
;             const char* a3 = a2 + kstep; const char* b3 = b2 + kstep;
;             if (last && has_next) S.a_ready(nxt);
;             if constexpr (SP2) {
;             PG8_LDB(B0, 0, 0); PG8_LDB(B1, 0, 1); PG8_SCHED; PG8_LDA(At, 0, 0); PG8_STAGE(PG8_SA(1, 1), a1 + hstep, voffA);
;             PG8_WAIT_V(8); PG8_WAIT_L(0); PG8_BAR; PG8_MMA(0, 0, At, B0); PG8_MMA(0, 1, At, B1); PG8_BAR; PG8_SCHED;
;             PG8_LDA(At, 0, 1); PG8_STAGE(PG8_SB(0, 0), b2, voffB); PG8_STAGE(PG8_SB(0, 1), b2 + hstep, voffB); PG8_STAGE(PG8_SA(0, 0), a2, voffA);
.LBB0_1458:
	s_ashr_i32 s21, s20, 31
	s_lshl_b64 s[0:1], s[20:21], 19
	s_add_u32 s22, s2, s0
	s_addc_u32 s23, s3, s1
	s_and_b64 s[0:1], s[6:7], exec
	s_cselect_b32 s21, s23, s31
	s_cselect_b32 s27, s22, s30
	s_ashr_i32 s19, s18, 31
	s_lshl_b64 s[0:1], s[18:19], 19
	s_add_u32 s24, s33, s0
	s_addc_u32 s25, s34, s1
	s_and_b64 s[0:1], s[6:7], exec
	s_cselect_b32 s19, s25, s29
	s_cselect_b32 s56, s24, s28
	s_add_u32 s57, s28, 0x100
	s_addc_u32 s58, s29, 0
	s_add_u32 s28, s30, 0x40080
	v_mov_b32_e32 v0, 0
	s_addc_u32 s29, s31, 0
	s_mov_b32 s59, -2
	s_waitcnt vmcnt(0)
	ds_read_b128 v[144:147], v151
	ds_read_b128 v[168:171], v152
	ds_read_b128 v[172:175], v153
	ds_read_b128 v[176:179], v154
	ds_read_b128 v[180:183], v155
	ds_read_b128 v[184:187], v156
	ds_read_b128 v[188:191], v157
	ds_read_b128 v[192:195], v158
	s_add_u32 s0, s28, 0xfffc0080
	s_addc_u32 s1, s29, -1
	s_cmp_eq_u32 s59, 12
	s_cselect_b32 s31, s21, s1
	s_cselect_b32 s30, s27, s0
	s_cselect_b32 s1, s19, s58
	s_cselect_b32 s0, s56, s57
	s_mov_b32 m0, s53
	v_lshl_add_u64 v[228:229], s[28:29], 0, v[138:139]
	ds_read_b128 v[196:199], v150
	ds_read_b128 v[200:203], v150 offset:1024
	ds_read_b128 v[204:207], v150 offset:2048
	ds_read_b128 v[208:211], v150 offset:3072
	ds_read_b128 v[212:215], v150 offset:4096
	ds_read_b128 v[216:219], v150 offset:5120
	ds_read_b128 v[220:223], v150 offset:6144
	ds_read_b128 v[224:227], v150 offset:7168
	global_load_lds_dwordx4 v[228:229], off
	v_lshl_add_u64 v[228:229], s[28:29], 0, v[136:137]
	s_mov_b32 m0, s54
	s_nop 0
	global_load_lds_dwordx4 v[228:229], off
	s_waitcnt vmcnt(8)
	s_waitcnt lgkmcnt(0)
	s_setprio 1
	s_barrier
	v_mfma_f32_16x16x32_bf16 v[124:127], v[144:147], v[196:199], 0
	v_mfma_f32_16x16x32_bf16 v[120:123], v[172:175], v[196:199], 0
	v_mfma_f32_16x16x32_bf16 v[108:111], v[144:147], v[204:207], 0
	v_mfma_f32_16x16x32_bf16 v[104:107], v[172:175], v[204:207], 0
	v_mfma_f32_16x16x32_bf16 v[92:95], v[144:147], v[212:215], 0
	v_mfma_f32_16x16x32_bf16 v[88:91], v[172:175], v[212:215], 0
	v_mfma_f32_16x16x32_bf16 v[76:79], v[144:147], v[220:223], 0
	v_mfma_f32_16x16x32_bf16 v[72:75], v[172:175], v[220:223], 0
	v_mfma_f32_16x16x32_bf16 v[124:127], v[168:171], v[200:203], v[124:127]
	v_mfma_f32_16x16x32_bf16 v[120:123], v[176:179], v[200:203], v[120:123]
	v_mfma_f32_16x16x32_bf16 v[108:111], v[168:171], v[208:211], v[108:111]
	v_mfma_f32_16x16x32_bf16 v[104:107], v[176:179], v[208:211], v[104:107]
	v_mfma_f32_16x16x32_bf16 v[92:95], v[168:171], v[216:219], v[92:95]
	v_mfma_f32_16x16x32_bf16 v[88:91], v[176:179], v[216:219], v[88:91]
	v_mfma_f32_16x16x32_bf16 v[76:79], v[168:171], v[224:227], v[76:79]
	v_mfma_f32_16x16x32_bf16 v[72:75], v[176:179], v[224:227], v[72:75]
	s_setprio 0
	s_setprio 1
	v_mfma_f32_16x16x32_bf16 v[116:119], v[180:183], v[196:199], 0
	v_mfma_f32_16x16x32_bf16 v[112:115], v[188:191], v[196:199], 0
	v_mfma_f32_16x16x32_bf16 v[100:103], v[180:183], v[204:207], 0
	v_mfma_f32_16x16x32_bf16 v[96:99], v[188:191], v[204:207], 0
	v_mfma_f32_16x16x32_bf16 v[84:87], v[180:183], v[212:215], 0
	v_mfma_f32_16x16x32_bf16 v[80:83], v[188:191], v[212:215], 0
	v_mfma_f32_16x16x32_bf16 v[68:71], v[180:183], v[220:223], 0
	v_mfma_f32_16x16x32_bf16 v[64:67], v[188:191], v[220:223], 0
	v_mfma_f32_16x16x32_bf16 v[116:119], v[184:187], v[200:203], v[116:119]
	v_mfma_f32_16x16x32_bf16 v[112:115], v[192:195], v[200:203], v[112:115]
	v_mfma_f32_16x16x32_bf16 v[100:103], v[184:187], v[208:211], v[100:103]
	v_mfma_f32_16x16x32_bf16 v[96:99], v[192:195], v[208:211], v[96:99]
	v_mfma_f32_16x16x32_bf16 v[84:87], v[184:187], v[216:219], v[84:87]
	v_mfma_f32_16x16x32_bf16 v[80:83], v[192:195], v[216:219], v[80:83]
	v_mfma_f32_16x16x32_bf16 v[68:71], v[184:187], v[224:227], v[68:71]
	v_mfma_f32_16x16x32_bf16 v[64:67], v[192:195], v[224:227], v[64:67]
	s_barrier
	s_setprio 0
	s_mov_b32 m0, s5
	v_lshl_add_u64 v[228:229], s[0:1], 0, v[130:131]
	s_add_u32 s60, s0, 0x40000
	ds_read_b128 v[196:199], v150 offset:16384
	ds_read_b128 v[200:203], v150 offset:17408
	ds_read_b128 v[204:207], v150 offset:18432
	ds_read_b128 v[208:211], v150 offset:19456
	ds_read_b128 v[212:215], v150 offset:20480
	ds_read_b128 v[216:219], v150 offset:21504
	ds_read_b128 v[220:223], v150 offset:22528
	ds_read_b128 v[224:227], v150 offset:23552
	global_load_lds_dwordx4 v[228:229], off
	v_lshl_add_u64 v[230:231], s[0:1], 0, v[134:135]
	s_mov_b32 m0, s36
	s_addc_u32 s61, s1, 0
	global_load_lds_dwordx4 v[230:231], off
	v_lshl_add_u64 v[232:233], s[60:61], 0, v[130:131]
	s_mov_b32 m0, s37
	v_lshl_add_u64 v[234:235], s[30:31], 0, v[132:133]
	global_load_lds_dwordx4 v[232:233], off
	v_lshl_add_u64 v[232:233], s[60:61], 0, v[134:135]
	s_mov_b32 m0, s38
	s_nop 0
	global_load_lds_dwordx4 v[232:233], off
	v_lshl_add_u64 v[232:233], s[30:31], 0, v[128:129]
	s_mov_b32 m0, s35
	s_nop 0
	global_load_lds_dwordx4 v[232:233], off
	s_mov_b32 m0, s39
	s_nop 0
	global_load_lds_dwordx4 v[234:235], off
	s_waitcnt vmcnt(8)
	s_waitcnt lgkmcnt(0)
	s_setprio 1
	s_barrier
; #define PG8_STAGE(bufoff, gbase, voff) do { _Pragma("unroll") for (int _i = 0; _i < 2; ++_i) \
;         __builtin_amdgcn_global_load_lds((const unsigned*)((const char*)(gbase) + (voff)[_i]), (PG8_LAS unsigned*)(lds + (bufoff) + ldsw + _i * 8192), 16, 0, 0); } while (0)
; #define PG8_LDA(dst, b, h) do { _Pragma("unroll") for (int m = 0; m < 4; ++m) _Pragma("unroll") for (int k = 0; k < 2; ++k) dst[m][k] = *(const PG8_LAS bf16x8*)(lds + PG8_SA(b, h) + aoff + m * 2048 + k * 1024); } while (0)
; #define PG8_LDB(dst, b, h) do { _Pragma("unroll") for (int n = 0; n < 2; ++n) _Pragma("unroll") for (int k = 0; k < 2; ++k) dst[n][k] = *(const PG8_LAS bf16x8*)(lds + PG8_SB(b, h) + boff + n * 2048 + k * 1024); } while (0)
; #define PG8_MMA(ai, bj, At, Bt) do { __builtin_amdgcn_s_setprio(1); _Pragma("unroll") for (int m = 0; m < 4; ++m) _Pragma("unroll") for (int n = 0; n < 2; ++n) _Pragma("unroll") for (int k = 0; k < 2; ++k) \
;         acc[ai][bj][m][n] = __builtin_amdgcn_mfma_f32_16x16x32_bf16(Bt[n][k], At[m][k], acc[ai][bj][m][n], 0, 0, 0); __builtin_amdgcn_s_setprio(0); } while (0)
; #define PG8_WAIT_V(n) asm volatile("s_waitcnt vmcnt(" #n ")" ::: "memory")
; #define PG8_WAIT_L(n) asm volatile("s_waitcnt lgkmcnt(" #n ")" ::: "memory")
; #define PG8_BAR __builtin_amdgcn_s_barrier()
; #define PG8_SCHED __builtin_amdgcn_sched_barrier(0)
; template <class Epi, class Sched, bool ALIGN_EPI = false, bool SP2 = false>
; __device__ __forceinline__ void gemm_phase(PG8_LAS unsigned char* lds, const Gemm g, const Sched& S, const Epi& E, const int tid_arg) {
;     ...
;             PG8_WAIT_V(8); PG8_WAIT_L(0); PG8_BAR; PG8_MMA(1, 0, At, B0); PG8_MMA(1, 1, At, B1); PG8_BAR; PG8_SCHED;
;             PG8_LDB(B0, 1, 0); PG8_LDB(B1, 1, 1); PG8_SCHED; PG8_LDA(At, 1, 0); PG8_STAGE(PG8_SA(0, 1), a2 + hstep, voffA);
;             PG8_WAIT_V(8); PG8_WAIT_L(0); PG8_BAR; PG8_MMA(0, 0, At, B0); PG8_MMA(0, 1, At, B1); PG8_BAR; PG8_SCHED;
	v_mfma_f32_16x16x32_bf16 v[60:63], v[144:147], v[196:199], 0
	v_mfma_f32_16x16x32_bf16 v[56:59], v[172:175], v[196:199], 0
	v_mfma_f32_16x16x32_bf16 v[44:47], v[144:147], v[204:207], 0
	v_mfma_f32_16x16x32_bf16 v[40:43], v[172:175], v[204:207], 0
	v_mfma_f32_16x16x32_bf16 v[28:31], v[144:147], v[212:215], 0
	v_mfma_f32_16x16x32_bf16 v[24:27], v[172:175], v[212:215], 0
	v_mfma_f32_16x16x32_bf16 v[12:15], v[144:147], v[220:223], 0
	v_mfma_f32_16x16x32_bf16 v[8:11], v[172:175], v[220:223], 0
	v_mfma_f32_16x16x32_bf16 v[60:63], v[168:171], v[200:203], v[60:63]
	v_mfma_f32_16x16x32_bf16 v[56:59], v[176:179], v[200:203], v[56:59]
	v_mfma_f32_16x16x32_bf16 v[44:47], v[168:171], v[208:211], v[44:47]
	v_mfma_f32_16x16x32_bf16 v[40:43], v[176:179], v[208:211], v[40:43]
	v_mfma_f32_16x16x32_bf16 v[28:31], v[168:171], v[216:219], v[28:31]
	v_mfma_f32_16x16x32_bf16 v[24:27], v[176:179], v[216:219], v[24:27]
	v_mfma_f32_16x16x32_bf16 v[12:15], v[168:171], v[224:227], v[12:15]
	v_mfma_f32_16x16x32_bf16 v[8:11], v[176:179], v[224:227], v[8:11]
	s_setprio 0
	s_setprio 1
	v_mfma_f32_16x16x32_bf16 v[52:55], v[180:183], v[196:199], 0
	v_mfma_f32_16x16x32_bf16 v[48:51], v[188:191], v[196:199], 0
	v_mfma_f32_16x16x32_bf16 v[36:39], v[180:183], v[204:207], 0
	v_mfma_f32_16x16x32_bf16 v[32:35], v[188:191], v[204:207], 0
	v_mfma_f32_16x16x32_bf16 v[20:23], v[180:183], v[212:215], 0
	v_mfma_f32_16x16x32_bf16 v[16:19], v[188:191], v[212:215], 0
	v_mfma_f32_16x16x32_bf16 v[4:7], v[180:183], v[220:223], 0
	v_mfma_f32_16x16x32_bf16 v[0:3], v[188:191], v[220:223], 0
	v_mfma_f32_16x16x32_bf16 v[52:55], v[184:187], v[200:203], v[52:55]
	v_mfma_f32_16x16x32_bf16 v[48:51], v[192:195], v[200:203], v[48:51]
	v_mfma_f32_16x16x32_bf16 v[36:39], v[184:187], v[208:211], v[36:39]
	v_mfma_f32_16x16x32_bf16 v[32:35], v[192:195], v[208:211], v[32:35]
	v_mfma_f32_16x16x32_bf16 v[20:23], v[184:187], v[216:219], v[20:23]
	v_mfma_f32_16x16x32_bf16 v[16:19], v[192:195], v[216:219], v[16:19]
	v_mfma_f32_16x16x32_bf16 v[4:7], v[184:187], v[224:227], v[4:7]
	v_mfma_f32_16x16x32_bf16 v[0:3], v[192:195], v[224:227], v[0:3]
	s_barrier
	s_setprio 0
	ds_read_b128 v[144:147], v159
	ds_read_b128 v[168:171], v160
	ds_read_b128 v[172:175], v161
	ds_read_b128 v[176:179], v162
	ds_read_b128 v[180:183], v163
	ds_read_b128 v[184:187], v164
	ds_read_b128 v[188:191], v165
	ds_read_b128 v[192:195], v166
	s_add_u32 s30, s30, 0x40000
	s_addc_u32 s31, s31, 0
	s_mov_b32 m0, s40
	v_lshl_add_u64 v[236:237], s[30:31], 0, v[128:129]
	ds_read_b128 v[196:199], v150 offset:32768
	ds_read_b128 v[200:203], v150 offset:33792
	ds_read_b128 v[204:207], v150 offset:34816
	ds_read_b128 v[208:211], v150 offset:35840
	ds_read_b128 v[212:215], v150 offset:36864
	ds_read_b128 v[216:219], v150 offset:37888
	ds_read_b128 v[220:223], v150 offset:38912
	ds_read_b128 v[224:227], v150 offset:39936
	global_load_lds_dwordx4 v[236:237], off
	v_lshl_add_u64 v[236:237], s[30:31], 0, v[132:133]
	s_mov_b32 m0, s41
	s_nop 0
	global_load_lds_dwordx4 v[236:237], off
	s_waitcnt vmcnt(8)
	s_waitcnt lgkmcnt(0)
	s_setprio 1
	s_barrier
	v_mfma_f32_16x16x32_bf16 v[124:127], v[144:147], v[196:199], v[124:127]
	v_mfma_f32_16x16x32_bf16 v[120:123], v[172:175], v[196:199], v[120:123]
	v_mfma_f32_16x16x32_bf16 v[108:111], v[144:147], v[204:207], v[108:111]
	v_mfma_f32_16x16x32_bf16 v[104:107], v[172:175], v[204:207], v[104:107]
	v_mfma_f32_16x16x32_bf16 v[92:95], v[144:147], v[212:215], v[92:95]
	v_mfma_f32_16x16x32_bf16 v[88:91], v[172:175], v[212:215], v[88:91]
	v_mfma_f32_16x16x32_bf16 v[76:79], v[144:147], v[220:223], v[76:79]
	v_mfma_f32_16x16x32_bf16 v[72:75], v[172:175], v[220:223], v[72:75]
	v_mfma_f32_16x16x32_bf16 v[124:127], v[168:171], v[200:203], v[124:127]
	v_mfma_f32_16x16x32_bf16 v[120:123], v[176:179], v[200:203], v[120:123]
	v_mfma_f32_16x16x32_bf16 v[108:111], v[168:171], v[208:211], v[108:111]
	v_mfma_f32_16x16x32_bf16 v[104:107], v[176:179], v[208:211], v[104:107]
	v_mfma_f32_16x16x32_bf16 v[92:95], v[168:171], v[216:219], v[92:95]
	v_mfma_f32_16x16x32_bf16 v[88:91], v[176:179], v[216:219], v[88:91]
	v_mfma_f32_16x16x32_bf16 v[76:79], v[168:171], v[224:227], v[76:79]
	v_mfma_f32_16x16x32_bf16 v[72:75], v[176:179], v[224:227], v[72:75]
	s_setprio 0
	s_setprio 1
	v_mfma_f32_16x16x32_bf16 v[116:119], v[180:183], v[196:199], v[116:119]
	v_mfma_f32_16x16x32_bf16 v[112:115], v[188:191], v[196:199], v[112:115]
	v_mfma_f32_16x16x32_bf16 v[100:103], v[180:183], v[204:207], v[100:103]
	v_mfma_f32_16x16x32_bf16 v[96:99], v[188:191], v[204:207], v[96:99]
	v_mfma_f32_16x16x32_bf16 v[84:87], v[180:183], v[212:215], v[84:87]
	v_mfma_f32_16x16x32_bf16 v[80:83], v[188:191], v[212:215], v[80:83]
	v_mfma_f32_16x16x32_bf16 v[68:71], v[180:183], v[220:223], v[68:71]
	v_mfma_f32_16x16x32_bf16 v[64:67], v[188:191], v[220:223], v[64:67]
	v_mfma_f32_16x16x32_bf16 v[116:119], v[184:187], v[200:203], v[116:119]
	v_mfma_f32_16x16x32_bf16 v[112:115], v[192:195], v[200:203], v[112:115]
	v_mfma_f32_16x16x32_bf16 v[100:103], v[184:187], v[208:211], v[100:103]
	v_mfma_f32_16x16x32_bf16 v[96:99], v[192:195], v[208:211], v[96:99]
	v_mfma_f32_16x16x32_bf16 v[84:87], v[184:187], v[216:219], v[84:87]
	v_mfma_f32_16x16x32_bf16 v[80:83], v[192:195], v[216:219], v[80:83]
	v_mfma_f32_16x16x32_bf16 v[68:71], v[184:187], v[224:227], v[68:71]
	v_mfma_f32_16x16x32_bf16 v[64:67], v[192:195], v[224:227], v[64:67]
	s_barrier
; #define PG8_STAGE(bufoff, gbase, voff) do { _Pragma("unroll") for (int _i = 0; _i < 2; ++_i) \
;         __builtin_amdgcn_global_load_lds((const unsigned*)((const char*)(gbase) + (voff)[_i]), (PG8_LAS unsigned*)(lds + (bufoff) + ldsw + _i * 8192), 16, 0, 0); } while (0)
; #define PG8_LDA(dst, b, h) do { _Pragma("unroll") for (int m = 0; m < 4; ++m) _Pragma("unroll") for (int k = 0; k < 2; ++k) dst[m][k] = *(const PG8_LAS bf16x8*)(lds + PG8_SA(b, h) + aoff + m * 2048 + k * 1024); } while (0)
; #define PG8_MMA(ai, bj, At, Bt) do { __builtin_amdgcn_s_setprio(1); _Pragma("unroll") for (int m = 0; m < 4; ++m) _Pragma("unroll") for (int n = 0; n < 2; ++n) _Pragma("unroll") for (int k = 0; k < 2; ++k) \
;         acc[ai][bj][m][n] = __builtin_amdgcn_mfma_f32_16x16x32_bf16(Bt[n][k], At[m][k], acc[ai][bj][m][n], 0, 0, 0); __builtin_amdgcn_s_setprio(0); } while (0)
; #define PG8_WAIT_V(n) asm volatile("s_waitcnt vmcnt(" #n ")" ::: "memory")
; #define PG8_WAIT_L(n) asm volatile("s_waitcnt lgkmcnt(" #n ")" ::: "memory")
; #define PG8_BAR __builtin_amdgcn_s_barrier()
; #define PG8_SCHED __builtin_amdgcn_sched_barrier(0)
; template <class Epi, class Sched, bool ALIGN_EPI = false, bool SP2 = false>
; __device__ __forceinline__ void gemm_phase(PG8_LAS unsigned char* lds, const Gemm g, const Sched& S, const Epi& E, const int tid_arg) {
;     ...
;         for (int t = 0; t < nt; t += 2) {
;     ...
;             PG8_LDA(At, 1, 1); PG8_STAGE(PG8_SB(1, 0), b3, voffB); PG8_STAGE(PG8_SB(1, 1), b3 + hstep, voffB); PG8_STAGE(PG8_SA(1, 0), a3, voffA);
;             PG8_WAIT_V(8); PG8_WAIT_L(0); PG8_BAR; PG8_MMA(1, 0, At, B0); PG8_MMA(1, 1, At, B1); PG8_BAR; PG8_SCHED;
	s_setprio 0
	s_mov_b32 m0, s45
	v_lshl_add_u64 v[228:229], v[228:229], 0, s[14:15]
	s_add_u32 s0, s0, 0x40080
	ds_read_b128 v[196:199], v150 offset:49152
	ds_read_b128 v[200:203], v150 offset:50176
	ds_read_b128 v[204:207], v150 offset:51200
	ds_read_b128 v[208:211], v150 offset:52224
	ds_read_b128 v[212:215], v150 offset:53248
	ds_read_b128 v[216:219], v150 offset:54272
	ds_read_b128 v[220:223], v150 offset:55296
	ds_read_b128 v[224:227], v150 offset:56320
	global_load_lds_dwordx4 v[228:229], off
	v_lshl_add_u64 v[228:229], v[230:231], 0, s[14:15]
	s_mov_b32 m0, s46
	s_addc_u32 s1, s1, 0
	global_load_lds_dwordx4 v[228:229], off
	v_lshl_add_u64 v[228:229], s[0:1], 0, v[130:131]
	s_mov_b32 m0, s49
	s_nop 0
	global_load_lds_dwordx4 v[228:229], off
	v_lshl_add_u64 v[228:229], s[0:1], 0, v[134:135]
	s_mov_b32 m0, s50
	s_nop 0
	global_load_lds_dwordx4 v[228:229], off
	v_lshl_add_u64 v[228:229], v[232:233], 0, s[14:15]
	s_mov_b32 m0, s47
	s_nop 0
	global_load_lds_dwordx4 v[228:229], off
	v_lshl_add_u64 v[228:229], v[234:235], 0, s[14:15]
	s_mov_b32 m0, s48
	s_nop 0
	global_load_lds_dwordx4 v[228:229], off
	s_waitcnt vmcnt(8)
	s_waitcnt lgkmcnt(0)
	s_setprio 1
	s_barrier
	v_mfma_f32_16x16x32_bf16 v[60:63], v[144:147], v[196:199], v[60:63]
	v_mfma_f32_16x16x32_bf16 v[56:59], v[172:175], v[196:199], v[56:59]
	v_mfma_f32_16x16x32_bf16 v[44:47], v[144:147], v[204:207], v[44:47]
	v_mfma_f32_16x16x32_bf16 v[40:43], v[172:175], v[204:207], v[40:43]
	v_mfma_f32_16x16x32_bf16 v[28:31], v[144:147], v[212:215], v[28:31]
	v_mfma_f32_16x16x32_bf16 v[24:27], v[172:175], v[212:215], v[24:27]
	v_mfma_f32_16x16x32_bf16 v[12:15], v[144:147], v[220:223], v[12:15]
	v_mfma_f32_16x16x32_bf16 v[8:11], v[172:175], v[220:223], v[8:11]
	v_mfma_f32_16x16x32_bf16 v[60:63], v[168:171], v[200:203], v[60:63]
	v_mfma_f32_16x16x32_bf16 v[56:59], v[176:179], v[200:203], v[56:59]
	v_mfma_f32_16x16x32_bf16 v[44:47], v[168:171], v[208:211], v[44:47]
	v_mfma_f32_16x16x32_bf16 v[40:43], v[176:179], v[208:211], v[40:43]
	v_mfma_f32_16x16x32_bf16 v[28:31], v[168:171], v[216:219], v[28:31]
	v_mfma_f32_16x16x32_bf16 v[24:27], v[176:179], v[216:219], v[24:27]
	v_mfma_f32_16x16x32_bf16 v[12:15], v[168:171], v[224:227], v[12:15]
	v_mfma_f32_16x16x32_bf16 v[8:11], v[176:179], v[224:227], v[8:11]
	s_setprio 0
	s_setprio 1
	v_mfma_f32_16x16x32_bf16 v[52:55], v[180:183], v[196:199], v[52:55]
	v_mfma_f32_16x16x32_bf16 v[48:51], v[188:191], v[196:199], v[48:51]
	v_mfma_f32_16x16x32_bf16 v[36:39], v[180:183], v[204:207], v[36:39]
	v_mfma_f32_16x16x32_bf16 v[32:35], v[188:191], v[204:207], v[32:35]
	v_mfma_f32_16x16x32_bf16 v[20:23], v[180:183], v[212:215], v[20:23]
	v_mfma_f32_16x16x32_bf16 v[16:19], v[188:191], v[212:215], v[16:19]
	v_mfma_f32_16x16x32_bf16 v[4:7], v[180:183], v[220:223], v[4:7]
	v_mfma_f32_16x16x32_bf16 v[0:3], v[188:191], v[220:223], v[0:3]
	v_mfma_f32_16x16x32_bf16 v[52:55], v[184:187], v[200:203], v[52:55]
	v_mfma_f32_16x16x32_bf16 v[48:51], v[192:195], v[200:203], v[48:51]
	v_mfma_f32_16x16x32_bf16 v[36:39], v[184:187], v[208:211], v[36:39]
	v_mfma_f32_16x16x32_bf16 v[32:35], v[192:195], v[208:211], v[32:35]
	v_mfma_f32_16x16x32_bf16 v[20:23], v[184:187], v[216:219], v[20:23]
	v_mfma_f32_16x16x32_bf16 v[16:19], v[192:195], v[216:219], v[16:19]
	v_mfma_f32_16x16x32_bf16 v[4:7], v[184:187], v[224:227], v[4:7]
	v_mfma_f32_16x16x32_bf16 v[0:3], v[192:195], v[224:227], v[0:3]
	s_barrier
	s_setprio 0
	s_add_i32 s59, s59, 2
	s_add_u32 s57, s57, 0x100
	s_addc_u32 s58, s58, 0
	s_add_u32 s28, s28, 0x100
	s_addc_u32 s29, s29, 0
	s_cmp_gt_u32 s59, 13
	s_cbranch_scc0 .LBB0_1459
	s_branch .Lkpeel_exit_8

; #define PG8_STAGE(bufoff, gbase, voff) do { _Pragma("unroll") for (int _i = 0; _i < 2; ++_i) \
;         __builtin_amdgcn_global_load_lds((const unsigned*)((const char*)(gbase) + (voff)[_i]), (PG8_LAS unsigned*)(lds + (bufoff) + ldsw + _i * 8192), 16, 0, 0); } while (0)
; #define PG8_LDA(dst, b, h) do { _Pragma("unroll") for (int m = 0; m < 4; ++m) _Pragma("unroll") for (int k = 0; k < 2; ++k) dst[m][k] = *(const PG8_LAS bf16x8*)(lds + PG8_SA(b, h) + aoff + m * 2048 + k * 1024); } while (0)
; #define PG8_LDB(dst, b, h) do { _Pragma("unroll") for (int n = 0; n < 2; ++n) _Pragma("unroll") for (int k = 0; k < 2; ++k) dst[n][k] = *(const PG8_LAS bf16x8*)(lds + PG8_SB(b, h) + boff + n * 2048 + k * 1024); } while (0)
; #define PG8_MMA(ai, bj, At, Bt) do { __builtin_amdgcn_s_setprio(1); _Pragma("unroll") for (int m = 0; m < 4; ++m) _Pragma("unroll") for (int n = 0; n < 2; ++n) _Pragma("unroll") for (int k = 0; k < 2; ++k) \
;         acc[ai][bj][m][n] = __builtin_amdgcn_mfma_f32_16x16x32_bf16(Bt[n][k], At[m][k], acc[ai][bj][m][n], 0, 0, 0); __builtin_amdgcn_s_setprio(0); } while (0)
; template <class Epi, class Sched, bool ALIGN_EPI = false, bool SP2 = false>
; __device__ __forceinline__ void gemm_phase(PG8_LAS unsigned char* lds, const Gemm g, const Sched& S, const Epi& E, const int tid_arg) {
;     ...
;         const bool has_next = S.next(ui + 1, nxt);
;         const char* nA = has_next ? (const char*)g.A + (size_t)nxt.pm * tstep : cA; const char* nB = has_next ? (const char*)g.Bt + (size_t)nxt.pn * tstep : cB;
;         for (int t = 0; t < nt; t += 2) {
;             const bool last = (t == nt - 2);
;             const char* a1 = cA + (size_t)(t + 1) * kstep;
;             const char* a2 = last ? nA : cA + (size_t)(t + 2) * kstep; const char* b2 = last ? nB : cB + (size_t)(t + 2) * kstep;
;             const char* a3 = a2 + kstep; const char* b3 = b2 + kstep;
;             if (last && has_next) S.a_ready(nxt);
;             if constexpr (SP2) {
;             PG8_LDB(B0, 0, 0); PG8_LDB(B1, 0, 1); PG8_SCHED; PG8_LDA(At, 0, 0); PG8_STAGE(PG8_SA(1, 1), a1 + hstep, voffA);
;             PG8_WAIT_V(8); PG8_WAIT_L(0); PG8_BAR; PG8_MMA(0, 0, At, B0); PG8_MMA(0, 1, At, B1); PG8_BAR; PG8_SCHED;
;             PG8_LDA(At, 0, 1); PG8_STAGE(PG8_SB(0, 0), b2, voffB); PG8_STAGE(PG8_SB(0, 1), b2 + hstep, voffB); PG8_STAGE(PG8_SA(0, 0), a2, voffA);
.LBB0_1546:
	s_ashr_i32 s31, s30, 31
	s_lshl_b64 s[0:1], s[30:31], 19
	s_add_u32 s34, s2, s0
	s_addc_u32 s35, s3, s1
	s_and_b64 s[0:1], s[8:9], exec
	s_cselect_b32 s13, s35, s5
	s_cselect_b32 s31, s34, s4
	s_ashr_i32 s29, s28, 31
	s_lshl_b64 s[0:1], s[28:29], 19
	s_add_u32 s36, s44, s0
	s_addc_u32 s37, s45, s1
	s_and_b64 s[0:1], s[8:9], exec
	s_cselect_b32 s29, s37, s7
	s_cselect_b32 s42, s36, s6
	s_add_u32 s43, s6, 0x100
	v_mov_b32_e32 v0, 0
	s_addc_u32 s75, s7, 0
	s_mov_b32 s78, -2
	s_waitcnt vmcnt(0)
	ds_read_b128 v[72:75], v207
	ds_read_b128 v[100:103], v208
	ds_read_b128 v[136:139], v209
	ds_read_b128 v[140:143], v210
	ds_read_b128 v[144:147], v211
	ds_read_b128 v[148:151], v212
	ds_read_b128 v[152:155], v213
	ds_read_b128 v[156:159], v214
	s_add_u32 s6, s4, 0x100
	s_addc_u32 s7, s5, 0
	s_cmp_eq_u32 s78, 12
	s_cselect_b32 s11, s13, s7
	s_cselect_b32 s10, s31, s6
	s_cselect_b32 s1, s29, s75
	s_cselect_b32 s0, s42, s43
	s_mov_b32 m0, s71
	v_lshl_add_u64 v[184:185], s[4:5], 0, v[196:197]
	ds_read_b128 v[160:163], v206
	ds_read_b128 v[164:167], v206 offset:1024
	ds_read_b128 v[168:171], v206 offset:2048
	ds_read_b128 v[172:175], v206 offset:3072
	ds_read_b128 v[176:179], v206 offset:4096
	ds_read_b128 v[180:183], v206 offset:5120
	ds_read_b128 v[226:229], v206 offset:6144
	ds_read_b128 v[230:233], v206 offset:7168
	global_load_lds_dwordx4 v[184:185], off
	v_lshl_add_u64 v[184:185], s[4:5], 0, v[194:195]
	s_mov_b32 m0, s72
	s_nop 0
	global_load_lds_dwordx4 v[184:185], off
	s_waitcnt vmcnt(8)
	s_waitcnt lgkmcnt(0)
	s_setprio 1
	s_barrier
	v_mfma_f32_16x16x32_bf16 v[132:135], v[72:75], v[160:163], 0
	v_mfma_f32_16x16x32_bf16 v[60:63], v[136:139], v[160:163], 0
	v_mfma_f32_16x16x32_bf16 v[124:127], v[72:75], v[168:171], 0
	v_mfma_f32_16x16x32_bf16 v[52:55], v[136:139], v[168:171], 0
	v_mfma_f32_16x16x32_bf16 v[116:119], v[72:75], v[176:179], 0
	v_mfma_f32_16x16x32_bf16 v[44:47], v[136:139], v[176:179], 0
	v_mfma_f32_16x16x32_bf16 v[108:111], v[72:75], v[226:229], 0
	v_mfma_f32_16x16x32_bf16 v[36:39], v[136:139], v[226:229], 0
	v_mfma_f32_16x16x32_bf16 v[132:135], v[100:103], v[164:167], v[132:135]
	v_mfma_f32_16x16x32_bf16 v[60:63], v[140:143], v[164:167], v[60:63]
	v_mfma_f32_16x16x32_bf16 v[124:127], v[100:103], v[172:175], v[124:127]
	v_mfma_f32_16x16x32_bf16 v[52:55], v[140:143], v[172:175], v[52:55]
	v_mfma_f32_16x16x32_bf16 v[116:119], v[100:103], v[180:183], v[116:119]
	v_mfma_f32_16x16x32_bf16 v[44:47], v[140:143], v[180:183], v[44:47]
	v_mfma_f32_16x16x32_bf16 v[108:111], v[100:103], v[230:233], v[108:111]
	v_mfma_f32_16x16x32_bf16 v[36:39], v[140:143], v[230:233], v[36:39]
	s_setprio 0
	s_setprio 1
	v_mfma_f32_16x16x32_bf16 v[128:131], v[144:147], v[160:163], 0
	v_mfma_f32_16x16x32_bf16 v[56:59], v[152:155], v[160:163], 0
	v_mfma_f32_16x16x32_bf16 v[120:123], v[144:147], v[168:171], 0
	v_mfma_f32_16x16x32_bf16 v[48:51], v[152:155], v[168:171], 0
	v_mfma_f32_16x16x32_bf16 v[112:115], v[144:147], v[176:179], 0
	v_mfma_f32_16x16x32_bf16 v[40:43], v[152:155], v[176:179], 0
	v_mfma_f32_16x16x32_bf16 v[104:107], v[144:147], v[226:229], 0
	v_mfma_f32_16x16x32_bf16 v[32:35], v[152:155], v[226:229], 0
	v_mfma_f32_16x16x32_bf16 v[128:131], v[148:151], v[164:167], v[128:131]
	v_mfma_f32_16x16x32_bf16 v[56:59], v[156:159], v[164:167], v[56:59]
	v_mfma_f32_16x16x32_bf16 v[120:123], v[148:151], v[172:175], v[120:123]
	v_mfma_f32_16x16x32_bf16 v[48:51], v[156:159], v[172:175], v[48:51]
	v_mfma_f32_16x16x32_bf16 v[112:115], v[148:151], v[180:183], v[112:115]
	v_mfma_f32_16x16x32_bf16 v[40:43], v[156:159], v[180:183], v[40:43]
	v_mfma_f32_16x16x32_bf16 v[104:107], v[148:151], v[230:233], v[104:107]
	v_mfma_f32_16x16x32_bf16 v[32:35], v[156:159], v[230:233], v[32:35]
	s_barrier
	s_setprio 0
	s_mov_b32 m0, s39
	v_lshl_add_u64 v[184:185], s[0:1], 0, v[188:189]
	s_add_u32 s4, s0, 0x40000
	ds_read_b128 v[160:163], v206 offset:16384
	ds_read_b128 v[164:167], v206 offset:17408
	ds_read_b128 v[168:171], v206 offset:18432
	ds_read_b128 v[172:175], v206 offset:19456
	ds_read_b128 v[176:179], v206 offset:20480
	ds_read_b128 v[180:183], v206 offset:21504
	ds_read_b128 v[226:229], v206 offset:22528
	ds_read_b128 v[230:233], v206 offset:23552
	global_load_lds_dwordx4 v[184:185], off
	v_lshl_add_u64 v[202:203], s[0:1], 0, v[192:193]
	s_mov_b32 m0, s41
	s_addc_u32 s5, s1, 0
	global_load_lds_dwordx4 v[202:203], off
	v_lshl_add_u64 v[234:235], s[4:5], 0, v[188:189]
	s_mov_b32 m0, s47
	v_lshl_add_u64 v[236:237], s[10:11], 0, v[190:191]
	global_load_lds_dwordx4 v[234:235], off
	v_lshl_add_u64 v[234:235], s[4:5], 0, v[192:193]
	s_mov_b32 m0, s48
	s_nop 0
	global_load_lds_dwordx4 v[234:235], off
	v_lshl_add_u64 v[234:235], s[10:11], 0, v[186:187]
	s_mov_b32 m0, s46
	s_nop 0
	global_load_lds_dwordx4 v[234:235], off
	s_mov_b32 m0, s49
	s_nop 0
	global_load_lds_dwordx4 v[236:237], off
	s_waitcnt vmcnt(8)
	s_waitcnt lgkmcnt(0)
	s_setprio 1
	s_barrier
; #define PG8_STAGE(bufoff, gbase, voff) do { _Pragma("unroll") for (int _i = 0; _i < 2; ++_i) \
;         __builtin_amdgcn_global_load_lds((const unsigned*)((const char*)(gbase) + (voff)[_i]), (PG8_LAS unsigned*)(lds + (bufoff) + ldsw + _i * 8192), 16, 0, 0); } while (0)
; #define PG8_LDA(dst, b, h) do { _Pragma("unroll") for (int m = 0; m < 4; ++m) _Pragma("unroll") for (int k = 0; k < 2; ++k) dst[m][k] = *(const PG8_LAS bf16x8*)(lds + PG8_SA(b, h) + aoff + m * 2048 + k * 1024); } while (0)
; #define PG8_LDB(dst, b, h) do { _Pragma("unroll") for (int n = 0; n < 2; ++n) _Pragma("unroll") for (int k = 0; k < 2; ++k) dst[n][k] = *(const PG8_LAS bf16x8*)(lds + PG8_SB(b, h) + boff + n * 2048 + k * 1024); } while (0)
; #define PG8_MMA(ai, bj, At, Bt) do { __builtin_amdgcn_s_setprio(1); _Pragma("unroll") for (int m = 0; m < 4; ++m) _Pragma("unroll") for (int n = 0; n < 2; ++n) _Pragma("unroll") for (int k = 0; k < 2; ++k) \
;         acc[ai][bj][m][n] = __builtin_amdgcn_mfma_f32_16x16x32_bf16(Bt[n][k], At[m][k], acc[ai][bj][m][n], 0, 0, 0); __builtin_amdgcn_s_setprio(0); } while (0)
; #define PG8_WAIT_V(n) asm volatile("s_waitcnt vmcnt(" #n ")" ::: "memory")
; #define PG8_WAIT_L(n) asm volatile("s_waitcnt lgkmcnt(" #n ")" ::: "memory")
; #define PG8_BAR __builtin_amdgcn_s_barrier()
; #define PG8_SCHED __builtin_amdgcn_sched_barrier(0)
; template <class Epi, class Sched, bool ALIGN_EPI = false, bool SP2 = false>
; __device__ __forceinline__ void gemm_phase(PG8_LAS unsigned char* lds, const Gemm g, const Sched& S, const Epi& E, const int tid_arg) {
;     ...
;             PG8_WAIT_V(8); PG8_WAIT_L(0); PG8_BAR; PG8_MMA(1, 0, At, B0); PG8_MMA(1, 1, At, B1); PG8_BAR; PG8_SCHED;
;             PG8_LDB(B0, 1, 0); PG8_LDB(B1, 1, 1); PG8_SCHED; PG8_LDA(At, 1, 0); PG8_STAGE(PG8_SA(0, 1), a2 + hstep, voffA);
;             PG8_WAIT_V(8); PG8_WAIT_L(0); PG8_BAR; PG8_MMA(0, 0, At, B0); PG8_MMA(0, 1, At, B1); PG8_BAR; PG8_SCHED;
	v_mfma_f32_16x16x32_bf16 v[96:99], v[72:75], v[160:163], 0
	v_mfma_f32_16x16x32_bf16 v[28:31], v[136:139], v[160:163], 0
	v_mfma_f32_16x16x32_bf16 v[88:91], v[72:75], v[168:171], 0
	v_mfma_f32_16x16x32_bf16 v[20:23], v[136:139], v[168:171], 0
	v_mfma_f32_16x16x32_bf16 v[80:83], v[72:75], v[176:179], 0
	v_mfma_f32_16x16x32_bf16 v[12:15], v[136:139], v[176:179], 0
	v_mfma_f32_16x16x32_bf16 v[68:71], v[72:75], v[226:229], 0
	v_mfma_f32_16x16x32_bf16 v[4:7], v[136:139], v[226:229], 0
	v_mfma_f32_16x16x32_bf16 v[96:99], v[100:103], v[164:167], v[96:99]
	v_mfma_f32_16x16x32_bf16 v[28:31], v[140:143], v[164:167], v[28:31]
	v_mfma_f32_16x16x32_bf16 v[88:91], v[100:103], v[172:175], v[88:91]
	v_mfma_f32_16x16x32_bf16 v[20:23], v[140:143], v[172:175], v[20:23]
	v_mfma_f32_16x16x32_bf16 v[80:83], v[100:103], v[180:183], v[80:83]
	v_mfma_f32_16x16x32_bf16 v[12:15], v[140:143], v[180:183], v[12:15]
	v_mfma_f32_16x16x32_bf16 v[68:71], v[100:103], v[230:233], v[68:71]
	v_mfma_f32_16x16x32_bf16 v[4:7], v[140:143], v[230:233], v[4:7]
	s_setprio 0
	s_setprio 1
	v_mfma_f32_16x16x32_bf16 v[24:27], v[152:155], v[160:163], 0
	v_mfma_f32_16x16x32_bf16 v[84:87], v[144:147], v[168:171], 0
	v_mfma_f32_16x16x32_bf16 v[16:19], v[152:155], v[168:171], 0
	v_mfma_f32_16x16x32_bf16 v[76:79], v[144:147], v[176:179], 0
	v_mfma_f32_16x16x32_bf16 v[8:11], v[152:155], v[176:179], 0
	v_mfma_f32_16x16x32_bf16 v[64:67], v[144:147], v[226:229], 0
	v_mfma_f32_16x16x32_bf16 v[0:3], v[152:155], v[226:229], 0
	v_mfma_f32_16x16x32_bf16 v[72:75], v[144:147], v[160:163], 0
	v_mfma_f32_16x16x32_bf16 v[24:27], v[156:159], v[164:167], v[24:27]
	v_mfma_f32_16x16x32_bf16 v[84:87], v[148:151], v[172:175], v[84:87]
	v_mfma_f32_16x16x32_bf16 v[16:19], v[156:159], v[172:175], v[16:19]
	v_mfma_f32_16x16x32_bf16 v[76:79], v[148:151], v[180:183], v[76:79]
	v_mfma_f32_16x16x32_bf16 v[8:11], v[156:159], v[180:183], v[8:11]
	v_mfma_f32_16x16x32_bf16 v[64:67], v[148:151], v[230:233], v[64:67]
	v_mfma_f32_16x16x32_bf16 v[0:3], v[156:159], v[230:233], v[0:3]
	v_mfma_f32_16x16x32_bf16 v[72:75], v[148:151], v[164:167], v[72:75]
	s_barrier
	s_setprio 0
	ds_read_b128 v[92:95], v215
	ds_read_b128 v[100:103], v216
	ds_read_b128 v[136:139], v217
	ds_read_b128 v[140:143], v218
	ds_read_b128 v[144:147], v219
	ds_read_b128 v[148:151], v220
	ds_read_b128 v[152:155], v221
	ds_read_b128 v[156:159], v222
	s_add_u32 s4, s10, 0x40000
	s_addc_u32 s5, s11, 0
	s_mov_b32 m0, s50
	v_lshl_add_u64 v[238:239], s[4:5], 0, v[186:187]
	ds_read_b128 v[160:163], v206 offset:32768
	ds_read_b128 v[164:167], v206 offset:33792
	ds_read_b128 v[168:171], v206 offset:34816
	ds_read_b128 v[172:175], v206 offset:35840
	ds_read_b128 v[176:179], v206 offset:36864
	ds_read_b128 v[180:183], v206 offset:37888
	ds_read_b128 v[226:229], v206 offset:38912
	ds_read_b128 v[230:233], v206 offset:39936
	global_load_lds_dwordx4 v[238:239], off
	v_lshl_add_u64 v[238:239], s[4:5], 0, v[190:191]
	s_mov_b32 m0, s51
	s_nop 0
	global_load_lds_dwordx4 v[238:239], off
	s_waitcnt vmcnt(8)
	s_waitcnt lgkmcnt(0)
	s_setprio 1
	s_barrier
	v_mfma_f32_16x16x32_bf16 v[132:135], v[92:95], v[160:163], v[132:135]
	v_mfma_f32_16x16x32_bf16 v[60:63], v[136:139], v[160:163], v[60:63]
	v_mfma_f32_16x16x32_bf16 v[124:127], v[92:95], v[168:171], v[124:127]
	v_mfma_f32_16x16x32_bf16 v[52:55], v[136:139], v[168:171], v[52:55]
	v_mfma_f32_16x16x32_bf16 v[116:119], v[92:95], v[176:179], v[116:119]
	v_mfma_f32_16x16x32_bf16 v[44:47], v[136:139], v[176:179], v[44:47]
	v_mfma_f32_16x16x32_bf16 v[108:111], v[92:95], v[226:229], v[108:111]
	v_mfma_f32_16x16x32_bf16 v[36:39], v[136:139], v[226:229], v[36:39]
	v_mfma_f32_16x16x32_bf16 v[132:135], v[100:103], v[164:167], v[132:135]
	v_mfma_f32_16x16x32_bf16 v[60:63], v[140:143], v[164:167], v[60:63]
	v_mfma_f32_16x16x32_bf16 v[124:127], v[100:103], v[172:175], v[124:127]
	v_mfma_f32_16x16x32_bf16 v[52:55], v[140:143], v[172:175], v[52:55]
	v_mfma_f32_16x16x32_bf16 v[116:119], v[100:103], v[180:183], v[116:119]
	v_mfma_f32_16x16x32_bf16 v[44:47], v[140:143], v[180:183], v[44:47]
	v_mfma_f32_16x16x32_bf16 v[108:111], v[100:103], v[230:233], v[108:111]
	v_mfma_f32_16x16x32_bf16 v[36:39], v[140:143], v[230:233], v[36:39]
	s_setprio 0
	s_setprio 1
	v_mfma_f32_16x16x32_bf16 v[128:131], v[144:147], v[160:163], v[128:131]
	v_mfma_f32_16x16x32_bf16 v[56:59], v[152:155], v[160:163], v[56:59]
	v_mfma_f32_16x16x32_bf16 v[120:123], v[144:147], v[168:171], v[120:123]
	v_mfma_f32_16x16x32_bf16 v[48:51], v[152:155], v[168:171], v[48:51]
	v_mfma_f32_16x16x32_bf16 v[112:115], v[144:147], v[176:179], v[112:115]
	v_mfma_f32_16x16x32_bf16 v[40:43], v[152:155], v[176:179], v[40:43]
	v_mfma_f32_16x16x32_bf16 v[104:107], v[144:147], v[226:229], v[104:107]
	v_mfma_f32_16x16x32_bf16 v[32:35], v[152:155], v[226:229], v[32:35]
	v_mfma_f32_16x16x32_bf16 v[128:131], v[148:151], v[164:167], v[128:131]
	v_mfma_f32_16x16x32_bf16 v[56:59], v[156:159], v[164:167], v[56:59]
	v_mfma_f32_16x16x32_bf16 v[120:123], v[148:151], v[172:175], v[120:123]
	v_mfma_f32_16x16x32_bf16 v[48:51], v[156:159], v[172:175], v[48:51]
	v_mfma_f32_16x16x32_bf16 v[112:115], v[148:151], v[180:183], v[112:115]
	v_mfma_f32_16x16x32_bf16 v[40:43], v[156:159], v[180:183], v[40:43]
	v_mfma_f32_16x16x32_bf16 v[104:107], v[148:151], v[230:233], v[104:107]
	v_mfma_f32_16x16x32_bf16 v[32:35], v[156:159], v[230:233], v[32:35]
	s_barrier
; #define PG8_STAGE(bufoff, gbase, voff) do { _Pragma("unroll") for (int _i = 0; _i < 2; ++_i) \
;         __builtin_amdgcn_global_load_lds((const unsigned*)((const char*)(gbase) + (voff)[_i]), (PG8_LAS unsigned*)(lds + (bufoff) + ldsw + _i * 8192), 16, 0, 0); } while (0)
; #define PG8_LDA(dst, b, h) do { _Pragma("unroll") for (int m = 0; m < 4; ++m) _Pragma("unroll") for (int k = 0; k < 2; ++k) dst[m][k] = *(const PG8_LAS bf16x8*)(lds + PG8_SA(b, h) + aoff + m * 2048 + k * 1024); } while (0)
; #define PG8_MMA(ai, bj, At, Bt) do { __builtin_amdgcn_s_setprio(1); _Pragma("unroll") for (int m = 0; m < 4; ++m) _Pragma("unroll") for (int n = 0; n < 2; ++n) _Pragma("unroll") for (int k = 0; k < 2; ++k) \
;         acc[ai][bj][m][n] = __builtin_amdgcn_mfma_f32_16x16x32_bf16(Bt[n][k], At[m][k], acc[ai][bj][m][n], 0, 0, 0); __builtin_amdgcn_s_setprio(0); } while (0)
; #define PG8_WAIT_V(n) asm volatile("s_waitcnt vmcnt(" #n ")" ::: "memory")
; #define PG8_WAIT_L(n) asm volatile("s_waitcnt lgkmcnt(" #n ")" ::: "memory")
; #define PG8_BAR __builtin_amdgcn_s_barrier()
; #define PG8_SCHED __builtin_amdgcn_sched_barrier(0)
; template <class Epi, class Sched, bool ALIGN_EPI = false, bool SP2 = false>
; __device__ __forceinline__ void gemm_phase(PG8_LAS unsigned char* lds, const Gemm g, const Sched& S, const Epi& E, const int tid_arg) {
;     ...
;         for (int t = 0; t < nt; t += 2) {
;     ...
;             PG8_LDA(At, 1, 1); PG8_STAGE(PG8_SB(1, 0), b3, voffB); PG8_STAGE(PG8_SB(1, 1), b3 + hstep, voffB); PG8_STAGE(PG8_SA(1, 0), a3, voffA);
;             PG8_WAIT_V(8); PG8_WAIT_L(0); PG8_BAR; PG8_MMA(1, 0, At, B0); PG8_MMA(1, 1, At, B1); PG8_BAR; PG8_SCHED;
	s_setprio 0
	s_mov_b32 m0, s60
	v_lshl_add_u64 v[184:185], v[184:185], 0, s[20:21]
	s_add_u32 s0, s0, 0x40080
	ds_read_b128 v[160:163], v206 offset:49152
	ds_read_b128 v[164:167], v206 offset:50176
	ds_read_b128 v[168:171], v206 offset:51200
	ds_read_b128 v[172:175], v206 offset:52224
	ds_read_b128 v[176:179], v206 offset:53248
	ds_read_b128 v[180:183], v206 offset:54272
	ds_read_b128 v[226:229], v206 offset:55296
	ds_read_b128 v[230:233], v206 offset:56320
	global_load_lds_dwordx4 v[184:185], off
	v_lshl_add_u64 v[184:185], v[202:203], 0, s[20:21]
	s_mov_b32 m0, s61
	s_addc_u32 s1, s1, 0
	global_load_lds_dwordx4 v[184:185], off
	v_lshl_add_u64 v[184:185], s[0:1], 0, v[188:189]
	s_mov_b32 m0, s64
	s_nop 0
	global_load_lds_dwordx4 v[184:185], off
	v_lshl_add_u64 v[184:185], s[0:1], 0, v[192:193]
	s_mov_b32 m0, s65
	s_nop 0
	global_load_lds_dwordx4 v[184:185], off
	v_lshl_add_u64 v[184:185], v[234:235], 0, s[20:21]
	s_mov_b32 m0, s62
	s_nop 0
	global_load_lds_dwordx4 v[184:185], off
	v_lshl_add_u64 v[184:185], v[236:237], 0, s[20:21]
	s_mov_b32 m0, s63
	s_nop 0
	global_load_lds_dwordx4 v[184:185], off
	s_waitcnt vmcnt(8)
	s_waitcnt lgkmcnt(0)
	s_setprio 1
	s_barrier
	v_mfma_f32_16x16x32_bf16 v[96:99], v[92:95], v[160:163], v[96:99]
	v_mfma_f32_16x16x32_bf16 v[28:31], v[136:139], v[160:163], v[28:31]
	v_mfma_f32_16x16x32_bf16 v[88:91], v[92:95], v[168:171], v[88:91]
	v_mfma_f32_16x16x32_bf16 v[20:23], v[136:139], v[168:171], v[20:23]
	v_mfma_f32_16x16x32_bf16 v[80:83], v[92:95], v[176:179], v[80:83]
	v_mfma_f32_16x16x32_bf16 v[12:15], v[136:139], v[176:179], v[12:15]
	v_mfma_f32_16x16x32_bf16 v[68:71], v[92:95], v[226:229], v[68:71]
	v_mfma_f32_16x16x32_bf16 v[4:7], v[136:139], v[226:229], v[4:7]
	v_mfma_f32_16x16x32_bf16 v[96:99], v[100:103], v[164:167], v[96:99]
	v_mfma_f32_16x16x32_bf16 v[28:31], v[140:143], v[164:167], v[28:31]
	v_mfma_f32_16x16x32_bf16 v[88:91], v[100:103], v[172:175], v[88:91]
	v_mfma_f32_16x16x32_bf16 v[20:23], v[140:143], v[172:175], v[20:23]
	v_mfma_f32_16x16x32_bf16 v[80:83], v[100:103], v[180:183], v[80:83]
	v_mfma_f32_16x16x32_bf16 v[12:15], v[140:143], v[180:183], v[12:15]
	v_mfma_f32_16x16x32_bf16 v[68:71], v[100:103], v[230:233], v[68:71]
	v_mfma_f32_16x16x32_bf16 v[4:7], v[140:143], v[230:233], v[4:7]
	s_setprio 0
	s_setprio 1
	v_mfma_f32_16x16x32_bf16 v[72:75], v[144:147], v[160:163], v[72:75]
	v_mfma_f32_16x16x32_bf16 v[92:95], v[148:151], v[164:167], v[72:75]
	v_mfma_f32_16x16x32_bf16 v[72:75], v[144:147], v[168:171], v[84:87]
	v_mfma_f32_16x16x32_bf16 v[24:27], v[152:155], v[160:163], v[24:27]
	v_mfma_f32_16x16x32_bf16 v[84:87], v[148:151], v[172:175], v[72:75]
	v_mfma_f32_16x16x32_bf16 v[16:19], v[152:155], v[168:171], v[16:19]
	v_mfma_f32_16x16x32_bf16 v[72:75], v[144:147], v[176:179], v[76:79]
	v_mfma_f32_16x16x32_bf16 v[8:11], v[152:155], v[176:179], v[8:11]
	v_mfma_f32_16x16x32_bf16 v[64:67], v[144:147], v[226:229], v[64:67]
	v_mfma_f32_16x16x32_bf16 v[0:3], v[152:155], v[226:229], v[0:3]
	v_mfma_f32_16x16x32_bf16 v[24:27], v[156:159], v[164:167], v[24:27]
	v_mfma_f32_16x16x32_bf16 v[16:19], v[156:159], v[172:175], v[16:19]
	v_mfma_f32_16x16x32_bf16 v[76:79], v[148:151], v[180:183], v[72:75]
	v_mfma_f32_16x16x32_bf16 v[8:11], v[156:159], v[180:183], v[8:11]
	v_mfma_f32_16x16x32_bf16 v[64:67], v[148:151], v[230:233], v[64:67]
	v_mfma_f32_16x16x32_bf16 v[0:3], v[156:159], v[230:233], v[0:3]
	s_barrier
	s_setprio 0
	s_add_i32 s78, s78, 2
	s_add_u32 s43, s43, 0x100
	s_addc_u32 s75, s75, 0
	s_cmp_gt_u32 s78, 13
	s_mov_b64 s[4:5], s[6:7]
	s_cbranch_scc0 .LBB0_1547
	s_branch .Lkpeel_exit_9

; #define PG8_STAGE(bufoff, gbase, voff) do { _Pragma("unroll") for (int _i = 0; _i < 2; ++_i) \
;         __builtin_amdgcn_global_load_lds((const unsigned*)((const char*)(gbase) + (voff)[_i]), (PG8_LAS unsigned*)(lds + (bufoff) + ldsw + _i * 8192), 16, 0, 0); } while (0)
; #define PG8_LDA(dst, b, h) do { _Pragma("unroll") for (int m = 0; m < 4; ++m) _Pragma("unroll") for (int k = 0; k < 2; ++k) dst[m][k] = *(const PG8_LAS bf16x8*)(lds + PG8_SA(b, h) + aoff + m * 2048 + k * 1024); } while (0)
; #define PG8_LDB(dst, b, h) do { _Pragma("unroll") for (int n = 0; n < 2; ++n) _Pragma("unroll") for (int k = 0; k < 2; ++k) dst[n][k] = *(const PG8_LAS bf16x8*)(lds + PG8_SB(b, h) + boff + n * 2048 + k * 1024); } while (0)
; #define PG8_MMA(ai, bj, At, Bt) do { __builtin_amdgcn_s_setprio(1); _Pragma("unroll") for (int m = 0; m < 4; ++m) _Pragma("unroll") for (int n = 0; n < 2; ++n) _Pragma("unroll") for (int k = 0; k < 2; ++k) \
;         acc[ai][bj][m][n] = __builtin_amdgcn_mfma_f32_16x16x32_bf16(Bt[n][k], At[m][k], acc[ai][bj][m][n], 0, 0, 0); __builtin_amdgcn_s_setprio(0); } while (0)
; #define PG8_WAIT_V(n) asm volatile("s_waitcnt vmcnt(" #n ")" ::: "memory")
; #define PG8_WAIT_L(n) asm volatile("s_waitcnt lgkmcnt(" #n ")" ::: "memory")
; #define PG8_BAR __builtin_amdgcn_s_barrier()
; #define PG8_SCHED __builtin_amdgcn_sched_barrier(0)
; template <class Epi, class Sched, bool ALIGN_EPI = false, bool SP2 = false>
; __device__ __forceinline__ void gemm_phase(PG8_LAS unsigned char* lds, const Gemm g, const Sched& S, const Epi& E, const int tid_arg) {
;     ...
;             PG8_LDB(B0, 0, 0); PG8_LDB(B1, 0, 1); PG8_SCHED; PG8_LDA(At, 0, 0); PG8_STAGE(PG8_SA(1, 1), a1 + hstep, voffA);
;             PG8_WAIT_V(8); PG8_WAIT_L(0); PG8_BAR; PG8_MMA(0, 0, At, B0); PG8_MMA(0, 1, At, B1); PG8_BAR; PG8_SCHED;
;             PG8_LDA(At, 0, 1); PG8_STAGE(PG8_SB(0, 0), b2, voffB); PG8_STAGE(PG8_SB(0, 1), b2 + hstep, voffB); PG8_STAGE(PG8_SA(0, 0), a2, voffA);
;             PG8_WAIT_V(8); PG8_WAIT_L(0); PG8_BAR; PG8_MMA(1, 0, At, B0); PG8_MMA(1, 1, At, B1); PG8_BAR; PG8_SCHED;
.LBB0_1732:
	s_add_u32 s55, s22, 0x100
	v_mov_b32_e32 v0, 0
	s_addc_u32 s56, s23, 0
	s_mov_b32 s57, -2
	ds_read_b128 v[144:147], v151
	ds_read_b128 v[168:171], v152
	ds_read_b128 v[172:175], v153
	ds_read_b128 v[176:179], v154
	ds_read_b128 v[180:183], v155
	ds_read_b128 v[184:187], v156
	ds_read_b128 v[188:191], v157
	ds_read_b128 v[192:195], v158
	s_add_u32 s22, s4, 0x100
	s_addc_u32 s23, s5, 0
	s_cmp_eq_u32 s57, 40
	s_cselect_b32 s25, s9, s23
	s_cselect_b32 s24, s8, s22
	s_cselect_b32 s1, s21, s56
	s_cselect_b32 s0, s20, s55
	s_mov_b32 m0, s48
	v_lshl_add_u64 v[228:229], s[4:5], 0, v[138:139]
	ds_read_b128 v[196:199], v150
	ds_read_b128 v[200:203], v150 offset:1024
	ds_read_b128 v[204:207], v150 offset:2048
	ds_read_b128 v[208:211], v150 offset:3072
	ds_read_b128 v[212:215], v150 offset:4096
	ds_read_b128 v[216:219], v150 offset:5120
	ds_read_b128 v[220:223], v150 offset:6144
	ds_read_b128 v[224:227], v150 offset:7168
	global_load_lds_dwordx4 v[228:229], off
	v_lshl_add_u64 v[228:229], s[4:5], 0, v[136:137]
	s_mov_b32 m0, s49
	s_nop 0
	global_load_lds_dwordx4 v[228:229], off
	s_waitcnt vmcnt(8)
	s_waitcnt lgkmcnt(0)
	s_setprio 1
	s_barrier
	v_mfma_f32_16x16x32_bf16 v[124:127], v[144:147], v[196:199], 0
	v_mfma_f32_16x16x32_bf16 v[120:123], v[172:175], v[196:199], 0
	v_mfma_f32_16x16x32_bf16 v[108:111], v[144:147], v[204:207], 0
	v_mfma_f32_16x16x32_bf16 v[104:107], v[172:175], v[204:207], 0
	v_mfma_f32_16x16x32_bf16 v[92:95], v[144:147], v[212:215], 0
	v_mfma_f32_16x16x32_bf16 v[88:91], v[172:175], v[212:215], 0
	v_mfma_f32_16x16x32_bf16 v[76:79], v[144:147], v[220:223], 0
	v_mfma_f32_16x16x32_bf16 v[72:75], v[172:175], v[220:223], 0
	v_mfma_f32_16x16x32_bf16 v[124:127], v[168:171], v[200:203], v[124:127]
	v_mfma_f32_16x16x32_bf16 v[120:123], v[176:179], v[200:203], v[120:123]
	v_mfma_f32_16x16x32_bf16 v[108:111], v[168:171], v[208:211], v[108:111]
	v_mfma_f32_16x16x32_bf16 v[104:107], v[176:179], v[208:211], v[104:107]
	v_mfma_f32_16x16x32_bf16 v[92:95], v[168:171], v[216:219], v[92:95]
	v_mfma_f32_16x16x32_bf16 v[88:91], v[176:179], v[216:219], v[88:91]
	v_mfma_f32_16x16x32_bf16 v[76:79], v[168:171], v[224:227], v[76:79]
	v_mfma_f32_16x16x32_bf16 v[72:75], v[176:179], v[224:227], v[72:75]
	s_setprio 0
	s_setprio 1
	v_mfma_f32_16x16x32_bf16 v[116:119], v[180:183], v[196:199], 0
	v_mfma_f32_16x16x32_bf16 v[112:115], v[188:191], v[196:199], 0
	v_mfma_f32_16x16x32_bf16 v[100:103], v[180:183], v[204:207], 0
	v_mfma_f32_16x16x32_bf16 v[96:99], v[188:191], v[204:207], 0
	v_mfma_f32_16x16x32_bf16 v[84:87], v[180:183], v[212:215], 0
	v_mfma_f32_16x16x32_bf16 v[80:83], v[188:191], v[212:215], 0
	v_mfma_f32_16x16x32_bf16 v[68:71], v[180:183], v[220:223], 0
	v_mfma_f32_16x16x32_bf16 v[64:67], v[188:191], v[220:223], 0
	v_mfma_f32_16x16x32_bf16 v[116:119], v[184:187], v[200:203], v[116:119]
	v_mfma_f32_16x16x32_bf16 v[112:115], v[192:195], v[200:203], v[112:115]
	v_mfma_f32_16x16x32_bf16 v[100:103], v[184:187], v[208:211], v[100:103]
	v_mfma_f32_16x16x32_bf16 v[96:99], v[192:195], v[208:211], v[96:99]
	v_mfma_f32_16x16x32_bf16 v[84:87], v[184:187], v[216:219], v[84:87]
	v_mfma_f32_16x16x32_bf16 v[80:83], v[192:195], v[216:219], v[80:83]
	v_mfma_f32_16x16x32_bf16 v[68:71], v[184:187], v[224:227], v[68:71]
	v_mfma_f32_16x16x32_bf16 v[64:67], v[192:195], v[224:227], v[64:67]
	s_barrier
	s_setprio 0
	s_mov_b32 m0, s29
	v_lshl_add_u64 v[228:229], s[0:1], 0, v[130:131]
	s_add_u32 s4, s0, 0xb0000
	ds_read_b128 v[196:199], v150 offset:16384
	ds_read_b128 v[200:203], v150 offset:17408
	ds_read_b128 v[204:207], v150 offset:18432
	ds_read_b128 v[208:211], v150 offset:19456
	ds_read_b128 v[212:215], v150 offset:20480
	ds_read_b128 v[216:219], v150 offset:21504
	ds_read_b128 v[220:223], v150 offset:22528
	ds_read_b128 v[224:227], v150 offset:23552
	global_load_lds_dwordx4 v[228:229], off
	v_lshl_add_u64 v[230:231], s[0:1], 0, v[134:135]
	s_mov_b32 m0, s30
	s_addc_u32 s5, s1, 0
	global_load_lds_dwordx4 v[230:231], off
	v_lshl_add_u64 v[232:233], s[4:5], 0, v[130:131]
	s_mov_b32 m0, s31
	v_lshl_add_u64 v[234:235], s[24:25], 0, v[132:133]
	global_load_lds_dwordx4 v[232:233], off
	v_lshl_add_u64 v[232:233], s[4:5], 0, v[134:135]
	s_mov_b32 m0, s33
	s_nop 0
	global_load_lds_dwordx4 v[232:233], off
	v_lshl_add_u64 v[232:233], s[24:25], 0, v[128:129]
	s_mov_b32 m0, s28
	s_nop 0
	global_load_lds_dwordx4 v[232:233], off
	s_mov_b32 m0, s34
	s_nop 0
	global_load_lds_dwordx4 v[234:235], off
	s_waitcnt vmcnt(8)
	s_waitcnt lgkmcnt(0)
	s_setprio 1
	s_barrier
	v_mfma_f32_16x16x32_bf16 v[60:63], v[144:147], v[196:199], 0
	v_mfma_f32_16x16x32_bf16 v[56:59], v[172:175], v[196:199], 0
	v_mfma_f32_16x16x32_bf16 v[44:47], v[144:147], v[204:207], 0
	v_mfma_f32_16x16x32_bf16 v[40:43], v[172:175], v[204:207], 0
	v_mfma_f32_16x16x32_bf16 v[28:31], v[144:147], v[212:215], 0
	v_mfma_f32_16x16x32_bf16 v[24:27], v[172:175], v[212:215], 0
	v_mfma_f32_16x16x32_bf16 v[12:15], v[144:147], v[220:223], 0
	v_mfma_f32_16x16x32_bf16 v[8:11], v[172:175], v[220:223], 0
	v_mfma_f32_16x16x32_bf16 v[60:63], v[168:171], v[200:203], v[60:63]
	v_mfma_f32_16x16x32_bf16 v[56:59], v[176:179], v[200:203], v[56:59]
	v_mfma_f32_16x16x32_bf16 v[44:47], v[168:171], v[208:211], v[44:47]
	v_mfma_f32_16x16x32_bf16 v[40:43], v[176:179], v[208:211], v[40:43]
	v_mfma_f32_16x16x32_bf16 v[28:31], v[168:171], v[216:219], v[28:31]
	v_mfma_f32_16x16x32_bf16 v[24:27], v[176:179], v[216:219], v[24:27]
	v_mfma_f32_16x16x32_bf16 v[12:15], v[168:171], v[224:227], v[12:15]
	v_mfma_f32_16x16x32_bf16 v[8:11], v[176:179], v[224:227], v[8:11]
	s_setprio 0
	s_setprio 1
	v_mfma_f32_16x16x32_bf16 v[52:55], v[180:183], v[196:199], 0
	v_mfma_f32_16x16x32_bf16 v[48:51], v[188:191], v[196:199], 0
	v_mfma_f32_16x16x32_bf16 v[36:39], v[180:183], v[204:207], 0
	v_mfma_f32_16x16x32_bf16 v[32:35], v[188:191], v[204:207], 0
	v_mfma_f32_16x16x32_bf16 v[20:23], v[180:183], v[212:215], 0
	v_mfma_f32_16x16x32_bf16 v[16:19], v[188:191], v[212:215], 0
	v_mfma_f32_16x16x32_bf16 v[4:7], v[180:183], v[220:223], 0
	v_mfma_f32_16x16x32_bf16 v[0:3], v[188:191], v[220:223], 0
	v_mfma_f32_16x16x32_bf16 v[52:55], v[184:187], v[200:203], v[52:55]
	v_mfma_f32_16x16x32_bf16 v[48:51], v[192:195], v[200:203], v[48:51]
	v_mfma_f32_16x16x32_bf16 v[36:39], v[184:187], v[208:211], v[36:39]
	v_mfma_f32_16x16x32_bf16 v[32:35], v[192:195], v[208:211], v[32:35]
	v_mfma_f32_16x16x32_bf16 v[20:23], v[184:187], v[216:219], v[20:23]
	v_mfma_f32_16x16x32_bf16 v[16:19], v[192:195], v[216:219], v[16:19]
	v_mfma_f32_16x16x32_bf16 v[4:7], v[184:187], v[224:227], v[4:7]
	v_mfma_f32_16x16x32_bf16 v[0:3], v[192:195], v[224:227], v[0:3]
	s_barrier
; #define PG8_STAGE(bufoff, gbase, voff) do { _Pragma("unroll") for (int _i = 0; _i < 2; ++_i) \
;         __builtin_amdgcn_global_load_lds((const unsigned*)((const char*)(gbase) + (voff)[_i]), (PG8_LAS unsigned*)(lds + (bufoff) + ldsw + _i * 8192), 16, 0, 0); } while (0)
; #define PG8_LDA(dst, b, h) do { _Pragma("unroll") for (int m = 0; m < 4; ++m) _Pragma("unroll") for (int k = 0; k < 2; ++k) dst[m][k] = *(const PG8_LAS bf16x8*)(lds + PG8_SA(b, h) + aoff + m * 2048 + k * 1024); } while (0)
; #define PG8_LDB(dst, b, h) do { _Pragma("unroll") for (int n = 0; n < 2; ++n) _Pragma("unroll") for (int k = 0; k < 2; ++k) dst[n][k] = *(const PG8_LAS bf16x8*)(lds + PG8_SB(b, h) + boff + n * 2048 + k * 1024); } while (0)
; #define PG8_MMA(ai, bj, At, Bt) do { __builtin_amdgcn_s_setprio(1); _Pragma("unroll") for (int m = 0; m < 4; ++m) _Pragma("unroll") for (int n = 0; n < 2; ++n) _Pragma("unroll") for (int k = 0; k < 2; ++k) \
;         acc[ai][bj][m][n] = __builtin_amdgcn_mfma_f32_16x16x32_bf16(Bt[n][k], At[m][k], acc[ai][bj][m][n], 0, 0, 0); __builtin_amdgcn_s_setprio(0); } while (0)
; #define PG8_WAIT_V(n) asm volatile("s_waitcnt vmcnt(" #n ")" ::: "memory")
; #define PG8_WAIT_L(n) asm volatile("s_waitcnt lgkmcnt(" #n ")" ::: "memory")
; #define PG8_BAR __builtin_amdgcn_s_barrier()
; template <class Epi, class Sched, bool ALIGN_EPI = false, bool SP2 = false>
; __device__ __forceinline__ void gemm_phase(PG8_LAS unsigned char* lds, const Gemm g, const Sched& S, const Epi& E, const int tid_arg) {
;     ...
;         for (int t = 0; t < nt; t += 2) {
;             const bool last = (t == nt - 2);
;             const char* a1 = cA + (size_t)(t + 1) * kstep;
;             const char* a2 = last ? nA : cA + (size_t)(t + 2) * kstep; const char* b2 = last ? nB : cB + (size_t)(t + 2) * kstep;
;             const char* a3 = a2 + kstep; const char* b3 = b2 + kstep;
;     ...
;             PG8_LDB(B0, 1, 0); PG8_LDB(B1, 1, 1); PG8_SCHED; PG8_LDA(At, 1, 0); PG8_STAGE(PG8_SA(0, 1), a2 + hstep, voffA);
;             PG8_WAIT_V(8); PG8_WAIT_L(0); PG8_BAR; PG8_MMA(0, 0, At, B0); PG8_MMA(0, 1, At, B1); PG8_BAR; PG8_SCHED;
;             PG8_LDA(At, 1, 1); PG8_STAGE(PG8_SB(1, 0), b3, voffB); PG8_STAGE(PG8_SB(1, 1), b3 + hstep, voffB); PG8_STAGE(PG8_SA(1, 0), a3, voffA);
;             PG8_WAIT_V(8); PG8_WAIT_L(0); PG8_BAR; PG8_MMA(1, 0, At, B0); PG8_MMA(1, 1, At, B1); PG8_BAR; PG8_SCHED;
	s_setprio 0
	ds_read_b128 v[144:147], v159
	ds_read_b128 v[168:171], v160
	ds_read_b128 v[172:175], v161
	ds_read_b128 v[176:179], v162
	ds_read_b128 v[180:183], v163
	ds_read_b128 v[184:187], v164
	ds_read_b128 v[188:191], v165
	ds_read_b128 v[192:195], v166
	s_add_u32 s4, s24, 0xb0000
	s_addc_u32 s5, s25, 0
	s_mov_b32 m0, s35
	v_lshl_add_u64 v[236:237], s[4:5], 0, v[128:129]
	ds_read_b128 v[196:199], v150 offset:32768
	ds_read_b128 v[200:203], v150 offset:33792
	ds_read_b128 v[204:207], v150 offset:34816
	ds_read_b128 v[208:211], v150 offset:35840
	ds_read_b128 v[212:215], v150 offset:36864
	ds_read_b128 v[216:219], v150 offset:37888
	ds_read_b128 v[220:223], v150 offset:38912
	ds_read_b128 v[224:227], v150 offset:39936
	global_load_lds_dwordx4 v[236:237], off
	v_lshl_add_u64 v[236:237], s[4:5], 0, v[132:133]
	s_mov_b32 m0, s36
	s_nop 0
	global_load_lds_dwordx4 v[236:237], off
	s_waitcnt vmcnt(8)
	s_waitcnt lgkmcnt(0)
	s_setprio 1
	s_barrier
	v_mfma_f32_16x16x32_bf16 v[124:127], v[144:147], v[196:199], v[124:127]
	v_mfma_f32_16x16x32_bf16 v[120:123], v[172:175], v[196:199], v[120:123]
	v_mfma_f32_16x16x32_bf16 v[108:111], v[144:147], v[204:207], v[108:111]
	v_mfma_f32_16x16x32_bf16 v[104:107], v[172:175], v[204:207], v[104:107]
	v_mfma_f32_16x16x32_bf16 v[92:95], v[144:147], v[212:215], v[92:95]
	v_mfma_f32_16x16x32_bf16 v[88:91], v[172:175], v[212:215], v[88:91]
	v_mfma_f32_16x16x32_bf16 v[76:79], v[144:147], v[220:223], v[76:79]
	v_mfma_f32_16x16x32_bf16 v[72:75], v[172:175], v[220:223], v[72:75]
	v_mfma_f32_16x16x32_bf16 v[124:127], v[168:171], v[200:203], v[124:127]
	v_mfma_f32_16x16x32_bf16 v[120:123], v[176:179], v[200:203], v[120:123]
	v_mfma_f32_16x16x32_bf16 v[108:111], v[168:171], v[208:211], v[108:111]
	v_mfma_f32_16x16x32_bf16 v[104:107], v[176:179], v[208:211], v[104:107]
	v_mfma_f32_16x16x32_bf16 v[92:95], v[168:171], v[216:219], v[92:95]
	v_mfma_f32_16x16x32_bf16 v[88:91], v[176:179], v[216:219], v[88:91]
	v_mfma_f32_16x16x32_bf16 v[76:79], v[168:171], v[224:227], v[76:79]
	v_mfma_f32_16x16x32_bf16 v[72:75], v[176:179], v[224:227], v[72:75]
	s_setprio 0
	s_setprio 1
	v_mfma_f32_16x16x32_bf16 v[116:119], v[180:183], v[196:199], v[116:119]
	v_mfma_f32_16x16x32_bf16 v[112:115], v[188:191], v[196:199], v[112:115]
	v_mfma_f32_16x16x32_bf16 v[100:103], v[180:183], v[204:207], v[100:103]
	v_mfma_f32_16x16x32_bf16 v[96:99], v[188:191], v[204:207], v[96:99]
	v_mfma_f32_16x16x32_bf16 v[84:87], v[180:183], v[212:215], v[84:87]
	v_mfma_f32_16x16x32_bf16 v[80:83], v[188:191], v[212:215], v[80:83]
	v_mfma_f32_16x16x32_bf16 v[68:71], v[180:183], v[220:223], v[68:71]
	v_mfma_f32_16x16x32_bf16 v[64:67], v[188:191], v[220:223], v[64:67]
	v_mfma_f32_16x16x32_bf16 v[116:119], v[184:187], v[200:203], v[116:119]
	v_mfma_f32_16x16x32_bf16 v[112:115], v[192:195], v[200:203], v[112:115]
	v_mfma_f32_16x16x32_bf16 v[100:103], v[184:187], v[208:211], v[100:103]
	v_mfma_f32_16x16x32_bf16 v[96:99], v[192:195], v[208:211], v[96:99]
	v_mfma_f32_16x16x32_bf16 v[84:87], v[184:187], v[216:219], v[84:87]
	v_mfma_f32_16x16x32_bf16 v[80:83], v[192:195], v[216:219], v[80:83]
	v_mfma_f32_16x16x32_bf16 v[68:71], v[184:187], v[224:227], v[68:71]
	v_mfma_f32_16x16x32_bf16 v[64:67], v[192:195], v[224:227], v[64:67]
	s_barrier
	s_setprio 0
	s_mov_b32 m0, s40
	v_lshl_add_u64 v[228:229], v[228:229], 0, s[16:17]
	s_add_u32 s0, s0, 0xb0080
	ds_read_b128 v[196:199], v150 offset:49152
	ds_read_b128 v[200:203], v150 offset:50176
	ds_read_b128 v[204:207], v150 offset:51200
	ds_read_b128 v[208:211], v150 offset:52224
	ds_read_b128 v[212:215], v150 offset:53248
	ds_read_b128 v[216:219], v150 offset:54272
	ds_read_b128 v[220:223], v150 offset:55296
	ds_read_b128 v[224:227], v150 offset:56320
	global_load_lds_dwordx4 v[228:229], off
	v_lshl_add_u64 v[228:229], v[230:231], 0, s[16:17]
	s_mov_b32 m0, s41
	s_addc_u32 s1, s1, 0
	global_load_lds_dwordx4 v[228:229], off
	v_lshl_add_u64 v[228:229], s[0:1], 0, v[130:131]
	s_mov_b32 m0, s44
	s_nop 0
	global_load_lds_dwordx4 v[228:229], off
	v_lshl_add_u64 v[228:229], s[0:1], 0, v[134:135]
	s_mov_b32 m0, s45
	s_nop 0
	global_load_lds_dwordx4 v[228:229], off
	v_lshl_add_u64 v[228:229], v[232:233], 0, s[16:17]
	s_mov_b32 m0, s42
	s_nop 0
	global_load_lds_dwordx4 v[228:229], off
	v_lshl_add_u64 v[228:229], v[234:235], 0, s[16:17]
	s_mov_b32 m0, s43
	s_nop 0
	global_load_lds_dwordx4 v[228:229], off
	s_waitcnt vmcnt(8)
	s_waitcnt lgkmcnt(0)
	s_setprio 1
	s_barrier
	v_mfma_f32_16x16x32_bf16 v[60:63], v[144:147], v[196:199], v[60:63]
	v_mfma_f32_16x16x32_bf16 v[56:59], v[172:175], v[196:199], v[56:59]
	v_mfma_f32_16x16x32_bf16 v[44:47], v[144:147], v[204:207], v[44:47]
	v_mfma_f32_16x16x32_bf16 v[40:43], v[172:175], v[204:207], v[40:43]
	v_mfma_f32_16x16x32_bf16 v[28:31], v[144:147], v[212:215], v[28:31]
	v_mfma_f32_16x16x32_bf16 v[24:27], v[172:175], v[212:215], v[24:27]
	v_mfma_f32_16x16x32_bf16 v[12:15], v[144:147], v[220:223], v[12:15]
	v_mfma_f32_16x16x32_bf16 v[8:11], v[172:175], v[220:223], v[8:11]
	v_mfma_f32_16x16x32_bf16 v[60:63], v[168:171], v[200:203], v[60:63]
	v_mfma_f32_16x16x32_bf16 v[56:59], v[176:179], v[200:203], v[56:59]
	v_mfma_f32_16x16x32_bf16 v[44:47], v[168:171], v[208:211], v[44:47]
	v_mfma_f32_16x16x32_bf16 v[40:43], v[176:179], v[208:211], v[40:43]
	v_mfma_f32_16x16x32_bf16 v[28:31], v[168:171], v[216:219], v[28:31]
	v_mfma_f32_16x16x32_bf16 v[24:27], v[176:179], v[216:219], v[24:27]
	v_mfma_f32_16x16x32_bf16 v[12:15], v[168:171], v[224:227], v[12:15]
	v_mfma_f32_16x16x32_bf16 v[8:11], v[176:179], v[224:227], v[8:11]
	s_setprio 0
	s_setprio 1
	v_mfma_f32_16x16x32_bf16 v[52:55], v[180:183], v[196:199], v[52:55]
	v_mfma_f32_16x16x32_bf16 v[48:51], v[188:191], v[196:199], v[48:51]
	v_mfma_f32_16x16x32_bf16 v[36:39], v[180:183], v[204:207], v[36:39]
	v_mfma_f32_16x16x32_bf16 v[32:35], v[188:191], v[204:207], v[32:35]
	v_mfma_f32_16x16x32_bf16 v[20:23], v[180:183], v[212:215], v[20:23]
	v_mfma_f32_16x16x32_bf16 v[16:19], v[188:191], v[212:215], v[16:19]
	v_mfma_f32_16x16x32_bf16 v[4:7], v[180:183], v[220:223], v[4:7]
	v_mfma_f32_16x16x32_bf16 v[0:3], v[188:191], v[220:223], v[0:3]
	v_mfma_f32_16x16x32_bf16 v[52:55], v[184:187], v[200:203], v[52:55]
	v_mfma_f32_16x16x32_bf16 v[48:51], v[192:195], v[200:203], v[48:51]
	v_mfma_f32_16x16x32_bf16 v[36:39], v[184:187], v[208:211], v[36:39]
	v_mfma_f32_16x16x32_bf16 v[32:35], v[192:195], v[208:211], v[32:35]
	v_mfma_f32_16x16x32_bf16 v[20:23], v[184:187], v[216:219], v[20:23]
	v_mfma_f32_16x16x32_bf16 v[16:19], v[192:195], v[216:219], v[16:19]
	v_mfma_f32_16x16x32_bf16 v[4:7], v[184:187], v[224:227], v[4:7]
	v_mfma_f32_16x16x32_bf16 v[0:3], v[192:195], v[224:227], v[0:3]
	s_barrier
	s_setprio 0
	s_add_i32 s57, s57, 2
	s_add_u32 s55, s55, 0x100
	s_addc_u32 s56, s56, 0
	s_cmp_gt_u32 s57, 41
	s_mov_b64 s[4:5], s[22:23]
	s_cbranch_scc0 .LBB0_1733
	s_branch .Lkpeel_exit_10

; #define PG8_STAGE(bufoff, gbase, voff) do { _Pragma("unroll") for (int _i = 0; _i < 2; ++_i) \
;         __builtin_amdgcn_global_load_lds((const unsigned*)((const char*)(gbase) + (voff)[_i]), (PG8_LAS unsigned*)(lds + (bufoff) + ldsw + _i * 8192), 16, 0, 0); } while (0)
; #define PG8_LDA(dst, b, h) do { _Pragma("unroll") for (int m = 0; m < 4; ++m) _Pragma("unroll") for (int k = 0; k < 2; ++k) dst[m][k] = *(const PG8_LAS bf16x8*)(lds + PG8_SA(b, h) + aoff + m * 2048 + k * 1024); } while (0)
; #define PG8_LDB(dst, b, h) do { _Pragma("unroll") for (int n = 0; n < 2; ++n) _Pragma("unroll") for (int k = 0; k < 2; ++k) dst[n][k] = *(const PG8_LAS bf16x8*)(lds + PG8_SB(b, h) + boff + n * 2048 + k * 1024); } while (0)
; #define PG8_MMA(ai, bj, At, Bt) do { __builtin_amdgcn_s_setprio(1); _Pragma("unroll") for (int m = 0; m < 4; ++m) _Pragma("unroll") for (int n = 0; n < 2; ++n) _Pragma("unroll") for (int k = 0; k < 2; ++k) \
;         acc[ai][bj][m][n] = __builtin_amdgcn_mfma_f32_16x16x32_bf16(Bt[n][k], At[m][k], acc[ai][bj][m][n], 0, 0, 0); __builtin_amdgcn_s_setprio(0); } while (0)
; #define PG8_WAIT_V(n) asm volatile("s_waitcnt vmcnt(" #n ")" ::: "memory")
; #define PG8_WAIT_L(n) asm volatile("s_waitcnt lgkmcnt(" #n ")" ::: "memory")
; #define PG8_BAR __builtin_amdgcn_s_barrier()
; #define PG8_SCHED __builtin_amdgcn_sched_barrier(0)
; template <class Epi, class Sched, bool ALIGN_EPI = false, bool SP2 = false>
; __device__ __forceinline__ void gemm_phase(PG8_LAS unsigned char* lds, const Gemm g, const Sched& S, const Epi& E, const int tid_arg) {
;     ...
;         const bool has_next = S.next(ui + 1, nxt);
;         const char* nA = has_next ? (const char*)g.A + (size_t)nxt.pm * tstep : cA; const char* nB = has_next ? (const char*)g.Bt + (size_t)nxt.pn * tstep : cB;
;     ...
;             PG8_LDB(B0, 0, 0); PG8_LDB(B1, 0, 1); PG8_SCHED; PG8_LDA(At, 0, 0); PG8_STAGE(PG8_SA(1, 1), a1 + hstep, voffA);
;             PG8_WAIT_V(8); PG8_WAIT_L(0); PG8_BAR; PG8_MMA(0, 0, At, B0); PG8_MMA(0, 1, At, B1); PG8_BAR; PG8_SCHED;
.LBB0_1826:
	s_ashr_i32 s39, s38, 31
	s_lshl_b64 s[0:1], s[38:39], 19
	s_add_u32 s40, s3, s0
	s_addc_u32 s41, s33, s1
	s_and_b64 s[0:1], s[6:7], exec
	s_cselect_b32 s39, s41, s47
	s_cselect_b32 s75, s40, s46
	s_ashr_i32 s37, s36, 31
	s_lshl_b64 s[0:1], s[36:37], 19
	s_add_u32 s42, s48, s0
	s_addc_u32 s43, s49, s1
	s_and_b64 s[0:1], s[6:7], exec
	s_cselect_b32 s37, s43, s45
	s_cselect_b32 s78, s42, s44
	s_add_u32 s79, s44, 0x100
	s_addc_u32 s80, s45, 0
	s_add_u32 s44, s46, 0x40080
	v_mov_b32_e32 v0, 0
	s_addc_u32 s45, s47, 0
	s_mov_b32 s81, -2
	ds_read_b128 v[170:173], v151
	ds_read_b128 v[174:177], v153
	ds_read_b128 v[178:181], v155
	ds_read_b128 v[182:185], v156
	ds_read_b128 v[186:189], v157
	ds_read_b128 v[190:193], v158
	ds_read_b128 v[194:197], v159
	ds_read_b128 v[198:201], v160
	s_add_u32 s0, s44, 0xfffc0080
	s_addc_u32 s1, s45, -1
	s_cmp_eq_u32 s81, 12
	s_cselect_b32 s47, s39, s1
	s_cselect_b32 s46, s75, s0
	s_cselect_b32 s1, s37, s80
	s_cselect_b32 s0, s78, s79
	s_mov_b32 m0, s67
	v_lshl_add_u64 v[234:235], s[44:45], 0, v[138:139]
	ds_read_b128 v[202:205], v149
	ds_read_b128 v[206:209], v149 offset:1024
	ds_read_b128 v[210:213], v149 offset:2048
	ds_read_b128 v[214:217], v149 offset:3072
	ds_read_b128 v[218:221], v149 offset:4096
	ds_read_b128 v[222:225], v149 offset:5120
	ds_read_b128 v[226:229], v149 offset:6144
	ds_read_b128 v[230:233], v149 offset:7168
	global_load_lds_dwordx4 v[234:235], off
	v_lshl_add_u64 v[234:235], s[44:45], 0, v[136:137]
	s_mov_b32 m0, s68
	s_nop 0
	global_load_lds_dwordx4 v[234:235], off
	s_waitcnt vmcnt(8)
	s_waitcnt lgkmcnt(0)
	s_setprio 1
	s_barrier
	v_mfma_f32_16x16x32_bf16 v[124:127], v[170:173], v[202:205], 0
	v_mfma_f32_16x16x32_bf16 v[120:123], v[178:181], v[202:205], 0
	v_mfma_f32_16x16x32_bf16 v[108:111], v[170:173], v[210:213], 0
	v_mfma_f32_16x16x32_bf16 v[104:107], v[178:181], v[210:213], 0
	v_mfma_f32_16x16x32_bf16 v[92:95], v[170:173], v[218:221], 0
	v_mfma_f32_16x16x32_bf16 v[88:91], v[178:181], v[218:221], 0
	v_mfma_f32_16x16x32_bf16 v[76:79], v[170:173], v[226:229], 0
	v_mfma_f32_16x16x32_bf16 v[72:75], v[178:181], v[226:229], 0
	v_mfma_f32_16x16x32_bf16 v[124:127], v[174:177], v[206:209], v[124:127]
	v_mfma_f32_16x16x32_bf16 v[120:123], v[182:185], v[206:209], v[120:123]
	v_mfma_f32_16x16x32_bf16 v[108:111], v[174:177], v[214:217], v[108:111]
	v_mfma_f32_16x16x32_bf16 v[104:107], v[182:185], v[214:217], v[104:107]
	v_mfma_f32_16x16x32_bf16 v[92:95], v[174:177], v[222:225], v[92:95]
	v_mfma_f32_16x16x32_bf16 v[88:91], v[182:185], v[222:225], v[88:91]
	v_mfma_f32_16x16x32_bf16 v[76:79], v[174:177], v[230:233], v[76:79]
	v_mfma_f32_16x16x32_bf16 v[72:75], v[182:185], v[230:233], v[72:75]
	s_setprio 0
	s_setprio 1
	v_mfma_f32_16x16x32_bf16 v[116:119], v[186:189], v[202:205], 0
	v_mfma_f32_16x16x32_bf16 v[112:115], v[194:197], v[202:205], 0
	v_mfma_f32_16x16x32_bf16 v[100:103], v[186:189], v[210:213], 0
	v_mfma_f32_16x16x32_bf16 v[96:99], v[194:197], v[210:213], 0
	v_mfma_f32_16x16x32_bf16 v[84:87], v[186:189], v[218:221], 0
	v_mfma_f32_16x16x32_bf16 v[80:83], v[194:197], v[218:221], 0
	v_mfma_f32_16x16x32_bf16 v[68:71], v[186:189], v[226:229], 0
	v_mfma_f32_16x16x32_bf16 v[64:67], v[194:197], v[226:229], 0
	v_mfma_f32_16x16x32_bf16 v[116:119], v[190:193], v[206:209], v[116:119]
	v_mfma_f32_16x16x32_bf16 v[112:115], v[198:201], v[206:209], v[112:115]
	v_mfma_f32_16x16x32_bf16 v[100:103], v[190:193], v[214:217], v[100:103]
	v_mfma_f32_16x16x32_bf16 v[96:99], v[198:201], v[214:217], v[96:99]
	v_mfma_f32_16x16x32_bf16 v[84:87], v[190:193], v[222:225], v[84:87]
	v_mfma_f32_16x16x32_bf16 v[80:83], v[198:201], v[222:225], v[80:83]
	v_mfma_f32_16x16x32_bf16 v[68:71], v[190:193], v[230:233], v[68:71]
	v_mfma_f32_16x16x32_bf16 v[64:67], v[198:201], v[230:233], v[64:67]
	s_barrier
	s_setprio 0
	s_mov_b32 m0, s5
	v_lshl_add_u64 v[234:235], s[0:1], 0, v[130:131]
	s_add_u32 s82, s0, 0x40000
	ds_read_b128 v[202:205], v149 offset:16384
	ds_read_b128 v[206:209], v149 offset:17408
	ds_read_b128 v[210:213], v149 offset:18432
	ds_read_b128 v[214:217], v149 offset:19456
	ds_read_b128 v[218:221], v149 offset:20480
	ds_read_b128 v[222:225], v149 offset:21504
	ds_read_b128 v[226:229], v149 offset:22528
	ds_read_b128 v[230:233], v149 offset:23552
	global_load_lds_dwordx4 v[234:235], off
	v_lshl_add_u64 v[236:237], s[0:1], 0, v[134:135]
	s_mov_b32 m0, s51
	s_addc_u32 s83, s1, 0
	global_load_lds_dwordx4 v[236:237], off
	v_lshl_add_u64 v[238:239], s[82:83], 0, v[130:131]
	s_mov_b32 m0, s52
	v_lshl_add_u64 v[240:241], s[46:47], 0, v[132:133]
	global_load_lds_dwordx4 v[238:239], off
	v_lshl_add_u64 v[238:239], s[82:83], 0, v[134:135]
	s_mov_b32 m0, s53
	s_nop 0
	global_load_lds_dwordx4 v[238:239], off
	v_lshl_add_u64 v[238:239], s[46:47], 0, v[128:129]
	s_mov_b32 m0, s50
	s_nop 0
	global_load_lds_dwordx4 v[238:239], off
	s_mov_b32 m0, s54
	s_nop 0
	global_load_lds_dwordx4 v[240:241], off
	s_waitcnt vmcnt(8)
	s_waitcnt lgkmcnt(0)
	s_setprio 1
	s_barrier
; #define PG8_STAGE(bufoff, gbase, voff) do { _Pragma("unroll") for (int _i = 0; _i < 2; ++_i) \
;         __builtin_amdgcn_global_load_lds((const unsigned*)((const char*)(gbase) + (voff)[_i]), (PG8_LAS unsigned*)(lds + (bufoff) + ldsw + _i * 8192), 16, 0, 0); } while (0)
; #define PG8_LDA(dst, b, h) do { _Pragma("unroll") for (int m = 0; m < 4; ++m) _Pragma("unroll") for (int k = 0; k < 2; ++k) dst[m][k] = *(const PG8_LAS bf16x8*)(lds + PG8_SA(b, h) + aoff + m * 2048 + k * 1024); } while (0)
; #define PG8_LDB(dst, b, h) do { _Pragma("unroll") for (int n = 0; n < 2; ++n) _Pragma("unroll") for (int k = 0; k < 2; ++k) dst[n][k] = *(const PG8_LAS bf16x8*)(lds + PG8_SB(b, h) + boff + n * 2048 + k * 1024); } while (0)
; #define PG8_MMA(ai, bj, At, Bt) do { __builtin_amdgcn_s_setprio(1); _Pragma("unroll") for (int m = 0; m < 4; ++m) _Pragma("unroll") for (int n = 0; n < 2; ++n) _Pragma("unroll") for (int k = 0; k < 2; ++k) \
;         acc[ai][bj][m][n] = __builtin_amdgcn_mfma_f32_16x16x32_bf16(Bt[n][k], At[m][k], acc[ai][bj][m][n], 0, 0, 0); __builtin_amdgcn_s_setprio(0); } while (0)
; #define PG8_WAIT_V(n) asm volatile("s_waitcnt vmcnt(" #n ")" ::: "memory")
; #define PG8_WAIT_L(n) asm volatile("s_waitcnt lgkmcnt(" #n ")" ::: "memory")
; #define PG8_BAR __builtin_amdgcn_s_barrier()
; #define PG8_SCHED __builtin_amdgcn_sched_barrier(0)
; template <class Epi, class Sched, bool ALIGN_EPI = false, bool SP2 = false>
; __device__ __forceinline__ void gemm_phase(PG8_LAS unsigned char* lds, const Gemm g, const Sched& S, const Epi& E, const int tid_arg) {
;     ...
;             PG8_WAIT_V(8); PG8_WAIT_L(0); PG8_BAR; PG8_MMA(0, 0, At, B0); PG8_MMA(0, 1, At, B1); PG8_BAR; PG8_SCHED;
;             PG8_LDA(At, 0, 1); PG8_STAGE(PG8_SB(0, 0), b2, voffB); PG8_STAGE(PG8_SB(0, 1), b2 + hstep, voffB); PG8_STAGE(PG8_SA(0, 0), a2, voffA);
;             PG8_WAIT_V(8); PG8_WAIT_L(0); PG8_BAR; PG8_MMA(1, 0, At, B0); PG8_MMA(1, 1, At, B1); PG8_BAR; PG8_SCHED;
;             PG8_LDB(B0, 1, 0); PG8_LDB(B1, 1, 1); PG8_SCHED; PG8_LDA(At, 1, 0); PG8_STAGE(PG8_SA(0, 1), a2 + hstep, voffA);
;             PG8_WAIT_V(8); PG8_WAIT_L(0); PG8_BAR; PG8_MMA(0, 0, At, B0); PG8_MMA(0, 1, At, B1); PG8_BAR; PG8_SCHED;
	v_mfma_f32_16x16x32_bf16 v[60:63], v[170:173], v[202:205], 0
	v_mfma_f32_16x16x32_bf16 v[56:59], v[178:181], v[202:205], 0
	v_mfma_f32_16x16x32_bf16 v[44:47], v[170:173], v[210:213], 0
	v_mfma_f32_16x16x32_bf16 v[40:43], v[178:181], v[210:213], 0
	v_mfma_f32_16x16x32_bf16 v[28:31], v[170:173], v[218:221], 0
	v_mfma_f32_16x16x32_bf16 v[24:27], v[178:181], v[218:221], 0
	v_mfma_f32_16x16x32_bf16 v[12:15], v[170:173], v[226:229], 0
	v_mfma_f32_16x16x32_bf16 v[8:11], v[178:181], v[226:229], 0
	v_mfma_f32_16x16x32_bf16 v[60:63], v[174:177], v[206:209], v[60:63]
	v_mfma_f32_16x16x32_bf16 v[56:59], v[182:185], v[206:209], v[56:59]
	v_mfma_f32_16x16x32_bf16 v[44:47], v[174:177], v[214:217], v[44:47]
	v_mfma_f32_16x16x32_bf16 v[40:43], v[182:185], v[214:217], v[40:43]
	v_mfma_f32_16x16x32_bf16 v[28:31], v[174:177], v[222:225], v[28:31]
	v_mfma_f32_16x16x32_bf16 v[24:27], v[182:185], v[222:225], v[24:27]
	v_mfma_f32_16x16x32_bf16 v[12:15], v[174:177], v[230:233], v[12:15]
	v_mfma_f32_16x16x32_bf16 v[8:11], v[182:185], v[230:233], v[8:11]
	s_setprio 0
	s_setprio 1
	v_mfma_f32_16x16x32_bf16 v[52:55], v[186:189], v[202:205], 0
	v_mfma_f32_16x16x32_bf16 v[48:51], v[194:197], v[202:205], 0
	v_mfma_f32_16x16x32_bf16 v[36:39], v[186:189], v[210:213], 0
	v_mfma_f32_16x16x32_bf16 v[32:35], v[194:197], v[210:213], 0
	v_mfma_f32_16x16x32_bf16 v[20:23], v[186:189], v[218:221], 0
	v_mfma_f32_16x16x32_bf16 v[16:19], v[194:197], v[218:221], 0
	v_mfma_f32_16x16x32_bf16 v[4:7], v[186:189], v[226:229], 0
	v_mfma_f32_16x16x32_bf16 v[0:3], v[194:197], v[226:229], 0
	v_mfma_f32_16x16x32_bf16 v[52:55], v[190:193], v[206:209], v[52:55]
	v_mfma_f32_16x16x32_bf16 v[48:51], v[198:201], v[206:209], v[48:51]
	v_mfma_f32_16x16x32_bf16 v[36:39], v[190:193], v[214:217], v[36:39]
	v_mfma_f32_16x16x32_bf16 v[32:35], v[198:201], v[214:217], v[32:35]
	v_mfma_f32_16x16x32_bf16 v[20:23], v[190:193], v[222:225], v[20:23]
	v_mfma_f32_16x16x32_bf16 v[16:19], v[198:201], v[222:225], v[16:19]
	v_mfma_f32_16x16x32_bf16 v[4:7], v[190:193], v[230:233], v[4:7]
	v_mfma_f32_16x16x32_bf16 v[0:3], v[198:201], v[230:233], v[0:3]
	s_barrier
	s_setprio 0
	ds_read_b128 v[170:173], v161
	ds_read_b128 v[174:177], v162
	ds_read_b128 v[178:181], v163
	ds_read_b128 v[182:185], v164
	ds_read_b128 v[186:189], v165
	ds_read_b128 v[190:193], v166
	ds_read_b128 v[194:197], v167
	ds_read_b128 v[198:201], v168
	s_add_u32 s46, s46, 0x40000
	s_addc_u32 s47, s47, 0
	s_mov_b32 m0, s55
	v_lshl_add_u64 v[242:243], s[46:47], 0, v[128:129]
	ds_read_b128 v[202:205], v149 offset:32768
	ds_read_b128 v[206:209], v149 offset:33792
	ds_read_b128 v[210:213], v149 offset:34816
	ds_read_b128 v[214:217], v149 offset:35840
	ds_read_b128 v[218:221], v149 offset:36864
	ds_read_b128 v[222:225], v149 offset:37888
	ds_read_b128 v[226:229], v149 offset:38912
	ds_read_b128 v[230:233], v149 offset:39936
	global_load_lds_dwordx4 v[242:243], off
	v_lshl_add_u64 v[242:243], s[46:47], 0, v[132:133]
	s_mov_b32 m0, s56
	s_nop 0
	global_load_lds_dwordx4 v[242:243], off
	s_waitcnt vmcnt(8)
	s_waitcnt lgkmcnt(0)
	s_setprio 1
	s_barrier
	v_mfma_f32_16x16x32_bf16 v[124:127], v[170:173], v[202:205], v[124:127]
	v_mfma_f32_16x16x32_bf16 v[120:123], v[178:181], v[202:205], v[120:123]
	v_mfma_f32_16x16x32_bf16 v[108:111], v[170:173], v[210:213], v[108:111]
	v_mfma_f32_16x16x32_bf16 v[104:107], v[178:181], v[210:213], v[104:107]
	v_mfma_f32_16x16x32_bf16 v[92:95], v[170:173], v[218:221], v[92:95]
	v_mfma_f32_16x16x32_bf16 v[88:91], v[178:181], v[218:221], v[88:91]
	v_mfma_f32_16x16x32_bf16 v[76:79], v[170:173], v[226:229], v[76:79]
	v_mfma_f32_16x16x32_bf16 v[72:75], v[178:181], v[226:229], v[72:75]
	v_mfma_f32_16x16x32_bf16 v[124:127], v[174:177], v[206:209], v[124:127]
	v_mfma_f32_16x16x32_bf16 v[120:123], v[182:185], v[206:209], v[120:123]
	v_mfma_f32_16x16x32_bf16 v[108:111], v[174:177], v[214:217], v[108:111]
	v_mfma_f32_16x16x32_bf16 v[104:107], v[182:185], v[214:217], v[104:107]
	v_mfma_f32_16x16x32_bf16 v[92:95], v[174:177], v[222:225], v[92:95]
	v_mfma_f32_16x16x32_bf16 v[88:91], v[182:185], v[222:225], v[88:91]
	v_mfma_f32_16x16x32_bf16 v[76:79], v[174:177], v[230:233], v[76:79]
	v_mfma_f32_16x16x32_bf16 v[72:75], v[182:185], v[230:233], v[72:75]
	s_setprio 0
	s_setprio 1
	v_mfma_f32_16x16x32_bf16 v[116:119], v[186:189], v[202:205], v[116:119]
	v_mfma_f32_16x16x32_bf16 v[112:115], v[194:197], v[202:205], v[112:115]
	v_mfma_f32_16x16x32_bf16 v[100:103], v[186:189], v[210:213], v[100:103]
	v_mfma_f32_16x16x32_bf16 v[96:99], v[194:197], v[210:213], v[96:99]
	v_mfma_f32_16x16x32_bf16 v[84:87], v[186:189], v[218:221], v[84:87]
	v_mfma_f32_16x16x32_bf16 v[80:83], v[194:197], v[218:221], v[80:83]
	v_mfma_f32_16x16x32_bf16 v[68:71], v[186:189], v[226:229], v[68:71]
	v_mfma_f32_16x16x32_bf16 v[64:67], v[194:197], v[226:229], v[64:67]
	v_mfma_f32_16x16x32_bf16 v[116:119], v[190:193], v[206:209], v[116:119]
	v_mfma_f32_16x16x32_bf16 v[112:115], v[198:201], v[206:209], v[112:115]
	v_mfma_f32_16x16x32_bf16 v[100:103], v[190:193], v[214:217], v[100:103]
	v_mfma_f32_16x16x32_bf16 v[96:99], v[198:201], v[214:217], v[96:99]
	v_mfma_f32_16x16x32_bf16 v[84:87], v[190:193], v[222:225], v[84:87]
	v_mfma_f32_16x16x32_bf16 v[80:83], v[198:201], v[222:225], v[80:83]
	v_mfma_f32_16x16x32_bf16 v[68:71], v[190:193], v[230:233], v[68:71]
	v_mfma_f32_16x16x32_bf16 v[64:67], v[198:201], v[230:233], v[64:67]
	s_barrier
; #define PG8_STAGE(bufoff, gbase, voff) do { _Pragma("unroll") for (int _i = 0; _i < 2; ++_i) \
;         __builtin_amdgcn_global_load_lds((const unsigned*)((const char*)(gbase) + (voff)[_i]), (PG8_LAS unsigned*)(lds + (bufoff) + ldsw + _i * 8192), 16, 0, 0); } while (0)
; #define PG8_LDA(dst, b, h) do { _Pragma("unroll") for (int m = 0; m < 4; ++m) _Pragma("unroll") for (int k = 0; k < 2; ++k) dst[m][k] = *(const PG8_LAS bf16x8*)(lds + PG8_SA(b, h) + aoff + m * 2048 + k * 1024); } while (0)
; #define PG8_MMA(ai, bj, At, Bt) do { __builtin_amdgcn_s_setprio(1); _Pragma("unroll") for (int m = 0; m < 4; ++m) _Pragma("unroll") for (int n = 0; n < 2; ++n) _Pragma("unroll") for (int k = 0; k < 2; ++k) \
;         acc[ai][bj][m][n] = __builtin_amdgcn_mfma_f32_16x16x32_bf16(Bt[n][k], At[m][k], acc[ai][bj][m][n], 0, 0, 0); __builtin_amdgcn_s_setprio(0); } while (0)
; #define PG8_WAIT_V(n) asm volatile("s_waitcnt vmcnt(" #n ")" ::: "memory")
; #define PG8_WAIT_L(n) asm volatile("s_waitcnt lgkmcnt(" #n ")" ::: "memory")
; #define PG8_BAR __builtin_amdgcn_s_barrier()
; #define PG8_SCHED __builtin_amdgcn_sched_barrier(0)
; template <class Epi, class Sched, bool ALIGN_EPI = false, bool SP2 = false>
; __device__ __forceinline__ void gemm_phase(PG8_LAS unsigned char* lds, const Gemm g, const Sched& S, const Epi& E, const int tid_arg) {
;     ...
;         for (int t = 0; t < nt; t += 2) {
;     ...
;             PG8_LDA(At, 1, 1); PG8_STAGE(PG8_SB(1, 0), b3, voffB); PG8_STAGE(PG8_SB(1, 1), b3 + hstep, voffB); PG8_STAGE(PG8_SA(1, 0), a3, voffA);
;             PG8_WAIT_V(8); PG8_WAIT_L(0); PG8_BAR; PG8_MMA(1, 0, At, B0); PG8_MMA(1, 1, At, B1); PG8_BAR; PG8_SCHED;
	s_setprio 0
	s_mov_b32 m0, s59
	v_lshl_add_u64 v[234:235], v[234:235], 0, s[16:17]
	s_add_u32 s0, s0, 0x40080
	ds_read_b128 v[202:205], v149 offset:49152
	ds_read_b128 v[206:209], v149 offset:50176
	ds_read_b128 v[210:213], v149 offset:51200
	ds_read_b128 v[214:217], v149 offset:52224
	ds_read_b128 v[218:221], v149 offset:53248
	ds_read_b128 v[222:225], v149 offset:54272
	ds_read_b128 v[226:229], v149 offset:55296
	ds_read_b128 v[230:233], v149 offset:56320
	global_load_lds_dwordx4 v[234:235], off
	v_lshl_add_u64 v[234:235], v[236:237], 0, s[16:17]
	s_mov_b32 m0, s60
	s_addc_u32 s1, s1, 0
	global_load_lds_dwordx4 v[234:235], off
	v_lshl_add_u64 v[234:235], s[0:1], 0, v[130:131]
	s_mov_b32 m0, s63
	s_nop 0
	global_load_lds_dwordx4 v[234:235], off
	v_lshl_add_u64 v[234:235], s[0:1], 0, v[134:135]
	s_mov_b32 m0, s64
	s_nop 0
	global_load_lds_dwordx4 v[234:235], off
	v_lshl_add_u64 v[234:235], v[238:239], 0, s[16:17]
	s_mov_b32 m0, s61
	s_nop 0
	global_load_lds_dwordx4 v[234:235], off
	v_lshl_add_u64 v[234:235], v[240:241], 0, s[16:17]
	s_mov_b32 m0, s62
	s_nop 0
	global_load_lds_dwordx4 v[234:235], off
	s_waitcnt vmcnt(8)
	s_waitcnt lgkmcnt(0)
	s_setprio 1
	s_barrier
	v_mfma_f32_16x16x32_bf16 v[60:63], v[170:173], v[202:205], v[60:63]
	v_mfma_f32_16x16x32_bf16 v[56:59], v[178:181], v[202:205], v[56:59]
	v_mfma_f32_16x16x32_bf16 v[44:47], v[170:173], v[210:213], v[44:47]
	v_mfma_f32_16x16x32_bf16 v[40:43], v[178:181], v[210:213], v[40:43]
	v_mfma_f32_16x16x32_bf16 v[28:31], v[170:173], v[218:221], v[28:31]
	v_mfma_f32_16x16x32_bf16 v[24:27], v[178:181], v[218:221], v[24:27]
	v_mfma_f32_16x16x32_bf16 v[12:15], v[170:173], v[226:229], v[12:15]
	v_mfma_f32_16x16x32_bf16 v[8:11], v[178:181], v[226:229], v[8:11]
	v_mfma_f32_16x16x32_bf16 v[60:63], v[174:177], v[206:209], v[60:63]
	v_mfma_f32_16x16x32_bf16 v[56:59], v[182:185], v[206:209], v[56:59]
	v_mfma_f32_16x16x32_bf16 v[44:47], v[174:177], v[214:217], v[44:47]
	v_mfma_f32_16x16x32_bf16 v[40:43], v[182:185], v[214:217], v[40:43]
	v_mfma_f32_16x16x32_bf16 v[28:31], v[174:177], v[222:225], v[28:31]
	v_mfma_f32_16x16x32_bf16 v[24:27], v[182:185], v[222:225], v[24:27]
	v_mfma_f32_16x16x32_bf16 v[12:15], v[174:177], v[230:233], v[12:15]
	v_mfma_f32_16x16x32_bf16 v[8:11], v[182:185], v[230:233], v[8:11]
	s_setprio 0
	s_setprio 1
	v_mfma_f32_16x16x32_bf16 v[52:55], v[186:189], v[202:205], v[52:55]
	v_mfma_f32_16x16x32_bf16 v[48:51], v[194:197], v[202:205], v[48:51]
	v_mfma_f32_16x16x32_bf16 v[36:39], v[186:189], v[210:213], v[36:39]
	v_mfma_f32_16x16x32_bf16 v[32:35], v[194:197], v[210:213], v[32:35]
	v_mfma_f32_16x16x32_bf16 v[20:23], v[186:189], v[218:221], v[20:23]
	v_mfma_f32_16x16x32_bf16 v[16:19], v[194:197], v[218:221], v[16:19]
	v_mfma_f32_16x16x32_bf16 v[4:7], v[186:189], v[226:229], v[4:7]
	v_mfma_f32_16x16x32_bf16 v[0:3], v[194:197], v[226:229], v[0:3]
	v_mfma_f32_16x16x32_bf16 v[52:55], v[190:193], v[206:209], v[52:55]
	v_mfma_f32_16x16x32_bf16 v[48:51], v[198:201], v[206:209], v[48:51]
	v_mfma_f32_16x16x32_bf16 v[36:39], v[190:193], v[214:217], v[36:39]
	v_mfma_f32_16x16x32_bf16 v[32:35], v[198:201], v[214:217], v[32:35]
	v_mfma_f32_16x16x32_bf16 v[20:23], v[190:193], v[222:225], v[20:23]
	v_mfma_f32_16x16x32_bf16 v[16:19], v[198:201], v[222:225], v[16:19]
	v_mfma_f32_16x16x32_bf16 v[4:7], v[190:193], v[230:233], v[4:7]
	v_mfma_f32_16x16x32_bf16 v[0:3], v[198:201], v[230:233], v[0:3]
	s_barrier
	s_setprio 0
	s_add_i32 s81, s81, 2
	s_add_u32 s79, s79, 0x100
	s_addc_u32 s80, s80, 0
	s_add_u32 s44, s44, 0x100
	s_addc_u32 s45, s45, 0
	s_cmp_gt_u32 s81, 13
	s_cbranch_scc0 .LBB0_1827
	s_branch .Lkpeel_exit_11

; #define PG8_STAGE(bufoff, gbase, voff) do { _Pragma("unroll") for (int _i = 0; _i < 2; ++_i) \
;         __builtin_amdgcn_global_load_lds((const unsigned*)((const char*)(gbase) + (voff)[_i]), (PG8_LAS unsigned*)(lds + (bufoff) + ldsw + _i * 8192), 16, 0, 0); } while (0)
; #define PG8_LDA(dst, b, h) do { _Pragma("unroll") for (int m = 0; m < 4; ++m) _Pragma("unroll") for (int k = 0; k < 2; ++k) dst[m][k] = *(const PG8_LAS bf16x8*)(lds + PG8_SA(b, h) + aoff + m * 2048 + k * 1024); } while (0)
; #define PG8_LDB(dst, b, h) do { _Pragma("unroll") for (int n = 0; n < 2; ++n) _Pragma("unroll") for (int k = 0; k < 2; ++k) dst[n][k] = *(const PG8_LAS bf16x8*)(lds + PG8_SB(b, h) + boff + n * 2048 + k * 1024); } while (0)
; #define PG8_MMA(ai, bj, At, Bt) do { __builtin_amdgcn_s_setprio(1); _Pragma("unroll") for (int m = 0; m < 4; ++m) _Pragma("unroll") for (int n = 0; n < 2; ++n) _Pragma("unroll") for (int k = 0; k < 2; ++k) \
;         acc[ai][bj][m][n] = __builtin_amdgcn_mfma_f32_16x16x32_bf16(Bt[n][k], At[m][k], acc[ai][bj][m][n], 0, 0, 0); __builtin_amdgcn_s_setprio(0); } while (0)
; #define PG8_WAIT_V(n) asm volatile("s_waitcnt vmcnt(" #n ")" ::: "memory")
; #define PG8_WAIT_L(n) asm volatile("s_waitcnt lgkmcnt(" #n ")" ::: "memory")
; #define PG8_BAR __builtin_amdgcn_s_barrier()
; #define PG8_SCHED __builtin_amdgcn_sched_barrier(0)
; template <class Epi, class Sched, bool ALIGN_EPI = false, bool SP2 = false>
; __device__ __forceinline__ void gemm_phase(PG8_LAS unsigned char* lds, const Gemm g, const Sched& S, const Epi& E, const int tid_arg) {
;     ...
;     Unit cur, nxt; int ui = 0;
;     if (!S.next(0, cur)) return;
;     f32x4 acc[2][2][4][2];
; #pragma unroll
;     for (int a = 0; a < 2; ++a)
; #pragma unroll
;         for (int b = 0; b < 2; ++b)
; #pragma unroll
;             for (int m = 0; m < 4; ++m)
; #pragma unroll
;                 for (int n = 0; n < 2; ++n) acc[a][b][m][n] = (f32x4){0.f, 0.f, 0.f, 0.f};
;     bf16x8 At[4][2], B0[2][2], B1[2][2];
;     const char* cA = (const char*)g.A + (size_t)cur.pm * tstep; const char* cB = (const char*)g.Bt + (size_t)cur.pn * tstep;
;     S.a_ready(cur);
;     ...
;             PG8_LDB(B0, 0, 0); PG8_LDB(B1, 0, 1); PG8_SCHED; PG8_LDA(At, 0, 0); PG8_STAGE(PG8_SA(1, 1), a1 + hstep, voffA);
;             PG8_WAIT_V(8); PG8_WAIT_L(0); PG8_BAR; PG8_MMA(0, 0, At, B0); PG8_MMA(0, 1, At, B1); PG8_BAR; PG8_SCHED;
.LBB0_1909:
	v_mov_b32_e32 v127, 0
	s_and_b64 vcc, exec, s[0:1]
	s_cbranch_vccnz .LBB0_1912
	s_add_u32 s63, s34, 0x100
	s_addc_u32 s64, s35, 0
	s_add_u32 s6, s36, 0x80
	v_mov_b32_e32 v0, 0
	s_addc_u32 s7, s37, 0
	s_mov_b32 s34, 0
	ds_read_b128 v[144:147], v157
	ds_read_b128 v[148:151], v158
	ds_read_b128 v[174:177], v159
	ds_read_b128 v[178:181], v160
	ds_read_b128 v[182:185], v161
	ds_read_b128 v[186:189], v162
	ds_read_b128 v[190:193], v163
	ds_read_b128 v[194:197], v164
	s_add_i32 s36, s34, 2
	s_add_u32 s37, s6, 0x80
	s_addc_u32 s35, s7, 0
	s_cmp_eq_u32 s57, s34
	s_cselect_b32 s34, s28, s37
	s_cselect_b32 s35, s29, s35
	s_cselect_b32 s67, s31, s64
	s_cselect_b32 s66, s30, s63
	s_mov_b32 m0, s58
	v_lshl_add_u64 v[152:153], s[6:7], 0, v[138:139]
	ds_read_b128 v[198:201], v156
	ds_read_b128 v[202:205], v156 offset:1024
	ds_read_b128 v[206:209], v156 offset:2048
	ds_read_b128 v[210:213], v156 offset:3072
	ds_read_b128 v[214:217], v156 offset:4096
	ds_read_b128 v[218:221], v156 offset:5120
	ds_read_b128 v[222:225], v156 offset:6144
	ds_read_b128 v[226:229], v156 offset:7168
	global_load_lds_dwordx4 v[152:153], off
	v_lshl_add_u64 v[152:153], s[6:7], 0, v[136:137]
	s_mov_b32 m0, s59
	s_nop 0
	global_load_lds_dwordx4 v[152:153], off
	s_waitcnt vmcnt(8)
	s_waitcnt lgkmcnt(0)
	s_setprio 1
	s_barrier
	v_mfma_f32_16x16x32_bf16 v[124:127], v[144:147], v[198:201], 0
	v_mfma_f32_16x16x32_bf16 v[120:123], v[174:177], v[198:201], 0
	v_mfma_f32_16x16x32_bf16 v[108:111], v[144:147], v[206:209], 0
	v_mfma_f32_16x16x32_bf16 v[104:107], v[174:177], v[206:209], 0
	v_mfma_f32_16x16x32_bf16 v[92:95], v[144:147], v[214:217], 0
	v_mfma_f32_16x16x32_bf16 v[88:91], v[174:177], v[214:217], 0
	v_mfma_f32_16x16x32_bf16 v[76:79], v[144:147], v[222:225], 0
	v_mfma_f32_16x16x32_bf16 v[72:75], v[174:177], v[222:225], 0
	v_mfma_f32_16x16x32_bf16 v[124:127], v[148:151], v[202:205], v[124:127]
	v_mfma_f32_16x16x32_bf16 v[120:123], v[178:181], v[202:205], v[120:123]
	v_mfma_f32_16x16x32_bf16 v[108:111], v[148:151], v[210:213], v[108:111]
	v_mfma_f32_16x16x32_bf16 v[104:107], v[178:181], v[210:213], v[104:107]
	v_mfma_f32_16x16x32_bf16 v[92:95], v[148:151], v[218:221], v[92:95]
	v_mfma_f32_16x16x32_bf16 v[88:91], v[178:181], v[218:221], v[88:91]
	v_mfma_f32_16x16x32_bf16 v[76:79], v[148:151], v[226:229], v[76:79]
	v_mfma_f32_16x16x32_bf16 v[72:75], v[178:181], v[226:229], v[72:75]
	s_setprio 0
	s_setprio 1
	v_mfma_f32_16x16x32_bf16 v[116:119], v[182:185], v[198:201], 0
	v_mfma_f32_16x16x32_bf16 v[112:115], v[190:193], v[198:201], 0
	v_mfma_f32_16x16x32_bf16 v[100:103], v[182:185], v[206:209], 0
	v_mfma_f32_16x16x32_bf16 v[96:99], v[190:193], v[206:209], 0
	v_mfma_f32_16x16x32_bf16 v[84:87], v[182:185], v[214:217], 0
	v_mfma_f32_16x16x32_bf16 v[80:83], v[190:193], v[214:217], 0
	v_mfma_f32_16x16x32_bf16 v[68:71], v[182:185], v[222:225], 0
	v_mfma_f32_16x16x32_bf16 v[64:67], v[190:193], v[222:225], 0
	v_mfma_f32_16x16x32_bf16 v[116:119], v[186:189], v[202:205], v[116:119]
	v_mfma_f32_16x16x32_bf16 v[112:115], v[194:197], v[202:205], v[112:115]
	v_mfma_f32_16x16x32_bf16 v[100:103], v[186:189], v[210:213], v[100:103]
	v_mfma_f32_16x16x32_bf16 v[96:99], v[194:197], v[210:213], v[96:99]
	v_mfma_f32_16x16x32_bf16 v[84:87], v[186:189], v[218:221], v[84:87]
	v_mfma_f32_16x16x32_bf16 v[80:83], v[194:197], v[218:221], v[80:83]
	v_mfma_f32_16x16x32_bf16 v[68:71], v[186:189], v[226:229], v[68:71]
	v_mfma_f32_16x16x32_bf16 v[64:67], v[194:197], v[226:229], v[64:67]
	s_barrier
	s_setprio 0
	s_mov_b32 m0, s42
	v_lshl_add_u64 v[152:153], s[66:67], 0, v[130:131]
	v_lshl_add_u64 v[230:231], s[66:67], 0, v[134:135]
	s_add_u32 s66, s66, s12
	ds_read_b128 v[198:201], v156 offset:16384
	ds_read_b128 v[202:205], v156 offset:17408
	ds_read_b128 v[206:209], v156 offset:18432
	ds_read_b128 v[210:213], v156 offset:19456
	ds_read_b128 v[214:217], v156 offset:20480
	ds_read_b128 v[218:221], v156 offset:21504
	ds_read_b128 v[222:225], v156 offset:22528
	ds_read_b128 v[226:229], v156 offset:23552
	global_load_lds_dwordx4 v[152:153], off
	s_mov_b32 m0, s43
	s_addc_u32 s67, s67, s13
	global_load_lds_dwordx4 v[230:231], off
	v_lshl_add_u64 v[232:233], s[66:67], 0, v[130:131]
	s_mov_b32 m0, s44
	v_lshl_add_u64 v[234:235], s[66:67], 0, v[134:135]
	global_load_lds_dwordx4 v[232:233], off
	s_mov_b32 m0, s45
	v_lshl_add_u64 v[236:237], s[34:35], 0, v[128:129]
	global_load_lds_dwordx4 v[234:235], off
	s_mov_b32 m0, s41
	v_lshl_add_u64 v[238:239], s[34:35], 0, v[132:133]
	global_load_lds_dwordx4 v[236:237], off
	s_mov_b32 m0, s46
	s_nop 0
	global_load_lds_dwordx4 v[238:239], off
	s_waitcnt vmcnt(8)
	s_waitcnt lgkmcnt(0)
	s_setprio 1
	s_barrier
; #define PG8_STAGE(bufoff, gbase, voff) do { _Pragma("unroll") for (int _i = 0; _i < 2; ++_i) \
;         __builtin_amdgcn_global_load_lds((const unsigned*)((const char*)(gbase) + (voff)[_i]), (PG8_LAS unsigned*)(lds + (bufoff) + ldsw + _i * 8192), 16, 0, 0); } while (0)
; #define PG8_LDA(dst, b, h) do { _Pragma("unroll") for (int m = 0; m < 4; ++m) _Pragma("unroll") for (int k = 0; k < 2; ++k) dst[m][k] = *(const PG8_LAS bf16x8*)(lds + PG8_SA(b, h) + aoff + m * 2048 + k * 1024); } while (0)
; #define PG8_LDB(dst, b, h) do { _Pragma("unroll") for (int n = 0; n < 2; ++n) _Pragma("unroll") for (int k = 0; k < 2; ++k) dst[n][k] = *(const PG8_LAS bf16x8*)(lds + PG8_SB(b, h) + boff + n * 2048 + k * 1024); } while (0)
; #define PG8_MMA(ai, bj, At, Bt) do { __builtin_amdgcn_s_setprio(1); _Pragma("unroll") for (int m = 0; m < 4; ++m) _Pragma("unroll") for (int n = 0; n < 2; ++n) _Pragma("unroll") for (int k = 0; k < 2; ++k) \
;         acc[ai][bj][m][n] = __builtin_amdgcn_mfma_f32_16x16x32_bf16(Bt[n][k], At[m][k], acc[ai][bj][m][n], 0, 0, 0); __builtin_amdgcn_s_setprio(0); } while (0)
; #define PG8_WAIT_V(n) asm volatile("s_waitcnt vmcnt(" #n ")" ::: "memory")
; #define PG8_WAIT_L(n) asm volatile("s_waitcnt lgkmcnt(" #n ")" ::: "memory")
; #define PG8_BAR __builtin_amdgcn_s_barrier()
; #define PG8_SCHED __builtin_amdgcn_sched_barrier(0)
; template <class Epi, class Sched, bool ALIGN_EPI = false, bool SP2 = false>
; __device__ __forceinline__ void gemm_phase(PG8_LAS unsigned char* lds, const Gemm g, const Sched& S, const Epi& E, const int tid_arg) {
;     ...
;             PG8_WAIT_V(8); PG8_WAIT_L(0); PG8_BAR; PG8_MMA(0, 0, At, B0); PG8_MMA(0, 1, At, B1); PG8_BAR; PG8_SCHED;
;             PG8_LDA(At, 0, 1); PG8_STAGE(PG8_SB(0, 0), b2, voffB); PG8_STAGE(PG8_SB(0, 1), b2 + hstep, voffB); PG8_STAGE(PG8_SA(0, 0), a2, voffA);
;             PG8_WAIT_V(8); PG8_WAIT_L(0); PG8_BAR; PG8_MMA(1, 0, At, B0); PG8_MMA(1, 1, At, B1); PG8_BAR; PG8_SCHED;
;             PG8_LDB(B0, 1, 0); PG8_LDB(B1, 1, 1); PG8_SCHED; PG8_LDA(At, 1, 0); PG8_STAGE(PG8_SA(0, 1), a2 + hstep, voffA);
;             PG8_WAIT_V(8); PG8_WAIT_L(0); PG8_BAR; PG8_MMA(0, 0, At, B0); PG8_MMA(0, 1, At, B1); PG8_BAR; PG8_SCHED;
	v_mfma_f32_16x16x32_bf16 v[60:63], v[144:147], v[198:201], 0
	v_mfma_f32_16x16x32_bf16 v[56:59], v[174:177], v[198:201], 0
	v_mfma_f32_16x16x32_bf16 v[44:47], v[144:147], v[206:209], 0
	v_mfma_f32_16x16x32_bf16 v[40:43], v[174:177], v[206:209], 0
	v_mfma_f32_16x16x32_bf16 v[28:31], v[144:147], v[214:217], 0
	v_mfma_f32_16x16x32_bf16 v[24:27], v[174:177], v[214:217], 0
	v_mfma_f32_16x16x32_bf16 v[12:15], v[144:147], v[222:225], 0
	v_mfma_f32_16x16x32_bf16 v[8:11], v[174:177], v[222:225], 0
	v_mfma_f32_16x16x32_bf16 v[60:63], v[148:151], v[202:205], v[60:63]
	v_mfma_f32_16x16x32_bf16 v[56:59], v[178:181], v[202:205], v[56:59]
	v_mfma_f32_16x16x32_bf16 v[44:47], v[148:151], v[210:213], v[44:47]
	v_mfma_f32_16x16x32_bf16 v[40:43], v[178:181], v[210:213], v[40:43]
	v_mfma_f32_16x16x32_bf16 v[28:31], v[148:151], v[218:221], v[28:31]
	v_mfma_f32_16x16x32_bf16 v[24:27], v[178:181], v[218:221], v[24:27]
	v_mfma_f32_16x16x32_bf16 v[12:15], v[148:151], v[226:229], v[12:15]
	v_mfma_f32_16x16x32_bf16 v[8:11], v[178:181], v[226:229], v[8:11]
	s_setprio 0
	s_setprio 1
	v_mfma_f32_16x16x32_bf16 v[52:55], v[182:185], v[198:201], 0
	v_mfma_f32_16x16x32_bf16 v[48:51], v[190:193], v[198:201], 0
	v_mfma_f32_16x16x32_bf16 v[36:39], v[182:185], v[206:209], 0
	v_mfma_f32_16x16x32_bf16 v[32:35], v[190:193], v[206:209], 0
	v_mfma_f32_16x16x32_bf16 v[20:23], v[182:185], v[214:217], 0
	v_mfma_f32_16x16x32_bf16 v[16:19], v[190:193], v[214:217], 0
	v_mfma_f32_16x16x32_bf16 v[4:7], v[182:185], v[222:225], 0
	v_mfma_f32_16x16x32_bf16 v[0:3], v[190:193], v[222:225], 0
	v_mfma_f32_16x16x32_bf16 v[52:55], v[186:189], v[202:205], v[52:55]
	v_mfma_f32_16x16x32_bf16 v[48:51], v[194:197], v[202:205], v[48:51]
	v_mfma_f32_16x16x32_bf16 v[36:39], v[186:189], v[210:213], v[36:39]
	v_mfma_f32_16x16x32_bf16 v[32:35], v[194:197], v[210:213], v[32:35]
	v_mfma_f32_16x16x32_bf16 v[20:23], v[186:189], v[218:221], v[20:23]
	v_mfma_f32_16x16x32_bf16 v[16:19], v[194:197], v[218:221], v[16:19]
	v_mfma_f32_16x16x32_bf16 v[4:7], v[186:189], v[226:229], v[4:7]
	v_mfma_f32_16x16x32_bf16 v[0:3], v[194:197], v[226:229], v[0:3]
	s_barrier
	s_setprio 0
	ds_read_b128 v[144:147], v165
	ds_read_b128 v[148:151], v166
	ds_read_b128 v[174:177], v167
	ds_read_b128 v[178:181], v168
	ds_read_b128 v[182:185], v169
	ds_read_b128 v[186:189], v170
	ds_read_b128 v[190:193], v171
	ds_read_b128 v[194:197], v172
	s_add_u32 s34, s34, s12
	s_addc_u32 s35, s35, s13
	s_mov_b32 m0, s47
	v_lshl_add_u64 v[240:241], s[34:35], 0, v[128:129]
	ds_read_b128 v[198:201], v156 offset:32768
	ds_read_b128 v[202:205], v156 offset:33792
	ds_read_b128 v[206:209], v156 offset:34816
	ds_read_b128 v[210:213], v156 offset:35840
	ds_read_b128 v[214:217], v156 offset:36864
	ds_read_b128 v[218:221], v156 offset:37888
	ds_read_b128 v[222:225], v156 offset:38912
	ds_read_b128 v[226:229], v156 offset:39936
	global_load_lds_dwordx4 v[240:241], off
	v_lshl_add_u64 v[240:241], s[34:35], 0, v[132:133]
	s_mov_b32 m0, s48
	s_nop 0
	global_load_lds_dwordx4 v[240:241], off
	s_waitcnt vmcnt(8)
	s_waitcnt lgkmcnt(0)
	s_setprio 1
	s_barrier
	v_mfma_f32_16x16x32_bf16 v[124:127], v[144:147], v[198:201], v[124:127]
	v_mfma_f32_16x16x32_bf16 v[120:123], v[174:177], v[198:201], v[120:123]
	v_mfma_f32_16x16x32_bf16 v[108:111], v[144:147], v[206:209], v[108:111]
	v_mfma_f32_16x16x32_bf16 v[104:107], v[174:177], v[206:209], v[104:107]
	v_mfma_f32_16x16x32_bf16 v[92:95], v[144:147], v[214:217], v[92:95]
	v_mfma_f32_16x16x32_bf16 v[88:91], v[174:177], v[214:217], v[88:91]
	v_mfma_f32_16x16x32_bf16 v[76:79], v[144:147], v[222:225], v[76:79]
	v_mfma_f32_16x16x32_bf16 v[72:75], v[174:177], v[222:225], v[72:75]
	v_mfma_f32_16x16x32_bf16 v[124:127], v[148:151], v[202:205], v[124:127]
	v_mfma_f32_16x16x32_bf16 v[120:123], v[178:181], v[202:205], v[120:123]
	v_mfma_f32_16x16x32_bf16 v[108:111], v[148:151], v[210:213], v[108:111]
	v_mfma_f32_16x16x32_bf16 v[104:107], v[178:181], v[210:213], v[104:107]
	v_mfma_f32_16x16x32_bf16 v[92:95], v[148:151], v[218:221], v[92:95]
	v_mfma_f32_16x16x32_bf16 v[88:91], v[178:181], v[218:221], v[88:91]
	v_mfma_f32_16x16x32_bf16 v[76:79], v[148:151], v[226:229], v[76:79]
	v_mfma_f32_16x16x32_bf16 v[72:75], v[178:181], v[226:229], v[72:75]
	s_setprio 0
	s_setprio 1
	v_mfma_f32_16x16x32_bf16 v[116:119], v[182:185], v[198:201], v[116:119]
	v_mfma_f32_16x16x32_bf16 v[112:115], v[190:193], v[198:201], v[112:115]
	v_mfma_f32_16x16x32_bf16 v[100:103], v[182:185], v[206:209], v[100:103]
	v_mfma_f32_16x16x32_bf16 v[96:99], v[190:193], v[206:209], v[96:99]
	v_mfma_f32_16x16x32_bf16 v[84:87], v[182:185], v[214:217], v[84:87]
	v_mfma_f32_16x16x32_bf16 v[80:83], v[190:193], v[214:217], v[80:83]
	v_mfma_f32_16x16x32_bf16 v[68:71], v[182:185], v[222:225], v[68:71]
	v_mfma_f32_16x16x32_bf16 v[64:67], v[190:193], v[222:225], v[64:67]
	v_mfma_f32_16x16x32_bf16 v[116:119], v[186:189], v[202:205], v[116:119]
	v_mfma_f32_16x16x32_bf16 v[112:115], v[194:197], v[202:205], v[112:115]
	v_mfma_f32_16x16x32_bf16 v[100:103], v[186:189], v[210:213], v[100:103]
	v_mfma_f32_16x16x32_bf16 v[96:99], v[194:197], v[210:213], v[96:99]
	v_mfma_f32_16x16x32_bf16 v[84:87], v[186:189], v[218:221], v[84:87]
	v_mfma_f32_16x16x32_bf16 v[80:83], v[194:197], v[218:221], v[80:83]
	v_mfma_f32_16x16x32_bf16 v[68:71], v[186:189], v[226:229], v[68:71]
	v_mfma_f32_16x16x32_bf16 v[64:67], v[194:197], v[226:229], v[64:67]
	s_barrier
; #define PG8_STAGE(bufoff, gbase, voff) do { _Pragma("unroll") for (int _i = 0; _i < 2; ++_i) \
;         __builtin_amdgcn_global_load_lds((const unsigned*)((const char*)(gbase) + (voff)[_i]), (PG8_LAS unsigned*)(lds + (bufoff) + ldsw + _i * 8192), 16, 0, 0); } while (0)
; #define PG8_LDA(dst, b, h) do { _Pragma("unroll") for (int m = 0; m < 4; ++m) _Pragma("unroll") for (int k = 0; k < 2; ++k) dst[m][k] = *(const PG8_LAS bf16x8*)(lds + PG8_SA(b, h) + aoff + m * 2048 + k * 1024); } while (0)
; #define PG8_MMA(ai, bj, At, Bt) do { __builtin_amdgcn_s_setprio(1); _Pragma("unroll") for (int m = 0; m < 4; ++m) _Pragma("unroll") for (int n = 0; n < 2; ++n) _Pragma("unroll") for (int k = 0; k < 2; ++k) \
;         acc[ai][bj][m][n] = __builtin_amdgcn_mfma_f32_16x16x32_bf16(Bt[n][k], At[m][k], acc[ai][bj][m][n], 0, 0, 0); __builtin_amdgcn_s_setprio(0); } while (0)
; #define PG8_WAIT_V(n) asm volatile("s_waitcnt vmcnt(" #n ")" ::: "memory")
; #define PG8_WAIT_L(n) asm volatile("s_waitcnt lgkmcnt(" #n ")" ::: "memory")
; #define PG8_BAR __builtin_amdgcn_s_barrier()
; #define PG8_SCHED __builtin_amdgcn_sched_barrier(0)
; template <class Epi, class Sched, bool ALIGN_EPI = false, bool SP2 = false>
; __device__ __forceinline__ void gemm_phase(PG8_LAS unsigned char* lds, const Gemm g, const Sched& S, const Epi& E, const int tid_arg) {
;     ...
;         for (int t = 0; t < nt; t += 2) {
;     ...
;             PG8_LDA(At, 1, 1); PG8_STAGE(PG8_SB(1, 0), b3, voffB); PG8_STAGE(PG8_SB(1, 1), b3 + hstep, voffB); PG8_STAGE(PG8_SA(1, 0), a3, voffA);
;             PG8_WAIT_V(8); PG8_WAIT_L(0); PG8_BAR; PG8_MMA(1, 0, At, B0); PG8_MMA(1, 1, At, B1); PG8_BAR; PG8_SCHED;
	s_setprio 0
	s_mov_b32 m0, s49
	v_lshl_add_u64 v[152:153], v[152:153], 0, s[20:21]
	ds_read_b128 v[198:201], v156 offset:49152
	ds_read_b128 v[202:205], v156 offset:50176
	ds_read_b128 v[206:209], v156 offset:51200
	ds_read_b128 v[210:213], v156 offset:52224
	ds_read_b128 v[214:217], v156 offset:53248
	ds_read_b128 v[218:221], v156 offset:54272
	ds_read_b128 v[222:225], v156 offset:55296
	ds_read_b128 v[226:229], v156 offset:56320
	global_load_lds_dwordx4 v[152:153], off
	v_lshl_add_u64 v[152:153], v[230:231], 0, s[20:21]
	s_mov_b32 m0, s50
	s_nop 0
	global_load_lds_dwordx4 v[152:153], off
	v_lshl_add_u64 v[152:153], v[232:233], 0, s[20:21]
	s_mov_b32 m0, s53
	s_nop 0
	global_load_lds_dwordx4 v[152:153], off
	v_lshl_add_u64 v[152:153], v[234:235], 0, s[20:21]
	s_mov_b32 m0, s54
	s_nop 0
	global_load_lds_dwordx4 v[152:153], off
	v_lshl_add_u64 v[152:153], v[236:237], 0, s[20:21]
	s_mov_b32 m0, s51
	s_nop 0
	global_load_lds_dwordx4 v[152:153], off
	v_lshl_add_u64 v[152:153], v[238:239], 0, s[20:21]
	s_mov_b32 m0, s52
	s_nop 0
	global_load_lds_dwordx4 v[152:153], off
	s_waitcnt vmcnt(8)
	s_waitcnt lgkmcnt(0)
	s_setprio 1
	s_barrier
	v_mfma_f32_16x16x32_bf16 v[60:63], v[144:147], v[198:201], v[60:63]
	v_mfma_f32_16x16x32_bf16 v[56:59], v[174:177], v[198:201], v[56:59]
	v_mfma_f32_16x16x32_bf16 v[44:47], v[144:147], v[206:209], v[44:47]
	v_mfma_f32_16x16x32_bf16 v[40:43], v[174:177], v[206:209], v[40:43]
	v_mfma_f32_16x16x32_bf16 v[28:31], v[144:147], v[214:217], v[28:31]
	v_mfma_f32_16x16x32_bf16 v[24:27], v[174:177], v[214:217], v[24:27]
	v_mfma_f32_16x16x32_bf16 v[12:15], v[144:147], v[222:225], v[12:15]
	v_mfma_f32_16x16x32_bf16 v[8:11], v[174:177], v[222:225], v[8:11]
	v_mfma_f32_16x16x32_bf16 v[60:63], v[148:151], v[202:205], v[60:63]
	v_mfma_f32_16x16x32_bf16 v[56:59], v[178:181], v[202:205], v[56:59]
	v_mfma_f32_16x16x32_bf16 v[44:47], v[148:151], v[210:213], v[44:47]
	v_mfma_f32_16x16x32_bf16 v[40:43], v[178:181], v[210:213], v[40:43]
	v_mfma_f32_16x16x32_bf16 v[28:31], v[148:151], v[218:221], v[28:31]
	v_mfma_f32_16x16x32_bf16 v[24:27], v[178:181], v[218:221], v[24:27]
	v_mfma_f32_16x16x32_bf16 v[12:15], v[148:151], v[226:229], v[12:15]
	v_mfma_f32_16x16x32_bf16 v[8:11], v[178:181], v[226:229], v[8:11]
	s_setprio 0
	s_setprio 1
	v_mfma_f32_16x16x32_bf16 v[52:55], v[182:185], v[198:201], v[52:55]
	v_mfma_f32_16x16x32_bf16 v[48:51], v[190:193], v[198:201], v[48:51]
	v_mfma_f32_16x16x32_bf16 v[36:39], v[182:185], v[206:209], v[36:39]
	v_mfma_f32_16x16x32_bf16 v[32:35], v[190:193], v[206:209], v[32:35]
	v_mfma_f32_16x16x32_bf16 v[20:23], v[182:185], v[214:217], v[20:23]
	v_mfma_f32_16x16x32_bf16 v[16:19], v[190:193], v[214:217], v[16:19]
	v_mfma_f32_16x16x32_bf16 v[4:7], v[182:185], v[222:225], v[4:7]
	v_mfma_f32_16x16x32_bf16 v[0:3], v[190:193], v[222:225], v[0:3]
	v_mfma_f32_16x16x32_bf16 v[52:55], v[186:189], v[202:205], v[52:55]
	v_mfma_f32_16x16x32_bf16 v[48:51], v[194:197], v[202:205], v[48:51]
	v_mfma_f32_16x16x32_bf16 v[36:39], v[186:189], v[210:213], v[36:39]
	v_mfma_f32_16x16x32_bf16 v[32:35], v[194:197], v[210:213], v[32:35]
	v_mfma_f32_16x16x32_bf16 v[20:23], v[186:189], v[218:221], v[20:23]
	v_mfma_f32_16x16x32_bf16 v[16:19], v[194:197], v[218:221], v[16:19]
	v_mfma_f32_16x16x32_bf16 v[4:7], v[186:189], v[226:229], v[4:7]
	v_mfma_f32_16x16x32_bf16 v[0:3], v[194:197], v[226:229], v[0:3]
	s_barrier
	s_setprio 0
	s_add_u32 s63, s63, 0x100
	s_addc_u32 s64, s64, 0
	s_add_u32 s6, s6, 0x100
	s_addc_u32 s7, s7, 0
	s_cmp_ge_i32 s36, s55
	s_mov_b32 s34, s36
	s_cbranch_scc0 .LBB0_1911
	s_branch .Lkpeel_exit_12

; #define PG8_BAR __builtin_amdgcn_s_barrier()
; template <class Epi, class Sched, bool ALIGN_EPI = false, bool SP2 = false>
; __device__ __forceinline__ void gemm_phase(PG8_LAS unsigned char* lds, const Gemm g, const Sched& S, const Epi& E, const int tid_arg) {
;     ...
;         if constexpr (ALIGN_EPI) { if (wr == 0) PG8_BAR; }
.Lkpeel_exit_12:
.LBB0_1912:
	s_and_b64 vcc, exec, s[24:25]
	s_cbranch_vccz .LBB0_1914
	s_barrier
